# c19 + post-MMA barrier issued right after the last MFMA (trailing s_setprio 0 / scalar address ops moved behind it)
# speedup vs baseline: 1.0083x; 1.0083x over previous
.LBB0_42:
	s_add_u32 s82, s80, 0xfffc0080
	s_addc_u32 s83, s81, -1
	s_add_i32 s94, 0, 0x10000
	v_add_u32_e32 v0, s94, v189
	ds_read_b128 v[122:125], v0
	ds_read_b128 v[126:129], v0 offset:1024
	ds_read_b128 v[130:133], v0 offset:2048
	ds_read_b128 v[134:137], v0 offset:3072
	s_cmp_eq_u32 s93, 12
	s_cselect_b32 s85, s11, s83
	s_cselect_b32 s84, s89, s82
	s_cselect_b32 s83, s9, s92
	s_cselect_b32 s82, s90, s91
	v_lshl_add_u64 v[186:187], s[80:81], 0, v[184:185]
	s_add_i32 m0, s59, 0xc000
	ds_read_b128 v[146:149], v193
	ds_read_b128 v[150:153], v193 offset:1024
	ds_read_b128 v[154:157], v193 offset:2048
	ds_read_b128 v[158:161], v193 offset:3072
	ds_read_b128 v[162:165], v193 offset:4096
	ds_read_b128 v[166:169], v193 offset:5120
	ds_read_b128 v[170:173], v193 offset:6144
	ds_read_b128 v[174:177], v193 offset:7168
	global_load_lds_dwordx4 v[186:187], off
	v_lshl_add_u64 v[186:187], s[80:81], 0, v[182:183]
	s_add_i32 m0, s59, 0xe000
	s_nop 0
	global_load_lds_dwordx4 v[186:187], off
	s_waitcnt lgkmcnt(8)
	s_setprio 1
	s_barrier
	s_waitcnt lgkmcnt(0)
	v_mfma_f32_16x16x32_bf16 v[142:145], v[122:125], v[146:149], v[142:145]
	v_mfma_f32_16x16x32_bf16 v[138:141], v[130:133], v[146:149], v[138:141]
	v_mfma_f32_16x16x32_bf16 v[110:113], v[122:125], v[154:157], v[110:113]
	v_mfma_f32_16x16x32_bf16 v[106:109], v[130:133], v[154:157], v[106:109]
	v_mfma_f32_16x16x32_bf16 v[94:97], v[122:125], v[162:165], v[94:97]
	v_mfma_f32_16x16x32_bf16 v[90:93], v[130:133], v[162:165], v[90:93]
	v_mfma_f32_16x16x32_bf16 v[78:81], v[122:125], v[170:173], v[78:81]
	v_mfma_f32_16x16x32_bf16 v[74:77], v[130:133], v[170:173], v[74:77]
	v_mfma_f32_16x16x32_bf16 v[142:145], v[126:129], v[150:153], v[142:145]
	v_mfma_f32_16x16x32_bf16 v[138:141], v[134:137], v[150:153], v[138:141]
	v_mfma_f32_16x16x32_bf16 v[110:113], v[126:129], v[158:161], v[110:113]
	v_mfma_f32_16x16x32_bf16 v[106:109], v[134:137], v[158:161], v[106:109]
	v_mfma_f32_16x16x32_bf16 v[94:97], v[126:129], v[166:169], v[94:97]
	v_mfma_f32_16x16x32_bf16 v[90:93], v[134:137], v[166:169], v[90:93]
	v_mfma_f32_16x16x32_bf16 v[78:81], v[126:129], v[174:177], v[78:81]
	v_mfma_f32_16x16x32_bf16 v[74:77], v[134:137], v[174:177], v[74:77]
	s_barrier
	s_setprio 0
	s_add_i32 s96, 0, 0x14000
	s_add_i32 s94, s94, s46
	v_add_u32_e32 v0, s96, v189
	v_lshl_add_u64 v[186:187], s[82:83], 0, v[180:181]
	s_mov_b32 m0, s94
	ds_read_b128 v[194:197], v0
	ds_read_b128 v[198:201], v0 offset:1024
	ds_read_b128 v[202:205], v0 offset:2048
	ds_read_b128 v[206:209], v0 offset:3072
	global_load_lds_dwordx4 v[186:187], off
	v_lshl_add_u64 v[210:211], s[82:83], 0, v[178:179]
	s_add_i32 m0, s94, 0x2000
	s_nop 0
	global_load_lds_dwordx4 v[210:211], off
	s_setprio 1
	s_barrier
	s_waitcnt lgkmcnt(0)
	v_mfma_f32_16x16x32_bf16 v[118:121], v[194:197], v[146:149], v[118:121]
	v_mfma_f32_16x16x32_bf16 v[114:117], v[202:205], v[146:149], v[114:117]
	v_mfma_f32_16x16x32_bf16 v[102:105], v[194:197], v[154:157], v[102:105]
	v_mfma_f32_16x16x32_bf16 v[98:101], v[202:205], v[154:157], v[98:101]
	v_mfma_f32_16x16x32_bf16 v[86:89], v[194:197], v[162:165], v[86:89]
	v_mfma_f32_16x16x32_bf16 v[82:85], v[202:205], v[162:165], v[82:85]
	v_mfma_f32_16x16x32_bf16 v[70:73], v[194:197], v[170:173], v[70:73]
	v_mfma_f32_16x16x32_bf16 v[66:69], v[202:205], v[170:173], v[66:69]
	v_mfma_f32_16x16x32_bf16 v[118:121], v[198:201], v[150:153], v[118:121]
	v_mfma_f32_16x16x32_bf16 v[114:117], v[206:209], v[150:153], v[114:117]
	v_mfma_f32_16x16x32_bf16 v[102:105], v[198:201], v[158:161], v[102:105]
	v_mfma_f32_16x16x32_bf16 v[98:101], v[206:209], v[158:161], v[98:101]
	v_mfma_f32_16x16x32_bf16 v[86:89], v[198:201], v[166:169], v[86:89]
	v_mfma_f32_16x16x32_bf16 v[82:85], v[206:209], v[166:169], v[82:85]
	v_mfma_f32_16x16x32_bf16 v[70:73], v[198:201], v[174:177], v[70:73]
	v_mfma_f32_16x16x32_bf16 v[66:69], v[206:209], v[174:177], v[66:69]
	s_barrier
	s_setprio 0
	s_mov_b32 m0, s59
	v_lshl_add_u64 v[212:213], s[84:85], 0, v[180:181]
	ds_read_b128 v[146:149], v193 offset:16384
	ds_read_b128 v[150:153], v193 offset:17408
	ds_read_b128 v[154:157], v193 offset:18432
	ds_read_b128 v[158:161], v193 offset:19456
	ds_read_b128 v[162:165], v193 offset:20480
	ds_read_b128 v[166:169], v193 offset:21504
	ds_read_b128 v[170:173], v193 offset:22528
	ds_read_b128 v[174:177], v193 offset:23552
	global_load_lds_dwordx4 v[212:213], off
	v_lshl_add_u64 v[214:215], s[84:85], 0, v[178:179]
	s_mov_b32 m0, s60
	s_nop 0
	global_load_lds_dwordx4 v[214:215], off
	s_setprio 1
	s_barrier
	s_waitcnt lgkmcnt(0)
	v_mfma_f32_16x16x32_bf16 v[62:65], v[122:125], v[146:149], v[62:65]
	v_mfma_f32_16x16x32_bf16 v[58:61], v[130:133], v[146:149], v[58:61]
	v_mfma_f32_16x16x32_bf16 v[46:49], v[122:125], v[154:157], v[46:49]
	v_mfma_f32_16x16x32_bf16 v[42:45], v[130:133], v[154:157], v[42:45]
	v_mfma_f32_16x16x32_bf16 v[30:33], v[122:125], v[162:165], v[30:33]
	v_mfma_f32_16x16x32_bf16 v[26:29], v[130:133], v[162:165], v[26:29]
	v_mfma_f32_16x16x32_bf16 v[14:17], v[122:125], v[170:173], v[14:17]
	v_mfma_f32_16x16x32_bf16 v[10:13], v[130:133], v[170:173], v[10:13]
	v_mfma_f32_16x16x32_bf16 v[62:65], v[126:129], v[150:153], v[62:65]
	v_mfma_f32_16x16x32_bf16 v[58:61], v[134:137], v[150:153], v[58:61]
	v_mfma_f32_16x16x32_bf16 v[46:49], v[126:129], v[158:161], v[46:49]
	v_mfma_f32_16x16x32_bf16 v[42:45], v[134:137], v[158:161], v[42:45]
	v_mfma_f32_16x16x32_bf16 v[30:33], v[126:129], v[166:169], v[30:33]
	v_mfma_f32_16x16x32_bf16 v[26:29], v[134:137], v[166:169], v[26:29]
	v_mfma_f32_16x16x32_bf16 v[14:17], v[126:129], v[174:177], v[14:17]
	v_mfma_f32_16x16x32_bf16 v[10:13], v[134:137], v[174:177], v[10:13]
	s_barrier
	s_setprio 0
	s_add_u32 s94, s82, 0x40000
	s_addc_u32 s95, s83, 0
	s_add_i32 s96, s96, s46
	v_lshl_add_u64 v[122:123], s[94:95], 0, v[180:181]
	s_mov_b32 m0, s96
	s_nop 0
	global_load_lds_dwordx4 v[122:123], off
	v_lshl_add_u64 v[122:123], s[94:95], 0, v[178:179]
	s_add_i32 m0, s96, 0x2000
	s_nop 0
	global_load_lds_dwordx4 v[122:123], off
	s_waitcnt vmcnt(6)
	s_setprio 1
	s_barrier
	v_mfma_f32_16x16x32_bf16 v[54:57], v[194:197], v[146:149], v[54:57]
	v_mfma_f32_16x16x32_bf16 v[50:53], v[202:205], v[146:149], v[50:53]
	v_mfma_f32_16x16x32_bf16 v[38:41], v[194:197], v[154:157], v[38:41]
	v_mfma_f32_16x16x32_bf16 v[34:37], v[202:205], v[154:157], v[34:37]
	v_mfma_f32_16x16x32_bf16 v[22:25], v[194:197], v[162:165], v[22:25]
	v_mfma_f32_16x16x32_bf16 v[18:21], v[202:205], v[162:165], v[18:21]
	v_mfma_f32_16x16x32_bf16 v[6:9], v[194:197], v[170:173], v[6:9]
	v_mfma_f32_16x16x32_bf16 v[2:5], v[202:205], v[170:173], v[2:5]
	v_mfma_f32_16x16x32_bf16 v[54:57], v[198:201], v[150:153], v[54:57]
	v_mfma_f32_16x16x32_bf16 v[50:53], v[206:209], v[150:153], v[50:53]
	v_mfma_f32_16x16x32_bf16 v[38:41], v[198:201], v[158:161], v[38:41]
	v_mfma_f32_16x16x32_bf16 v[34:37], v[206:209], v[158:161], v[34:37]
	v_mfma_f32_16x16x32_bf16 v[22:25], v[198:201], v[166:169], v[22:25]
	v_mfma_f32_16x16x32_bf16 v[18:21], v[206:209], v[166:169], v[18:21]
	v_mfma_f32_16x16x32_bf16 v[6:9], v[198:201], v[174:177], v[6:9]
	v_mfma_f32_16x16x32_bf16 v[2:5], v[206:209], v[174:177], v[2:5]
	s_barrier
	s_setprio 0
	s_add_i32 s94, 0, 0x18000
	v_add_u32_e32 v0, s94, v189
	ds_read_b128 v[122:125], v0
	ds_read_b128 v[126:129], v0 offset:1024
	ds_read_b128 v[130:133], v0 offset:2048
	ds_read_b128 v[134:137], v0 offset:3072
	s_add_u32 s84, s84, 0x40000
	s_addc_u32 s85, s85, 0
	s_mov_b32 m0, s61
	v_lshl_add_u64 v[194:195], s[84:85], 0, v[180:181]
	ds_read_b128 v[146:149], v193 offset:32768
	ds_read_b128 v[150:153], v193 offset:33792
	ds_read_b128 v[154:157], v193 offset:34816
	ds_read_b128 v[158:161], v193 offset:35840
	ds_read_b128 v[162:165], v193 offset:36864
	ds_read_b128 v[166:169], v193 offset:37888
	ds_read_b128 v[170:173], v193 offset:38912
	ds_read_b128 v[174:177], v193 offset:39936
	global_load_lds_dwordx4 v[194:195], off
	v_lshl_add_u64 v[194:195], s[84:85], 0, v[178:179]
	s_mov_b32 m0, s76
	s_nop 0
	global_load_lds_dwordx4 v[194:195], off
	s_waitcnt lgkmcnt(8)
	s_setprio 1
	s_barrier
	s_waitcnt lgkmcnt(0)
	v_mfma_f32_16x16x32_bf16 v[142:145], v[122:125], v[146:149], v[142:145]
	v_mfma_f32_16x16x32_bf16 v[138:141], v[130:133], v[146:149], v[138:141]
	v_mfma_f32_16x16x32_bf16 v[110:113], v[122:125], v[154:157], v[110:113]
	v_mfma_f32_16x16x32_bf16 v[106:109], v[130:133], v[154:157], v[106:109]
	v_mfma_f32_16x16x32_bf16 v[94:97], v[122:125], v[162:165], v[94:97]
	v_mfma_f32_16x16x32_bf16 v[90:93], v[130:133], v[162:165], v[90:93]
	v_mfma_f32_16x16x32_bf16 v[78:81], v[122:125], v[170:173], v[78:81]
	v_mfma_f32_16x16x32_bf16 v[74:77], v[130:133], v[170:173], v[74:77]
	v_mfma_f32_16x16x32_bf16 v[142:145], v[126:129], v[150:153], v[142:145]
	v_mfma_f32_16x16x32_bf16 v[138:141], v[134:137], v[150:153], v[138:141]
	v_mfma_f32_16x16x32_bf16 v[110:113], v[126:129], v[158:161], v[110:113]
	v_mfma_f32_16x16x32_bf16 v[106:109], v[134:137], v[158:161], v[106:109]
	v_mfma_f32_16x16x32_bf16 v[94:97], v[126:129], v[166:169], v[94:97]
	v_mfma_f32_16x16x32_bf16 v[90:93], v[134:137], v[166:169], v[90:93]
	v_mfma_f32_16x16x32_bf16 v[78:81], v[126:129], v[174:177], v[78:81]
	v_mfma_f32_16x16x32_bf16 v[74:77], v[134:137], v[174:177], v[74:77]
	s_barrier
	s_setprio 0
	s_add_i32 s84, 0, 0x1c000
	s_add_i32 s85, s94, s46
	v_add_u32_e32 v0, s84, v189
	v_lshl_add_u64 v[186:187], v[186:187], 0, s[48:49]
	s_mov_b32 m0, s85
	ds_read_b128 v[194:197], v0
	ds_read_b128 v[198:201], v0 offset:1024
	ds_read_b128 v[202:205], v0 offset:2048
	ds_read_b128 v[206:209], v0 offset:3072
	global_load_lds_dwordx4 v[186:187], off
	v_lshl_add_u64 v[186:187], v[210:211], 0, s[48:49]
	s_add_i32 m0, s85, 0x2000
	s_nop 0
	global_load_lds_dwordx4 v[186:187], off
	s_setprio 1
	s_barrier
	s_waitcnt lgkmcnt(0)
	v_mfma_f32_16x16x32_bf16 v[118:121], v[194:197], v[146:149], v[118:121]
	v_mfma_f32_16x16x32_bf16 v[114:117], v[202:205], v[146:149], v[114:117]
	v_mfma_f32_16x16x32_bf16 v[102:105], v[194:197], v[154:157], v[102:105]
	v_mfma_f32_16x16x32_bf16 v[98:101], v[202:205], v[154:157], v[98:101]
	v_mfma_f32_16x16x32_bf16 v[86:89], v[194:197], v[162:165], v[86:89]
	v_mfma_f32_16x16x32_bf16 v[82:85], v[202:205], v[162:165], v[82:85]
	v_mfma_f32_16x16x32_bf16 v[70:73], v[194:197], v[170:173], v[70:73]
	v_mfma_f32_16x16x32_bf16 v[66:69], v[202:205], v[170:173], v[66:69]
	v_mfma_f32_16x16x32_bf16 v[118:121], v[198:201], v[150:153], v[118:121]
	v_mfma_f32_16x16x32_bf16 v[114:117], v[206:209], v[150:153], v[114:117]
	v_mfma_f32_16x16x32_bf16 v[102:105], v[198:201], v[158:161], v[102:105]
	v_mfma_f32_16x16x32_bf16 v[98:101], v[206:209], v[158:161], v[98:101]
	v_mfma_f32_16x16x32_bf16 v[86:89], v[198:201], v[166:169], v[86:89]
	v_mfma_f32_16x16x32_bf16 v[82:85], v[206:209], v[166:169], v[82:85]
	v_mfma_f32_16x16x32_bf16 v[70:73], v[198:201], v[174:177], v[70:73]
	v_mfma_f32_16x16x32_bf16 v[66:69], v[206:209], v[174:177], v[66:69]
	s_barrier
	s_setprio 0
	s_mov_b32 m0, s79
	v_lshl_add_u64 v[186:187], v[212:213], 0, s[48:49]
	ds_read_b128 v[146:149], v193 offset:49152
	ds_read_b128 v[150:153], v193 offset:50176
	ds_read_b128 v[154:157], v193 offset:51200
	ds_read_b128 v[158:161], v193 offset:52224
	ds_read_b128 v[162:165], v193 offset:53248
	ds_read_b128 v[166:169], v193 offset:54272
	ds_read_b128 v[170:173], v193 offset:55296
	ds_read_b128 v[174:177], v193 offset:56320
	global_load_lds_dwordx4 v[186:187], off
	v_lshl_add_u64 v[186:187], v[214:215], 0, s[48:49]
	s_mov_b32 m0, s86
	s_nop 0
	global_load_lds_dwordx4 v[186:187], off
	s_setprio 1
	s_barrier
; template <int CTRL> DEVI float dpp(float x) { return __builtin_bit_cast(float, __builtin_amdgcn_mov_dpp(__builtin_bit_cast(int, x), CTRL, 0xf, 0xf, true)); }
;     DEVI void operator()(AccRef acc, const pg8::Unit& u, int wr, int wc, int fr, int fq) const {
;         unsigned o = (unsigned)((u.pm * 256 + wr * 64 + fr) * DM + u.pn * 256 + wc * 32 + 4 * fq) * 4u;
;         const bool lo = fr < 8;
;         unsigned os = (unsigned)((u.pm * 256 + wr * 64 + (fr & 7)) * DM + u.pn * 256 + wc * 32 + 4 * fq) * 4u + (lo ? 0u : 64u);
; #pragma unroll
;         for (int ai = 0; ai < 2; ++ai) {
;             asm volatile("" : "+v"(o), "+v"(os));
;             f32x4 b[4][2][2];
; #pragma unroll
;             for (int m = 0; m < 4; ++m)
; #pragma unroll
;                 for (int bj = 0; bj < 2; ++bj)
; #pragma unroll
;                     for (int n = 0; n < 2; ++n) b[m][bj][n] = *(const f32x4*)((const char*)base + o + (unsigned)(m * 16 * DM * 4 + bj * 512 + n * 64));
; #pragma unroll
;             for (int m = 0; m < 4; ++m)
; #pragma unroll
;                 for (int bj = 0; bj < 2; ++bj) { const f32x4 d0 = b[m][bj][0] + alpha * acc[ai][bj][m][0], d1 = b[m][bj][1] + alpha * acc[ai][bj][m][1];
;                     f32x4 t0, t1;
; #pragma unroll
;                     for (int i = 0; i < 4; ++i) { t0[i] = dpp<0x128>(d0[i]); t1[i] = dpp<0x128>(d1[i]); }
;                     const f32x4 sa = lo ? d0 : t1, sb = lo ? t0 : d1;
;                     const unsigned oo = os + (unsigned)(m * 16 * DM * 4 + bj * 512);
;                     *(f32x4*)((char*)out + oo) = sa; *(f32x4*)((char*)out + oo + 8u * DM * 4u) = sb; }
;             o += 128u * DM * 4u; os += 128u * DM * 4u; }
	s_waitcnt lgkmcnt(0)
	v_mfma_f32_16x16x32_bf16 v[62:65], v[122:125], v[146:149], v[62:65]
	v_mfma_f32_16x16x32_bf16 v[58:61], v[130:133], v[146:149], v[58:61]
	v_mfma_f32_16x16x32_bf16 v[46:49], v[122:125], v[154:157], v[46:49]
	v_mfma_f32_16x16x32_bf16 v[42:45], v[130:133], v[154:157], v[42:45]
	v_mfma_f32_16x16x32_bf16 v[30:33], v[122:125], v[162:165], v[30:33]
	v_mfma_f32_16x16x32_bf16 v[26:29], v[130:133], v[162:165], v[26:29]
	v_mfma_f32_16x16x32_bf16 v[14:17], v[122:125], v[170:173], v[14:17]
	v_mfma_f32_16x16x32_bf16 v[10:13], v[130:133], v[170:173], v[10:13]
	v_mfma_f32_16x16x32_bf16 v[62:65], v[126:129], v[150:153], v[62:65]
	v_mfma_f32_16x16x32_bf16 v[58:61], v[134:137], v[150:153], v[58:61]
	v_mfma_f32_16x16x32_bf16 v[46:49], v[126:129], v[158:161], v[46:49]
	v_mfma_f32_16x16x32_bf16 v[42:45], v[134:137], v[158:161], v[42:45]
	v_mfma_f32_16x16x32_bf16 v[30:33], v[126:129], v[166:169], v[30:33]
	v_mfma_f32_16x16x32_bf16 v[26:29], v[134:137], v[166:169], v[26:29]
	v_mfma_f32_16x16x32_bf16 v[14:17], v[126:129], v[174:177], v[14:17]
	v_mfma_f32_16x16x32_bf16 v[10:13], v[134:137], v[174:177], v[10:13]
	s_barrier
	s_setprio 0
	s_add_u32 s82, s82, 0x40080
	s_addc_u32 s83, s83, 0
	s_add_i32 s84, s84, s46
	v_lshl_add_u64 v[122:123], s[82:83], 0, v[180:181]
	s_mov_b32 m0, s84
	s_nop 0
	global_load_lds_dwordx4 v[122:123], off
	v_lshl_add_u64 v[122:123], s[82:83], 0, v[178:179]
	s_add_i32 m0, s84, 0x2000
	s_nop 0
	global_load_lds_dwordx4 v[122:123], off
	s_waitcnt vmcnt(6)
	s_setprio 1
	s_barrier
	v_mfma_f32_16x16x32_bf16 v[54:57], v[194:197], v[146:149], v[54:57]
	v_mfma_f32_16x16x32_bf16 v[50:53], v[202:205], v[146:149], v[50:53]
	v_mfma_f32_16x16x32_bf16 v[38:41], v[194:197], v[154:157], v[38:41]
	v_mfma_f32_16x16x32_bf16 v[34:37], v[202:205], v[154:157], v[34:37]
	v_mfma_f32_16x16x32_bf16 v[22:25], v[194:197], v[162:165], v[22:25]
	v_mfma_f32_16x16x32_bf16 v[18:21], v[202:205], v[162:165], v[18:21]
	v_mfma_f32_16x16x32_bf16 v[6:9], v[194:197], v[170:173], v[6:9]
	v_mfma_f32_16x16x32_bf16 v[2:5], v[202:205], v[170:173], v[2:5]
	v_mfma_f32_16x16x32_bf16 v[54:57], v[198:201], v[150:153], v[54:57]
	v_mfma_f32_16x16x32_bf16 v[50:53], v[206:209], v[150:153], v[50:53]
	v_mfma_f32_16x16x32_bf16 v[38:41], v[198:201], v[158:161], v[38:41]
	v_mfma_f32_16x16x32_bf16 v[34:37], v[206:209], v[158:161], v[34:37]
	v_mfma_f32_16x16x32_bf16 v[22:25], v[198:201], v[166:169], v[22:25]
	v_mfma_f32_16x16x32_bf16 v[18:21], v[206:209], v[166:169], v[18:21]
	v_mfma_f32_16x16x32_bf16 v[6:9], v[198:201], v[174:177], v[6:9]
	v_mfma_f32_16x16x32_bf16 v[2:5], v[206:209], v[174:177], v[2:5]
	s_barrier
	s_setprio 0
	s_add_i32 s93, s93, 2
	s_add_u32 s91, s91, 0x100
	s_addc_u32 s92, s92, 0
	s_add_u32 s80, s80, 0x100
	s_addc_u32 s81, s81, 0
	s_cmp_gt_u32 s93, 13
	s_cbranch_scc0 .LBB0_42
	s_lshl_b32 s9, s78, 8
	s_add_i32 s9, s9, s77
	v_or_b32_e32 v0, s9, v188
	s_lshl_b32 s11, s88, 8
	v_or_b32_e32 v122, s9, v190
	v_lshl_add_u32 v0, v0, 10, s11
	v_lshl_add_u32 v122, v122, 10, s11
	v_or_b32_e32 v0, v0, v192
	v_or_b32_e32 v122, v122, v192
	v_lshlrev_b32_e32 v0, 2, v0
	v_lshl_or_b32 v186, v122, 2, v191
	s_mov_b32 s88, s8
	s_mov_b32 s78, s10
	s_mov_b64 s[80:81], s[24:25]
	s_mov_b64 s[82:83], s[22:23]
	v_add_u32_e32 v187, 0x8000, v186
	s_add_u32 s98, s28, 0x0
	s_addc_u32 s99, s29, 0
	global_load_dwordx4 v[194:197], v0, s[98:99]
	global_load_dwordx4 v[198:201], v0, s[98:99] offset:64
	global_load_dwordx4 v[202:205], v0, s[98:99] offset:512
	global_load_dwordx4 v[206:209], v0, s[98:99] offset:576
	s_add_u32 s98, s28, 0x10000
	s_addc_u32 s99, s29, 0
	global_load_dwordx4 v[174:177], v0, s[98:99]
	global_load_dwordx4 v[170:173], v0, s[98:99] offset:64
	global_load_dwordx4 v[166:169], v0, s[98:99] offset:512
	global_load_dwordx4 v[162:165], v0, s[98:99] offset:576
	s_add_u32 s98, s28, 0x20000
	s_addc_u32 s99, s29, 0
	global_load_dwordx4 v[158:161], v0, s[98:99]
	global_load_dwordx4 v[154:157], v0, s[98:99] offset:64
	global_load_dwordx4 v[150:153], v0, s[98:99] offset:512
	global_load_dwordx4 v[146:149], v0, s[98:99] offset:576
	s_add_u32 s98, s28, 0x30000
	s_addc_u32 s99, s29, 0
	global_load_dwordx4 v[134:137], v0, s[98:99]
	global_load_dwordx4 v[130:133], v0, s[98:99] offset:64
	global_load_dwordx4 v[126:129], v0, s[98:99] offset:512
	global_load_dwordx4 v[122:125], v0, s[98:99] offset:576
	s_waitcnt vmcnt(12)
	v_pk_add_f32 v[142:143], v[142:143], v[194:195]
	v_pk_add_f32 v[144:145], v[144:145], v[196:197]
	v_pk_add_f32 v[138:139], v[138:139], v[198:199]
	v_pk_add_f32 v[140:141], v[140:141], v[200:201]
	v_pk_add_f32 v[118:119], v[118:119], v[202:203]
	v_pk_add_f32 v[120:121], v[120:121], v[204:205]
	v_pk_add_f32 v[114:115], v[114:115], v[206:207]
	v_pk_add_f32 v[116:117], v[116:117], v[208:209]
	s_mov_b64 vcc, s[4:5]
	v_cndmask_b32_dpp v194, v138, v142, vcc row_ror:8 row_mask:0xf bank_mask:0xf bound_ctrl:1
	v_cndmask_b32_dpp v195, v139, v143, vcc row_ror:8 row_mask:0xf bank_mask:0xf bound_ctrl:1
	v_cndmask_b32_dpp v196, v140, v144, vcc row_ror:8 row_mask:0xf bank_mask:0xf bound_ctrl:1
	v_cndmask_b32_dpp v197, v141, v145, vcc row_ror:8 row_mask:0xf bank_mask:0xf bound_ctrl:1
	v_cndmask_b32_dpp v202, v114, v118, vcc row_ror:8 row_mask:0xf bank_mask:0xf bound_ctrl:1
	v_cndmask_b32_dpp v203, v115, v119, vcc row_ror:8 row_mask:0xf bank_mask:0xf bound_ctrl:1
	v_cndmask_b32_dpp v204, v116, v120, vcc row_ror:8 row_mask:0xf bank_mask:0xf bound_ctrl:1
	v_cndmask_b32_dpp v205, v117, v121, vcc row_ror:8 row_mask:0xf bank_mask:0xf bound_ctrl:1
	s_not_b64 vcc, s[4:5]
	v_cndmask_b32_dpp v198, v142, v138, vcc row_ror:8 row_mask:0xf bank_mask:0xf bound_ctrl:1
	v_cndmask_b32_dpp v199, v143, v139, vcc row_ror:8 row_mask:0xf bank_mask:0xf bound_ctrl:1
	v_cndmask_b32_dpp v200, v144, v140, vcc row_ror:8 row_mask:0xf bank_mask:0xf bound_ctrl:1
	v_cndmask_b32_dpp v201, v145, v141, vcc row_ror:8 row_mask:0xf bank_mask:0xf bound_ctrl:1
	v_cndmask_b32_dpp v206, v118, v114, vcc row_ror:8 row_mask:0xf bank_mask:0xf bound_ctrl:1
	v_cndmask_b32_dpp v207, v119, v115, vcc row_ror:8 row_mask:0xf bank_mask:0xf bound_ctrl:1
	v_cndmask_b32_dpp v208, v120, v116, vcc row_ror:8 row_mask:0xf bank_mask:0xf bound_ctrl:1
	v_cndmask_b32_dpp v209, v121, v117, vcc row_ror:8 row_mask:0xf bank_mask:0xf bound_ctrl:1
	s_add_u32 s100, s28, 0x0
	s_addc_u32 s101, s29, 0
	global_store_dwordx4 v186, v[194:197], s[100:101]
	global_store_dwordx4 v187, v[198:201], s[100:101]
	global_store_dwordx4 v186, v[202:205], s[100:101] offset:512
	global_store_dwordx4 v187, v[206:209], s[100:101] offset:512
	s_add_u32 s98, s28, 0x80000
	s_addc_u32 s99, s29, 0
	global_load_dwordx4 v[142:145], v0, s[98:99]
	global_load_dwordx4 v[138:141], v0, s[98:99] offset:64
	global_load_dwordx4 v[118:121], v0, s[98:99] offset:512
	global_load_dwordx4 v[114:117], v0, s[98:99] offset:576
	s_waitcnt vmcnt(16)
; template <int CTRL> DEVI float dpp(float x) { return __builtin_bit_cast(float, __builtin_amdgcn_mov_dpp(__builtin_bit_cast(int, x), CTRL, 0xf, 0xf, true)); }
;     DEVI void operator()(AccRef acc, const pg8::Unit& u, int wr, int wc, int fr, int fq) const {
;     ...
;         for (int ai = 0; ai < 2; ++ai) {
;             asm volatile("" : "+v"(o), "+v"(os));
;             f32x4 b[4][2][2];
; #pragma unroll
;             for (int m = 0; m < 4; ++m)
; #pragma unroll
;                 for (int bj = 0; bj < 2; ++bj)
; #pragma unroll
;                     for (int n = 0; n < 2; ++n) b[m][bj][n] = *(const f32x4*)((const char*)base + o + (unsigned)(m * 16 * DM * 4 + bj * 512 + n * 64));
; #pragma unroll
;             for (int m = 0; m < 4; ++m)
; #pragma unroll
;                 for (int bj = 0; bj < 2; ++bj) { const f32x4 d0 = b[m][bj][0] + alpha * acc[ai][bj][m][0], d1 = b[m][bj][1] + alpha * acc[ai][bj][m][1];
;                     f32x4 t0, t1;
; #pragma unroll
;                     for (int i = 0; i < 4; ++i) { t0[i] = dpp<0x128>(d0[i]); t1[i] = dpp<0x128>(d1[i]); }
;                     const f32x4 sa = lo ? d0 : t1, sb = lo ? t0 : d1;
;                     const unsigned oo = os + (unsigned)(m * 16 * DM * 4 + bj * 512);
;                     *(f32x4*)((char*)out + oo) = sa; *(f32x4*)((char*)out + oo + 8u * DM * 4u) = sb; }
;             o += 128u * DM * 4u; os += 128u * DM * 4u; }
	v_pk_add_f32 v[110:111], v[110:111], v[174:175]
	v_pk_add_f32 v[112:113], v[112:113], v[176:177]
	v_pk_add_f32 v[106:107], v[106:107], v[170:171]
	v_pk_add_f32 v[108:109], v[108:109], v[172:173]
	v_pk_add_f32 v[102:103], v[102:103], v[166:167]
	v_pk_add_f32 v[104:105], v[104:105], v[168:169]
	v_pk_add_f32 v[98:99], v[98:99], v[162:163]
	v_pk_add_f32 v[100:101], v[100:101], v[164:165]
	s_mov_b64 vcc, s[4:5]
	v_cndmask_b32_dpp v174, v106, v110, vcc row_ror:8 row_mask:0xf bank_mask:0xf bound_ctrl:1
	v_cndmask_b32_dpp v175, v107, v111, vcc row_ror:8 row_mask:0xf bank_mask:0xf bound_ctrl:1
	v_cndmask_b32_dpp v176, v108, v112, vcc row_ror:8 row_mask:0xf bank_mask:0xf bound_ctrl:1
	v_cndmask_b32_dpp v177, v109, v113, vcc row_ror:8 row_mask:0xf bank_mask:0xf bound_ctrl:1
	v_cndmask_b32_dpp v166, v98, v102, vcc row_ror:8 row_mask:0xf bank_mask:0xf bound_ctrl:1
	v_cndmask_b32_dpp v167, v99, v103, vcc row_ror:8 row_mask:0xf bank_mask:0xf bound_ctrl:1
	v_cndmask_b32_dpp v168, v100, v104, vcc row_ror:8 row_mask:0xf bank_mask:0xf bound_ctrl:1
	v_cndmask_b32_dpp v169, v101, v105, vcc row_ror:8 row_mask:0xf bank_mask:0xf bound_ctrl:1
	s_not_b64 vcc, s[4:5]
	v_cndmask_b32_dpp v170, v110, v106, vcc row_ror:8 row_mask:0xf bank_mask:0xf bound_ctrl:1
	v_cndmask_b32_dpp v171, v111, v107, vcc row_ror:8 row_mask:0xf bank_mask:0xf bound_ctrl:1
	v_cndmask_b32_dpp v172, v112, v108, vcc row_ror:8 row_mask:0xf bank_mask:0xf bound_ctrl:1
	v_cndmask_b32_dpp v173, v113, v109, vcc row_ror:8 row_mask:0xf bank_mask:0xf bound_ctrl:1
	v_cndmask_b32_dpp v162, v102, v98, vcc row_ror:8 row_mask:0xf bank_mask:0xf bound_ctrl:1
	v_cndmask_b32_dpp v163, v103, v99, vcc row_ror:8 row_mask:0xf bank_mask:0xf bound_ctrl:1
	v_cndmask_b32_dpp v164, v104, v100, vcc row_ror:8 row_mask:0xf bank_mask:0xf bound_ctrl:1
	v_cndmask_b32_dpp v165, v105, v101, vcc row_ror:8 row_mask:0xf bank_mask:0xf bound_ctrl:1
	s_add_u32 s100, s28, 0x10000
	s_addc_u32 s101, s29, 0
	global_store_dwordx4 v186, v[174:177], s[100:101]
	global_store_dwordx4 v187, v[170:173], s[100:101]
	global_store_dwordx4 v186, v[166:169], s[100:101] offset:512
	global_store_dwordx4 v187, v[162:165], s[100:101] offset:512
	s_add_u32 s98, s28, 0x90000
	s_addc_u32 s99, s29, 0
	global_load_dwordx4 v[110:113], v0, s[98:99]
	global_load_dwordx4 v[106:109], v0, s[98:99] offset:64
	global_load_dwordx4 v[102:105], v0, s[98:99] offset:512
	global_load_dwordx4 v[98:101], v0, s[98:99] offset:576
	s_waitcnt vmcnt(20)
	v_pk_add_f32 v[94:95], v[94:95], v[158:159]
	v_pk_add_f32 v[96:97], v[96:97], v[160:161]
	v_pk_add_f32 v[90:91], v[90:91], v[154:155]
	v_pk_add_f32 v[92:93], v[92:93], v[156:157]
	v_pk_add_f32 v[86:87], v[86:87], v[150:151]
	v_pk_add_f32 v[88:89], v[88:89], v[152:153]
	v_pk_add_f32 v[82:83], v[82:83], v[146:147]
	v_pk_add_f32 v[84:85], v[84:85], v[148:149]
	s_mov_b64 vcc, s[4:5]
	v_cndmask_b32_dpp v158, v90, v94, vcc row_ror:8 row_mask:0xf bank_mask:0xf bound_ctrl:1
	v_cndmask_b32_dpp v159, v91, v95, vcc row_ror:8 row_mask:0xf bank_mask:0xf bound_ctrl:1
	v_cndmask_b32_dpp v160, v92, v96, vcc row_ror:8 row_mask:0xf bank_mask:0xf bound_ctrl:1
	v_cndmask_b32_dpp v161, v93, v97, vcc row_ror:8 row_mask:0xf bank_mask:0xf bound_ctrl:1
	v_cndmask_b32_dpp v150, v82, v86, vcc row_ror:8 row_mask:0xf bank_mask:0xf bound_ctrl:1
	v_cndmask_b32_dpp v151, v83, v87, vcc row_ror:8 row_mask:0xf bank_mask:0xf bound_ctrl:1
	v_cndmask_b32_dpp v152, v84, v88, vcc row_ror:8 row_mask:0xf bank_mask:0xf bound_ctrl:1
	v_cndmask_b32_dpp v153, v85, v89, vcc row_ror:8 row_mask:0xf bank_mask:0xf bound_ctrl:1
	s_not_b64 vcc, s[4:5]
	v_cndmask_b32_dpp v154, v94, v90, vcc row_ror:8 row_mask:0xf bank_mask:0xf bound_ctrl:1
	v_cndmask_b32_dpp v155, v95, v91, vcc row_ror:8 row_mask:0xf bank_mask:0xf bound_ctrl:1
	v_cndmask_b32_dpp v156, v96, v92, vcc row_ror:8 row_mask:0xf bank_mask:0xf bound_ctrl:1
	v_cndmask_b32_dpp v157, v97, v93, vcc row_ror:8 row_mask:0xf bank_mask:0xf bound_ctrl:1
	v_cndmask_b32_dpp v146, v86, v82, vcc row_ror:8 row_mask:0xf bank_mask:0xf bound_ctrl:1
	v_cndmask_b32_dpp v147, v87, v83, vcc row_ror:8 row_mask:0xf bank_mask:0xf bound_ctrl:1
	v_cndmask_b32_dpp v148, v88, v84, vcc row_ror:8 row_mask:0xf bank_mask:0xf bound_ctrl:1
	v_cndmask_b32_dpp v149, v89, v85, vcc row_ror:8 row_mask:0xf bank_mask:0xf bound_ctrl:1
	s_add_u32 s100, s28, 0x20000
	s_addc_u32 s101, s29, 0
	global_store_dwordx4 v186, v[158:161], s[100:101]
	global_store_dwordx4 v187, v[154:157], s[100:101]
	global_store_dwordx4 v186, v[150:153], s[100:101] offset:512
	global_store_dwordx4 v187, v[146:149], s[100:101] offset:512
	s_add_u32 s98, s28, 0xa0000
	s_addc_u32 s99, s29, 0
	global_load_dwordx4 v[94:97], v0, s[98:99]
	global_load_dwordx4 v[90:93], v0, s[98:99] offset:64
	global_load_dwordx4 v[86:89], v0, s[98:99] offset:512
	global_load_dwordx4 v[82:85], v0, s[98:99] offset:576
	s_waitcnt vmcnt(24)
; template <int CTRL> DEVI float dpp(float x) { return __builtin_bit_cast(float, __builtin_amdgcn_mov_dpp(__builtin_bit_cast(int, x), CTRL, 0xf, 0xf, true)); }
;     DEVI void operator()(AccRef acc, const pg8::Unit& u, int wr, int wc, int fr, int fq) const {
;     ...
;         for (int ai = 0; ai < 2; ++ai) {
;             asm volatile("" : "+v"(o), "+v"(os));
;             f32x4 b[4][2][2];
; #pragma unroll
;             for (int m = 0; m < 4; ++m)
; #pragma unroll
;                 for (int bj = 0; bj < 2; ++bj)
; #pragma unroll
;                     for (int n = 0; n < 2; ++n) b[m][bj][n] = *(const f32x4*)((const char*)base + o + (unsigned)(m * 16 * DM * 4 + bj * 512 + n * 64));
; #pragma unroll
;             for (int m = 0; m < 4; ++m)
; #pragma unroll
;                 for (int bj = 0; bj < 2; ++bj) { const f32x4 d0 = b[m][bj][0] + alpha * acc[ai][bj][m][0], d1 = b[m][bj][1] + alpha * acc[ai][bj][m][1];
;                     f32x4 t0, t1;
; #pragma unroll
;                     for (int i = 0; i < 4; ++i) { t0[i] = dpp<0x128>(d0[i]); t1[i] = dpp<0x128>(d1[i]); }
;                     const f32x4 sa = lo ? d0 : t1, sb = lo ? t0 : d1;
;                     const unsigned oo = os + (unsigned)(m * 16 * DM * 4 + bj * 512);
;                     *(f32x4*)((char*)out + oo) = sa; *(f32x4*)((char*)out + oo + 8u * DM * 4u) = sb; }
;             o += 128u * DM * 4u; os += 128u * DM * 4u; }
	v_pk_add_f32 v[78:79], v[78:79], v[134:135]
	v_pk_add_f32 v[80:81], v[80:81], v[136:137]
	v_pk_add_f32 v[74:75], v[74:75], v[130:131]
	v_pk_add_f32 v[76:77], v[76:77], v[132:133]
	v_pk_add_f32 v[70:71], v[70:71], v[126:127]
	v_pk_add_f32 v[72:73], v[72:73], v[128:129]
	v_pk_add_f32 v[66:67], v[66:67], v[122:123]
	v_pk_add_f32 v[68:69], v[68:69], v[124:125]
	s_mov_b64 vcc, s[4:5]
	v_cndmask_b32_dpp v134, v74, v78, vcc row_ror:8 row_mask:0xf bank_mask:0xf bound_ctrl:1
	v_cndmask_b32_dpp v135, v75, v79, vcc row_ror:8 row_mask:0xf bank_mask:0xf bound_ctrl:1
	v_cndmask_b32_dpp v136, v76, v80, vcc row_ror:8 row_mask:0xf bank_mask:0xf bound_ctrl:1
	v_cndmask_b32_dpp v137, v77, v81, vcc row_ror:8 row_mask:0xf bank_mask:0xf bound_ctrl:1
	v_cndmask_b32_dpp v126, v66, v70, vcc row_ror:8 row_mask:0xf bank_mask:0xf bound_ctrl:1
	v_cndmask_b32_dpp v127, v67, v71, vcc row_ror:8 row_mask:0xf bank_mask:0xf bound_ctrl:1
	v_cndmask_b32_dpp v128, v68, v72, vcc row_ror:8 row_mask:0xf bank_mask:0xf bound_ctrl:1
	v_cndmask_b32_dpp v129, v69, v73, vcc row_ror:8 row_mask:0xf bank_mask:0xf bound_ctrl:1
	s_not_b64 vcc, s[4:5]
	v_cndmask_b32_dpp v130, v78, v74, vcc row_ror:8 row_mask:0xf bank_mask:0xf bound_ctrl:1
	v_cndmask_b32_dpp v131, v79, v75, vcc row_ror:8 row_mask:0xf bank_mask:0xf bound_ctrl:1
	v_cndmask_b32_dpp v132, v80, v76, vcc row_ror:8 row_mask:0xf bank_mask:0xf bound_ctrl:1
	v_cndmask_b32_dpp v133, v81, v77, vcc row_ror:8 row_mask:0xf bank_mask:0xf bound_ctrl:1
	v_cndmask_b32_dpp v122, v70, v66, vcc row_ror:8 row_mask:0xf bank_mask:0xf bound_ctrl:1
	v_cndmask_b32_dpp v123, v71, v67, vcc row_ror:8 row_mask:0xf bank_mask:0xf bound_ctrl:1
	v_cndmask_b32_dpp v124, v72, v68, vcc row_ror:8 row_mask:0xf bank_mask:0xf bound_ctrl:1
	v_cndmask_b32_dpp v125, v73, v69, vcc row_ror:8 row_mask:0xf bank_mask:0xf bound_ctrl:1
	s_add_u32 s100, s28, 0x30000
	s_addc_u32 s101, s29, 0
	global_store_dwordx4 v186, v[134:137], s[100:101]
	global_store_dwordx4 v187, v[130:133], s[100:101]
	global_store_dwordx4 v186, v[126:129], s[100:101] offset:512
	global_store_dwordx4 v187, v[122:125], s[100:101] offset:512
	s_add_u32 s98, s28, 0xb0000
	s_addc_u32 s99, s29, 0
	global_load_dwordx4 v[78:81], v0, s[98:99]
	global_load_dwordx4 v[74:77], v0, s[98:99] offset:64
	global_load_dwordx4 v[70:73], v0, s[98:99] offset:512
	global_load_dwordx4 v[66:69], v0, s[98:99] offset:576
	s_waitcnt vmcnt(24)
	v_pk_add_f32 v[62:63], v[62:63], v[142:143]
	v_pk_add_f32 v[64:65], v[64:65], v[144:145]
	v_pk_add_f32 v[58:59], v[58:59], v[138:139]
	v_pk_add_f32 v[60:61], v[60:61], v[140:141]
	v_pk_add_f32 v[54:55], v[54:55], v[118:119]
	v_pk_add_f32 v[56:57], v[56:57], v[120:121]
	v_pk_add_f32 v[50:51], v[50:51], v[114:115]
	v_pk_add_f32 v[52:53], v[52:53], v[116:117]
	s_mov_b64 vcc, s[4:5]
	v_cndmask_b32_dpp v142, v58, v62, vcc row_ror:8 row_mask:0xf bank_mask:0xf bound_ctrl:1
	v_cndmask_b32_dpp v143, v59, v63, vcc row_ror:8 row_mask:0xf bank_mask:0xf bound_ctrl:1
	v_cndmask_b32_dpp v144, v60, v64, vcc row_ror:8 row_mask:0xf bank_mask:0xf bound_ctrl:1
	v_cndmask_b32_dpp v145, v61, v65, vcc row_ror:8 row_mask:0xf bank_mask:0xf bound_ctrl:1
	v_cndmask_b32_dpp v118, v50, v54, vcc row_ror:8 row_mask:0xf bank_mask:0xf bound_ctrl:1
	v_cndmask_b32_dpp v119, v51, v55, vcc row_ror:8 row_mask:0xf bank_mask:0xf bound_ctrl:1
	v_cndmask_b32_dpp v120, v52, v56, vcc row_ror:8 row_mask:0xf bank_mask:0xf bound_ctrl:1
	v_cndmask_b32_dpp v121, v53, v57, vcc row_ror:8 row_mask:0xf bank_mask:0xf bound_ctrl:1
	s_not_b64 vcc, s[4:5]
	v_cndmask_b32_dpp v138, v62, v58, vcc row_ror:8 row_mask:0xf bank_mask:0xf bound_ctrl:1
	v_cndmask_b32_dpp v139, v63, v59, vcc row_ror:8 row_mask:0xf bank_mask:0xf bound_ctrl:1
	v_cndmask_b32_dpp v140, v64, v60, vcc row_ror:8 row_mask:0xf bank_mask:0xf bound_ctrl:1
	v_cndmask_b32_dpp v141, v65, v61, vcc row_ror:8 row_mask:0xf bank_mask:0xf bound_ctrl:1
	v_cndmask_b32_dpp v114, v54, v50, vcc row_ror:8 row_mask:0xf bank_mask:0xf bound_ctrl:1
	v_cndmask_b32_dpp v115, v55, v51, vcc row_ror:8 row_mask:0xf bank_mask:0xf bound_ctrl:1
	v_cndmask_b32_dpp v116, v56, v52, vcc row_ror:8 row_mask:0xf bank_mask:0xf bound_ctrl:1
	v_cndmask_b32_dpp v117, v57, v53, vcc row_ror:8 row_mask:0xf bank_mask:0xf bound_ctrl:1
	s_add_u32 s100, s28, 0x80000
	s_addc_u32 s101, s29, 0
	global_store_dwordx4 v186, v[142:145], s[100:101]
	global_store_dwordx4 v187, v[138:141], s[100:101]
	global_store_dwordx4 v186, v[118:121], s[100:101] offset:512
	global_store_dwordx4 v187, v[114:117], s[100:101] offset:512
	s_waitcnt vmcnt(20)
; template <int CTRL> DEVI float dpp(float x) { return __builtin_bit_cast(float, __builtin_amdgcn_mov_dpp(__builtin_bit_cast(int, x), CTRL, 0xf, 0xf, true)); }
; #define PG8_WAIT_V(n) asm volatile("s_waitcnt vmcnt(" #n ")" ::: "memory")
; #define PG8_BAR __builtin_amdgcn_s_barrier()
; template <class Epi, class Sched>
; __device__ __forceinline__ void gemm_phase(PG8_LAS unsigned char* lds, const Gemm g, const Sched& S, const Epi& E, int wv) {
;     ...
;     PG8_WAIT_V(0);
;     if (wr == 0) PG8_BAR;
;     DEVI void operator()(AccRef acc, const pg8::Unit& u, int wr, int wc, int fr, int fq) const {
;     ...
; #pragma unroll
;             for (int m = 0; m < 4; ++m)
; #pragma unroll
;                 for (int bj = 0; bj < 2; ++bj) { const f32x4 d0 = b[m][bj][0] + alpha * acc[ai][bj][m][0], d1 = b[m][bj][1] + alpha * acc[ai][bj][m][1];
;                     f32x4 t0, t1;
; #pragma unroll
;                     for (int i = 0; i < 4; ++i) { t0[i] = dpp<0x128>(d0[i]); t1[i] = dpp<0x128>(d1[i]); }
;                     const f32x4 sa = lo ? d0 : t1, sb = lo ? t0 : d1;
;                     const unsigned oo = os + (unsigned)(m * 16 * DM * 4 + bj * 512);
;                     *(f32x4*)((char*)out + oo) = sa; *(f32x4*)((char*)out + oo + 8u * DM * 4u) = sb; }
;             o += 128u * DM * 4u; os += 128u * DM * 4u; }
	v_pk_add_f32 v[46:47], v[46:47], v[110:111]
	v_pk_add_f32 v[48:49], v[48:49], v[112:113]
	v_pk_add_f32 v[42:43], v[42:43], v[106:107]
	v_pk_add_f32 v[44:45], v[44:45], v[108:109]
	v_pk_add_f32 v[38:39], v[38:39], v[102:103]
	v_pk_add_f32 v[40:41], v[40:41], v[104:105]
	v_pk_add_f32 v[34:35], v[34:35], v[98:99]
	v_pk_add_f32 v[36:37], v[36:37], v[100:101]
	s_mov_b64 vcc, s[4:5]
	v_cndmask_b32_dpp v110, v42, v46, vcc row_ror:8 row_mask:0xf bank_mask:0xf bound_ctrl:1
	v_cndmask_b32_dpp v111, v43, v47, vcc row_ror:8 row_mask:0xf bank_mask:0xf bound_ctrl:1
	v_cndmask_b32_dpp v112, v44, v48, vcc row_ror:8 row_mask:0xf bank_mask:0xf bound_ctrl:1
	v_cndmask_b32_dpp v113, v45, v49, vcc row_ror:8 row_mask:0xf bank_mask:0xf bound_ctrl:1
	v_cndmask_b32_dpp v102, v34, v38, vcc row_ror:8 row_mask:0xf bank_mask:0xf bound_ctrl:1
	v_cndmask_b32_dpp v103, v35, v39, vcc row_ror:8 row_mask:0xf bank_mask:0xf bound_ctrl:1
	v_cndmask_b32_dpp v104, v36, v40, vcc row_ror:8 row_mask:0xf bank_mask:0xf bound_ctrl:1
	v_cndmask_b32_dpp v105, v37, v41, vcc row_ror:8 row_mask:0xf bank_mask:0xf bound_ctrl:1
	s_not_b64 vcc, s[4:5]
	v_cndmask_b32_dpp v106, v46, v42, vcc row_ror:8 row_mask:0xf bank_mask:0xf bound_ctrl:1
	v_cndmask_b32_dpp v107, v47, v43, vcc row_ror:8 row_mask:0xf bank_mask:0xf bound_ctrl:1
	v_cndmask_b32_dpp v108, v48, v44, vcc row_ror:8 row_mask:0xf bank_mask:0xf bound_ctrl:1
	v_cndmask_b32_dpp v109, v49, v45, vcc row_ror:8 row_mask:0xf bank_mask:0xf bound_ctrl:1
	v_cndmask_b32_dpp v98, v38, v34, vcc row_ror:8 row_mask:0xf bank_mask:0xf bound_ctrl:1
	v_cndmask_b32_dpp v99, v39, v35, vcc row_ror:8 row_mask:0xf bank_mask:0xf bound_ctrl:1
	v_cndmask_b32_dpp v100, v40, v36, vcc row_ror:8 row_mask:0xf bank_mask:0xf bound_ctrl:1
	v_cndmask_b32_dpp v101, v41, v37, vcc row_ror:8 row_mask:0xf bank_mask:0xf bound_ctrl:1
	s_add_u32 s100, s28, 0x90000
	s_addc_u32 s101, s29, 0
	global_store_dwordx4 v186, v[110:113], s[100:101]
	global_store_dwordx4 v187, v[106:109], s[100:101]
	global_store_dwordx4 v186, v[102:105], s[100:101] offset:512
	global_store_dwordx4 v187, v[98:101], s[100:101] offset:512
	s_waitcnt vmcnt(16)
	v_pk_add_f32 v[30:31], v[30:31], v[94:95]
	v_pk_add_f32 v[32:33], v[32:33], v[96:97]
	v_pk_add_f32 v[26:27], v[26:27], v[90:91]
	v_pk_add_f32 v[28:29], v[28:29], v[92:93]
	v_pk_add_f32 v[22:23], v[22:23], v[86:87]
	v_pk_add_f32 v[24:25], v[24:25], v[88:89]
	v_pk_add_f32 v[18:19], v[18:19], v[82:83]
	v_pk_add_f32 v[20:21], v[20:21], v[84:85]
	s_mov_b64 vcc, s[4:5]
	v_cndmask_b32_dpp v94, v26, v30, vcc row_ror:8 row_mask:0xf bank_mask:0xf bound_ctrl:1
	v_cndmask_b32_dpp v95, v27, v31, vcc row_ror:8 row_mask:0xf bank_mask:0xf bound_ctrl:1
	v_cndmask_b32_dpp v96, v28, v32, vcc row_ror:8 row_mask:0xf bank_mask:0xf bound_ctrl:1
	v_cndmask_b32_dpp v97, v29, v33, vcc row_ror:8 row_mask:0xf bank_mask:0xf bound_ctrl:1
	v_cndmask_b32_dpp v86, v18, v22, vcc row_ror:8 row_mask:0xf bank_mask:0xf bound_ctrl:1
	v_cndmask_b32_dpp v87, v19, v23, vcc row_ror:8 row_mask:0xf bank_mask:0xf bound_ctrl:1
	v_cndmask_b32_dpp v88, v20, v24, vcc row_ror:8 row_mask:0xf bank_mask:0xf bound_ctrl:1
	v_cndmask_b32_dpp v89, v21, v25, vcc row_ror:8 row_mask:0xf bank_mask:0xf bound_ctrl:1
	s_not_b64 vcc, s[4:5]
	v_cndmask_b32_dpp v90, v30, v26, vcc row_ror:8 row_mask:0xf bank_mask:0xf bound_ctrl:1
	v_cndmask_b32_dpp v91, v31, v27, vcc row_ror:8 row_mask:0xf bank_mask:0xf bound_ctrl:1
	v_cndmask_b32_dpp v92, v32, v28, vcc row_ror:8 row_mask:0xf bank_mask:0xf bound_ctrl:1
	v_cndmask_b32_dpp v93, v33, v29, vcc row_ror:8 row_mask:0xf bank_mask:0xf bound_ctrl:1
	v_cndmask_b32_dpp v82, v22, v18, vcc row_ror:8 row_mask:0xf bank_mask:0xf bound_ctrl:1
	v_cndmask_b32_dpp v83, v23, v19, vcc row_ror:8 row_mask:0xf bank_mask:0xf bound_ctrl:1
	v_cndmask_b32_dpp v84, v24, v20, vcc row_ror:8 row_mask:0xf bank_mask:0xf bound_ctrl:1
	v_cndmask_b32_dpp v85, v25, v21, vcc row_ror:8 row_mask:0xf bank_mask:0xf bound_ctrl:1
	s_add_u32 s100, s28, 0xa0000
	s_addc_u32 s101, s29, 0
	global_store_dwordx4 v186, v[94:97], s[100:101]
	global_store_dwordx4 v187, v[90:93], s[100:101]
	global_store_dwordx4 v186, v[86:89], s[100:101] offset:512
	global_store_dwordx4 v187, v[82:85], s[100:101] offset:512
	s_waitcnt vmcnt(12)
	v_pk_add_f32 v[14:15], v[14:15], v[78:79]
	v_pk_add_f32 v[16:17], v[16:17], v[80:81]
	v_pk_add_f32 v[10:11], v[10:11], v[74:75]
	v_pk_add_f32 v[12:13], v[12:13], v[76:77]
	v_pk_add_f32 v[6:7], v[6:7], v[70:71]
	v_pk_add_f32 v[8:9], v[8:9], v[72:73]
	v_pk_add_f32 v[2:3], v[2:3], v[66:67]
	v_pk_add_f32 v[4:5], v[4:5], v[68:69]
	s_mov_b64 vcc, s[4:5]
	v_cndmask_b32_dpp v78, v10, v14, vcc row_ror:8 row_mask:0xf bank_mask:0xf bound_ctrl:1
	v_cndmask_b32_dpp v79, v11, v15, vcc row_ror:8 row_mask:0xf bank_mask:0xf bound_ctrl:1
	v_cndmask_b32_dpp v80, v12, v16, vcc row_ror:8 row_mask:0xf bank_mask:0xf bound_ctrl:1
	v_cndmask_b32_dpp v81, v13, v17, vcc row_ror:8 row_mask:0xf bank_mask:0xf bound_ctrl:1
	v_cndmask_b32_dpp v70, v2, v6, vcc row_ror:8 row_mask:0xf bank_mask:0xf bound_ctrl:1
	v_cndmask_b32_dpp v71, v3, v7, vcc row_ror:8 row_mask:0xf bank_mask:0xf bound_ctrl:1
	v_cndmask_b32_dpp v72, v4, v8, vcc row_ror:8 row_mask:0xf bank_mask:0xf bound_ctrl:1
	v_cndmask_b32_dpp v73, v5, v9, vcc row_ror:8 row_mask:0xf bank_mask:0xf bound_ctrl:1
	s_not_b64 vcc, s[4:5]
	v_cndmask_b32_dpp v74, v14, v10, vcc row_ror:8 row_mask:0xf bank_mask:0xf bound_ctrl:1
	v_cndmask_b32_dpp v75, v15, v11, vcc row_ror:8 row_mask:0xf bank_mask:0xf bound_ctrl:1
	v_cndmask_b32_dpp v76, v16, v12, vcc row_ror:8 row_mask:0xf bank_mask:0xf bound_ctrl:1
	v_cndmask_b32_dpp v77, v17, v13, vcc row_ror:8 row_mask:0xf bank_mask:0xf bound_ctrl:1
	v_cndmask_b32_dpp v66, v6, v2, vcc row_ror:8 row_mask:0xf bank_mask:0xf bound_ctrl:1
	v_cndmask_b32_dpp v67, v7, v3, vcc row_ror:8 row_mask:0xf bank_mask:0xf bound_ctrl:1
	v_cndmask_b32_dpp v68, v8, v4, vcc row_ror:8 row_mask:0xf bank_mask:0xf bound_ctrl:1
	v_cndmask_b32_dpp v69, v9, v5, vcc row_ror:8 row_mask:0xf bank_mask:0xf bound_ctrl:1
	s_add_u32 s100, s28, 0xb0000
	s_addc_u32 s101, s29, 0
	global_store_dwordx4 v186, v[78:81], s[100:101]
	global_store_dwordx4 v187, v[74:77], s[100:101]
	global_store_dwordx4 v186, v[70:73], s[100:101] offset:512
	global_store_dwordx4 v187, v[66:69], s[100:101] offset:512
	s_and_b64 vcc, exec, s[6:7]
	s_cbranch_vccz .LBB0_35
	s_waitcnt vmcnt(0)
	s_cmpk_gt_u32 s13, 0xff
	s_cbranch_scc1 .LBB0_46
	s_barrier

.LBB0_63:
	s_add_i32 s96, s96, 2
	s_cmp_gt_u32 s96, 15
	s_cselect_b32 s97, 0x13fff800, 0
	s_cmp_gt_u32 s96, 13
	s_cselect_b32 s86, 0x13fff800, 0
	s_add_u32 s86, s86, s84
	s_addc_u32 s87, 0, s85
	s_add_u32 s86, s82, s86
	s_addc_u32 s87, s83, s87
	s_add_u32 s86, s86, 0x100
	s_addc_u32 s87, s87, 0
	s_add_u32 vcc_lo, s94, s84
	s_addc_u32 vcc_hi, s95, s85
	s_add_i32 s13, 0, 0x10000
	v_add_u32_e32 v0, s13, v202
	ds_read_b128 v[132:135], v0
	ds_read_b128 v[136:139], v0 offset:1024
	ds_read_b128 v[140:143], v0 offset:2048
	ds_read_b128 v[144:147], v0 offset:3072
	s_cmpk_eq_i32 s84, 0xf00
	s_cselect_b32 s89, s25, s87
	s_cselect_b32 s88, s92, s86
	s_cselect_b32 s87, s23, vcc_hi
	s_cselect_b32 s86, s93, vcc_lo
	s_add_u32 vcc_lo, s97, s84
	s_addc_u32 vcc_hi, 0, s85
	v_lshl_add_u64 v[2:3], v[200:201], 0, vcc
	s_add_i32 m0, s59, 0xc000
	ds_read_b128 v[148:151], v204
	ds_read_b128 v[152:155], v204 offset:1024
	ds_read_b128 v[156:159], v204 offset:2048
	ds_read_b128 v[160:163], v204 offset:3072
	ds_read_b128 v[164:167], v204 offset:4096
	ds_read_b128 v[168:171], v204 offset:5120
	ds_read_b128 v[172:175], v204 offset:6144
	ds_read_b128 v[176:179], v204 offset:7168
	global_load_lds_dwordx4 v[2:3], off
	v_lshl_add_u64 v[2:3], v[194:195], 0, vcc
	s_add_i32 m0, s59, 0xe000
	s_nop 0
	global_load_lds_dwordx4 v[2:3], off
	s_waitcnt lgkmcnt(8)
	s_setprio 1
	s_barrier
	s_waitcnt lgkmcnt(0)
	v_mfma_f32_16x16x32_bf16 v[128:131], v[132:135], v[148:151], v[128:131]
	v_mfma_f32_16x16x32_bf16 v[124:127], v[140:143], v[148:151], v[124:127]
	v_mfma_f32_16x16x32_bf16 v[112:115], v[132:135], v[156:159], v[112:115]
	v_mfma_f32_16x16x32_bf16 v[108:111], v[140:143], v[156:159], v[108:111]
	v_mfma_f32_16x16x32_bf16 v[96:99], v[132:135], v[164:167], v[96:99]
	v_mfma_f32_16x16x32_bf16 v[92:95], v[140:143], v[164:167], v[92:95]
	v_mfma_f32_16x16x32_bf16 v[80:83], v[132:135], v[172:175], v[80:83]
	v_mfma_f32_16x16x32_bf16 v[76:79], v[140:143], v[172:175], v[76:79]
	v_mfma_f32_16x16x32_bf16 v[128:131], v[136:139], v[152:155], v[128:131]
	v_mfma_f32_16x16x32_bf16 v[124:127], v[144:147], v[152:155], v[124:127]
	v_mfma_f32_16x16x32_bf16 v[112:115], v[136:139], v[160:163], v[112:115]
	v_mfma_f32_16x16x32_bf16 v[108:111], v[144:147], v[160:163], v[108:111]
	v_mfma_f32_16x16x32_bf16 v[96:99], v[136:139], v[168:171], v[96:99]
	v_mfma_f32_16x16x32_bf16 v[92:95], v[144:147], v[168:171], v[92:95]
	v_mfma_f32_16x16x32_bf16 v[80:83], v[136:139], v[176:179], v[80:83]
	v_mfma_f32_16x16x32_bf16 v[76:79], v[144:147], v[176:179], v[76:79]
	s_barrier
	s_setprio 0
	s_add_i32 s97, 0, 0x14000
	s_add_i32 s13, s13, s46
	v_add_u32_e32 v0, s97, v202
	v_lshl_add_u64 v[214:215], s[86:87], 0, v[184:185]
	s_mov_b32 m0, s13
	ds_read_b128 v[196:199], v0
	ds_read_b128 v[206:209], v0 offset:1024
	ds_read_b128 v[210:213], v0 offset:2048
	ds_read_b128 v[218:221], v0 offset:3072
	global_load_lds_dwordx4 v[214:215], off
	v_lshl_add_u64 v[222:223], s[86:87], 0, v[180:181]
	s_add_i32 m0, s13, 0x2000
	s_nop 0
	global_load_lds_dwordx4 v[222:223], off
	s_setprio 1
	s_barrier
	s_waitcnt lgkmcnt(0)
	v_mfma_f32_16x16x32_bf16 v[120:123], v[196:199], v[148:151], v[120:123]
	v_mfma_f32_16x16x32_bf16 v[116:119], v[210:213], v[148:151], v[116:119]
	v_mfma_f32_16x16x32_bf16 v[104:107], v[196:199], v[156:159], v[104:107]
	v_mfma_f32_16x16x32_bf16 v[100:103], v[210:213], v[156:159], v[100:103]
	v_mfma_f32_16x16x32_bf16 v[88:91], v[196:199], v[164:167], v[88:91]
	v_mfma_f32_16x16x32_bf16 v[84:87], v[210:213], v[164:167], v[84:87]
	v_mfma_f32_16x16x32_bf16 v[72:75], v[196:199], v[172:175], v[72:75]
	v_mfma_f32_16x16x32_bf16 v[68:71], v[210:213], v[172:175], v[68:71]
	v_mfma_f32_16x16x32_bf16 v[120:123], v[206:209], v[152:155], v[120:123]
	v_mfma_f32_16x16x32_bf16 v[116:119], v[218:221], v[152:155], v[116:119]
	v_mfma_f32_16x16x32_bf16 v[104:107], v[206:209], v[160:163], v[104:107]
	v_mfma_f32_16x16x32_bf16 v[100:103], v[218:221], v[160:163], v[100:103]
	v_mfma_f32_16x16x32_bf16 v[88:91], v[206:209], v[168:171], v[88:91]
	v_mfma_f32_16x16x32_bf16 v[84:87], v[218:221], v[168:171], v[84:87]
	v_mfma_f32_16x16x32_bf16 v[72:75], v[206:209], v[176:179], v[72:75]
	v_mfma_f32_16x16x32_bf16 v[68:71], v[218:221], v[176:179], v[68:71]
	s_barrier
	s_setprio 0
	s_mov_b32 m0, s59
	v_lshl_add_u64 v[224:225], s[88:89], 0, v[186:187]
	ds_read_b128 v[148:151], v204 offset:16384
	ds_read_b128 v[152:155], v204 offset:17408
	ds_read_b128 v[156:159], v204 offset:18432
	ds_read_b128 v[160:163], v204 offset:19456
	ds_read_b128 v[164:167], v204 offset:20480
	ds_read_b128 v[168:171], v204 offset:21504
	ds_read_b128 v[172:175], v204 offset:22528
	ds_read_b128 v[176:179], v204 offset:23552
	global_load_lds_dwordx4 v[224:225], off
	v_lshl_add_u64 v[226:227], s[88:89], 0, v[182:183]
	s_mov_b32 m0, s60
	s_nop 0
	global_load_lds_dwordx4 v[226:227], off
	s_setprio 1
	s_barrier
	s_waitcnt lgkmcnt(0)
	v_mfma_f32_16x16x32_bf16 v[64:67], v[132:135], v[148:151], v[64:67]
	v_mfma_f32_16x16x32_bf16 v[60:63], v[140:143], v[148:151], v[60:63]
	v_mfma_f32_16x16x32_bf16 v[48:51], v[132:135], v[156:159], v[48:51]
	v_mfma_f32_16x16x32_bf16 v[44:47], v[140:143], v[156:159], v[44:47]
	v_mfma_f32_16x16x32_bf16 v[32:35], v[132:135], v[164:167], v[32:35]
	v_mfma_f32_16x16x32_bf16 v[28:31], v[140:143], v[164:167], v[28:31]
	v_mfma_f32_16x16x32_bf16 v[16:19], v[132:135], v[172:175], v[16:19]
	v_mfma_f32_16x16x32_bf16 v[12:15], v[140:143], v[172:175], v[12:15]
	v_mfma_f32_16x16x32_bf16 v[64:67], v[136:139], v[152:155], v[64:67]
	v_mfma_f32_16x16x32_bf16 v[60:63], v[144:147], v[152:155], v[60:63]
	v_mfma_f32_16x16x32_bf16 v[48:51], v[136:139], v[160:163], v[48:51]
	v_mfma_f32_16x16x32_bf16 v[44:47], v[144:147], v[160:163], v[44:47]
	v_mfma_f32_16x16x32_bf16 v[32:35], v[136:139], v[168:171], v[32:35]
	v_mfma_f32_16x16x32_bf16 v[28:31], v[144:147], v[168:171], v[28:31]
	v_mfma_f32_16x16x32_bf16 v[16:19], v[136:139], v[176:179], v[16:19]
	v_mfma_f32_16x16x32_bf16 v[12:15], v[144:147], v[176:179], v[12:15]
	s_barrier
	s_setprio 0
	s_add_u32 vcc_lo, s86, 0x80000
	s_addc_u32 vcc_hi, s87, 0
	s_add_i32 s13, s97, s46
	v_lshl_add_u64 v[2:3], vcc, 0, v[184:185]
	s_mov_b32 m0, s13
	s_nop 0
	global_load_lds_dwordx4 v[2:3], off
	v_lshl_add_u64 v[2:3], vcc, 0, v[180:181]
	s_add_i32 m0, s13, 0x2000
	s_nop 0
	global_load_lds_dwordx4 v[2:3], off
	s_waitcnt vmcnt(6)
	s_setprio 1
	s_barrier
	v_mfma_f32_16x16x32_bf16 v[56:59], v[196:199], v[148:151], v[56:59]
	v_mfma_f32_16x16x32_bf16 v[52:55], v[210:213], v[148:151], v[52:55]
	v_mfma_f32_16x16x32_bf16 v[40:43], v[196:199], v[156:159], v[40:43]
	v_mfma_f32_16x16x32_bf16 v[36:39], v[210:213], v[156:159], v[36:39]
	v_mfma_f32_16x16x32_bf16 v[24:27], v[196:199], v[164:167], v[24:27]
	v_mfma_f32_16x16x32_bf16 v[20:23], v[210:213], v[164:167], v[20:23]
	v_mfma_f32_16x16x32_bf16 v[8:11], v[196:199], v[172:175], v[8:11]
	v_mfma_f32_16x16x32_bf16 v[2:5], v[210:213], v[172:175], v[4:7]
	v_mfma_f32_16x16x32_bf16 v[56:59], v[206:209], v[152:155], v[56:59]
	v_mfma_f32_16x16x32_bf16 v[52:55], v[218:221], v[152:155], v[52:55]
	v_mfma_f32_16x16x32_bf16 v[40:43], v[206:209], v[160:163], v[40:43]
	v_mfma_f32_16x16x32_bf16 v[36:39], v[218:221], v[160:163], v[36:39]
	v_mfma_f32_16x16x32_bf16 v[24:27], v[206:209], v[168:171], v[24:27]
	v_mfma_f32_16x16x32_bf16 v[20:23], v[218:221], v[168:171], v[20:23]
	v_mfma_f32_16x16x32_bf16 v[8:11], v[206:209], v[176:179], v[8:11]
	v_mfma_f32_16x16x32_bf16 v[2:5], v[218:221], v[176:179], v[2:5]
	s_barrier
	s_setprio 0
	s_add_i32 s13, 0, 0x18000
	v_add_u32_e32 v0, s13, v202
	ds_read_b128 v[132:135], v0
	ds_read_b128 v[136:139], v0 offset:1024
	ds_read_b128 v[140:143], v0 offset:2048
	ds_read_b128 v[144:147], v0 offset:3072
	s_add_u32 s88, s88, 0x40000
	s_addc_u32 s89, s89, 0
	s_mov_b32 m0, s61
	v_lshl_add_u64 v[6:7], s[88:89], 0, v[186:187]
	ds_read_b128 v[148:151], v204 offset:32768
	ds_read_b128 v[152:155], v204 offset:33792
	ds_read_b128 v[156:159], v204 offset:34816
	ds_read_b128 v[160:163], v204 offset:35840
	ds_read_b128 v[164:167], v204 offset:36864
	ds_read_b128 v[168:171], v204 offset:37888
	ds_read_b128 v[172:175], v204 offset:38912
	ds_read_b128 v[176:179], v204 offset:39936
	global_load_lds_dwordx4 v[6:7], off
	v_lshl_add_u64 v[6:7], s[88:89], 0, v[182:183]
	s_mov_b32 m0, s76
	s_nop 0
	global_load_lds_dwordx4 v[6:7], off
	s_waitcnt lgkmcnt(8)
	s_setprio 1
	s_barrier
	s_waitcnt lgkmcnt(0)
	v_mfma_f32_16x16x32_bf16 v[128:131], v[132:135], v[148:151], v[128:131]
	v_mfma_f32_16x16x32_bf16 v[124:127], v[140:143], v[148:151], v[124:127]
	v_mfma_f32_16x16x32_bf16 v[112:115], v[132:135], v[156:159], v[112:115]
	v_mfma_f32_16x16x32_bf16 v[108:111], v[140:143], v[156:159], v[108:111]
	v_mfma_f32_16x16x32_bf16 v[96:99], v[132:135], v[164:167], v[96:99]
	v_mfma_f32_16x16x32_bf16 v[92:95], v[140:143], v[164:167], v[92:95]
	v_mfma_f32_16x16x32_bf16 v[80:83], v[132:135], v[172:175], v[80:83]
	v_mfma_f32_16x16x32_bf16 v[76:79], v[140:143], v[172:175], v[76:79]
	v_mfma_f32_16x16x32_bf16 v[128:131], v[136:139], v[152:155], v[128:131]
	v_mfma_f32_16x16x32_bf16 v[124:127], v[144:147], v[152:155], v[124:127]
	v_mfma_f32_16x16x32_bf16 v[112:115], v[136:139], v[160:163], v[112:115]
	v_mfma_f32_16x16x32_bf16 v[108:111], v[144:147], v[160:163], v[108:111]
	v_mfma_f32_16x16x32_bf16 v[96:99], v[136:139], v[168:171], v[96:99]
	v_mfma_f32_16x16x32_bf16 v[92:95], v[144:147], v[168:171], v[92:95]
	v_mfma_f32_16x16x32_bf16 v[80:83], v[136:139], v[176:179], v[80:83]
	v_mfma_f32_16x16x32_bf16 v[76:79], v[144:147], v[176:179], v[76:79]
	s_barrier
	s_setprio 0
	s_add_i32 s88, 0, 0x1c000
	s_add_i32 s13, s13, s46
	v_add_u32_e32 v0, s88, v202
	v_lshl_add_u64 v[6:7], v[214:215], 0, s[48:49]
	s_mov_b32 m0, s13
	ds_read_b128 v[196:199], v0
	ds_read_b128 v[206:209], v0 offset:1024
	ds_read_b128 v[210:213], v0 offset:2048
	ds_read_b128 v[218:221], v0 offset:3072
	global_load_lds_dwordx4 v[6:7], off
	v_lshl_add_u64 v[6:7], v[222:223], 0, s[48:49]
	s_add_i32 m0, s13, 0x2000
	s_nop 0
	global_load_lds_dwordx4 v[6:7], off
	s_setprio 1
	s_barrier
	s_waitcnt lgkmcnt(0)
	v_mfma_f32_16x16x32_bf16 v[120:123], v[196:199], v[148:151], v[120:123]
	v_mfma_f32_16x16x32_bf16 v[116:119], v[210:213], v[148:151], v[116:119]
	v_mfma_f32_16x16x32_bf16 v[104:107], v[196:199], v[156:159], v[104:107]
	v_mfma_f32_16x16x32_bf16 v[100:103], v[210:213], v[156:159], v[100:103]
	v_mfma_f32_16x16x32_bf16 v[88:91], v[196:199], v[164:167], v[88:91]
	v_mfma_f32_16x16x32_bf16 v[84:87], v[210:213], v[164:167], v[84:87]
	v_mfma_f32_16x16x32_bf16 v[72:75], v[196:199], v[172:175], v[72:75]
	v_mfma_f32_16x16x32_bf16 v[68:71], v[210:213], v[172:175], v[68:71]
	v_mfma_f32_16x16x32_bf16 v[120:123], v[206:209], v[152:155], v[120:123]
	v_mfma_f32_16x16x32_bf16 v[116:119], v[218:221], v[152:155], v[116:119]
	v_mfma_f32_16x16x32_bf16 v[104:107], v[206:209], v[160:163], v[104:107]
	v_mfma_f32_16x16x32_bf16 v[100:103], v[218:221], v[160:163], v[100:103]
	v_mfma_f32_16x16x32_bf16 v[88:91], v[206:209], v[168:171], v[88:91]
	v_mfma_f32_16x16x32_bf16 v[84:87], v[218:221], v[168:171], v[84:87]
	v_mfma_f32_16x16x32_bf16 v[72:75], v[206:209], v[176:179], v[72:75]
	v_mfma_f32_16x16x32_bf16 v[68:71], v[218:221], v[176:179], v[68:71]
	s_barrier
	s_setprio 0
	s_mov_b32 m0, s77
	v_lshl_add_u64 v[6:7], v[224:225], 0, s[48:49]
	ds_read_b128 v[148:151], v204 offset:49152
	ds_read_b128 v[152:155], v204 offset:50176
	ds_read_b128 v[156:159], v204 offset:51200
	ds_read_b128 v[160:163], v204 offset:52224
	ds_read_b128 v[164:167], v204 offset:53248
	ds_read_b128 v[168:171], v204 offset:54272
	ds_read_b128 v[172:175], v204 offset:55296
	ds_read_b128 v[176:179], v204 offset:56320
	global_load_lds_dwordx4 v[6:7], off
	v_lshl_add_u64 v[6:7], v[226:227], 0, s[48:49]
	s_mov_b32 m0, s90
	s_nop 0
	global_load_lds_dwordx4 v[6:7], off
	s_setprio 1
	s_barrier
	s_waitcnt lgkmcnt(0)
	v_mfma_f32_16x16x32_bf16 v[64:67], v[132:135], v[148:151], v[64:67]
	v_mfma_f32_16x16x32_bf16 v[60:63], v[140:143], v[148:151], v[60:63]
	v_mfma_f32_16x16x32_bf16 v[48:51], v[132:135], v[156:159], v[48:51]
	v_mfma_f32_16x16x32_bf16 v[44:47], v[140:143], v[156:159], v[44:47]
	v_mfma_f32_16x16x32_bf16 v[32:35], v[132:135], v[164:167], v[32:35]
	v_mfma_f32_16x16x32_bf16 v[28:31], v[140:143], v[164:167], v[28:31]
	v_mfma_f32_16x16x32_bf16 v[16:19], v[132:135], v[172:175], v[16:19]
	v_mfma_f32_16x16x32_bf16 v[12:15], v[140:143], v[172:175], v[12:15]
	v_mfma_f32_16x16x32_bf16 v[64:67], v[136:139], v[152:155], v[64:67]
	v_mfma_f32_16x16x32_bf16 v[60:63], v[144:147], v[152:155], v[60:63]
	v_mfma_f32_16x16x32_bf16 v[48:51], v[136:139], v[160:163], v[48:51]
	v_mfma_f32_16x16x32_bf16 v[44:47], v[144:147], v[160:163], v[44:47]
	v_mfma_f32_16x16x32_bf16 v[32:35], v[136:139], v[168:171], v[32:35]
	v_mfma_f32_16x16x32_bf16 v[28:31], v[144:147], v[168:171], v[28:31]
	v_mfma_f32_16x16x32_bf16 v[16:19], v[136:139], v[176:179], v[16:19]
	v_mfma_f32_16x16x32_bf16 v[12:15], v[144:147], v[176:179], v[12:15]
	s_barrier
	s_setprio 0
	s_add_u32 s86, s86, 0x80080
	s_addc_u32 s87, s87, 0
	s_add_i32 s13, s88, s46
	v_lshl_add_u64 v[6:7], s[86:87], 0, v[184:185]
	s_mov_b32 m0, s13
	s_nop 0
	global_load_lds_dwordx4 v[6:7], off
	v_lshl_add_u64 v[6:7], s[86:87], 0, v[180:181]
	s_add_i32 m0, s13, 0x2000
	s_nop 0
	global_load_lds_dwordx4 v[6:7], off
	s_waitcnt vmcnt(6)
	s_setprio 1
	s_barrier
	v_mfma_f32_16x16x32_bf16 v[56:59], v[196:199], v[148:151], v[56:59]
	v_mfma_f32_16x16x32_bf16 v[52:55], v[210:213], v[148:151], v[52:55]
	v_mfma_f32_16x16x32_bf16 v[40:43], v[196:199], v[156:159], v[40:43]
	v_mfma_f32_16x16x32_bf16 v[36:39], v[210:213], v[156:159], v[36:39]
	v_mfma_f32_16x16x32_bf16 v[24:27], v[196:199], v[164:167], v[24:27]
	v_mfma_f32_16x16x32_bf16 v[20:23], v[210:213], v[164:167], v[20:23]
	v_mfma_f32_16x16x32_bf16 v[6:9], v[196:199], v[172:175], v[8:11]
	v_mfma_f32_16x16x32_bf16 v[2:5], v[210:213], v[172:175], v[2:5]
	v_mfma_f32_16x16x32_bf16 v[56:59], v[206:209], v[152:155], v[56:59]
	v_mfma_f32_16x16x32_bf16 v[52:55], v[218:221], v[152:155], v[52:55]
	v_mfma_f32_16x16x32_bf16 v[40:43], v[206:209], v[160:163], v[40:43]
	v_mfma_f32_16x16x32_bf16 v[36:39], v[218:221], v[160:163], v[36:39]
	v_mfma_f32_16x16x32_bf16 v[24:27], v[206:209], v[168:171], v[24:27]
	v_mfma_f32_16x16x32_bf16 v[20:23], v[218:221], v[168:171], v[20:23]
	v_mfma_f32_16x16x32_bf16 v[8:11], v[206:209], v[176:179], v[6:9]
	v_mfma_f32_16x16x32_bf16 v[4:7], v[218:221], v[176:179], v[2:5]
	s_barrier
	s_setprio 0
	s_add_u32 s84, s84, 0x100
	s_addc_u32 s85, 0, s85
	s_cmp_gt_u32 s96, 29
	s_cbranch_scc1 .LBB0_55

.LBB0_409:
	s_add_u32 s8, s84, 0xfffc0080
	s_addc_u32 s9, s85, -1
	s_add_i32 s10, 0, 0x10000
	v_add_u32_e32 v0, s10, v159
	ds_read_b128 v[142:145], v0
	ds_read_b128 v[146:149], v0 offset:1024
	ds_read_b128 v[150:153], v0 offset:2048
	ds_read_b128 v[154:157], v0 offset:3072
	s_cmp_eq_u32 s46, 12
	s_cselect_b32 s89, s23, s9
	s_cselect_b32 s88, s60, s8
	s_cselect_b32 s87, s21, vcc_hi
	s_cselect_b32 s86, s61, vcc_lo
	v_lshl_add_u64 v[196:197], s[84:85], 0, v[140:141]
	s_add_i32 m0, s25, 0xc000
	ds_read_b128 v[180:183], v177
	ds_read_b128 v[184:187], v177 offset:1024
	ds_read_b128 v[188:191], v177 offset:2048
	ds_read_b128 v[192:195], v177 offset:3072
	ds_read_b128 v[200:203], v177 offset:4096
	ds_read_b128 v[204:207], v177 offset:5120
	ds_read_b128 v[208:211], v177 offset:6144
	ds_read_b128 v[212:215], v177 offset:7168
	global_load_lds_dwordx4 v[196:197], off
	v_lshl_add_u64 v[196:197], s[84:85], 0, v[138:139]
	s_add_i32 m0, s25, 0xe000
	s_nop 0
	global_load_lds_dwordx4 v[196:197], off
	s_waitcnt lgkmcnt(8)
	s_setprio 1
	s_barrier
	s_waitcnt lgkmcnt(0)
	v_mfma_f32_16x16x32_bf16 v[126:129], v[142:145], v[180:183], v[126:129]
	v_mfma_f32_16x16x32_bf16 v[118:121], v[150:153], v[180:183], v[118:121]
	v_mfma_f32_16x16x32_bf16 v[122:125], v[142:145], v[188:191], v[122:125]
	v_mfma_f32_16x16x32_bf16 v[110:113], v[150:153], v[188:191], v[110:113]
	v_mfma_f32_16x16x32_bf16 v[114:117], v[142:145], v[200:203], v[114:117]
	v_mfma_f32_16x16x32_bf16 v[102:105], v[150:153], v[200:203], v[102:105]
	v_mfma_f32_16x16x32_bf16 v[106:109], v[142:145], v[208:211], v[106:109]
	v_mfma_f32_16x16x32_bf16 v[98:101], v[150:153], v[208:211], v[98:101]
	v_mfma_f32_16x16x32_bf16 v[126:129], v[146:149], v[184:187], v[126:129]
	v_mfma_f32_16x16x32_bf16 v[118:121], v[154:157], v[184:187], v[118:121]
	v_mfma_f32_16x16x32_bf16 v[122:125], v[146:149], v[192:195], v[122:125]
	v_mfma_f32_16x16x32_bf16 v[110:113], v[154:157], v[192:195], v[110:113]
	v_mfma_f32_16x16x32_bf16 v[114:117], v[146:149], v[204:207], v[114:117]
	v_mfma_f32_16x16x32_bf16 v[102:105], v[154:157], v[204:207], v[102:105]
	v_mfma_f32_16x16x32_bf16 v[106:109], v[146:149], v[212:215], v[106:109]
	v_mfma_f32_16x16x32_bf16 v[98:101], v[154:157], v[212:215], v[98:101]
	s_barrier
	s_setprio 0
	s_add_i32 s11, 0, 0x14000
	s_add_i32 s8, s10, s59
	v_add_u32_e32 v0, s11, v159
	v_lshl_add_u64 v[196:197], s[86:87], 0, v[132:133]
	s_mov_b32 m0, s8
	ds_read_b128 v[218:221], v0
	ds_read_b128 v[222:225], v0 offset:1024
	ds_read_b128 v[226:229], v0 offset:2048
	ds_read_b128 v[230:233], v0 offset:3072
	global_load_lds_dwordx4 v[196:197], off
	v_lshl_add_u64 v[198:199], s[86:87], 0, v[136:137]
	s_add_i32 m0, s8, 0x2000
	s_nop 0
	global_load_lds_dwordx4 v[198:199], off
	s_setprio 1
	s_barrier
	s_waitcnt lgkmcnt(0)
	v_mfma_f32_16x16x32_bf16 v[62:65], v[218:221], v[180:183], v[62:65]
	v_mfma_f32_16x16x32_bf16 v[54:57], v[226:229], v[180:183], v[54:57]
	v_mfma_f32_16x16x32_bf16 v[58:61], v[218:221], v[188:191], v[58:61]
	v_mfma_f32_16x16x32_bf16 v[46:49], v[226:229], v[188:191], v[46:49]
	v_mfma_f32_16x16x32_bf16 v[50:53], v[218:221], v[200:203], v[50:53]
	v_mfma_f32_16x16x32_bf16 v[38:41], v[226:229], v[200:203], v[38:41]
	v_mfma_f32_16x16x32_bf16 v[42:45], v[218:221], v[208:211], v[42:45]
	v_mfma_f32_16x16x32_bf16 v[34:37], v[226:229], v[208:211], v[34:37]
	v_mfma_f32_16x16x32_bf16 v[62:65], v[222:225], v[184:187], v[62:65]
	v_mfma_f32_16x16x32_bf16 v[54:57], v[230:233], v[184:187], v[54:57]
	v_mfma_f32_16x16x32_bf16 v[58:61], v[222:225], v[192:195], v[58:61]
	v_mfma_f32_16x16x32_bf16 v[46:49], v[230:233], v[192:195], v[46:49]
	v_mfma_f32_16x16x32_bf16 v[50:53], v[222:225], v[204:207], v[50:53]
	v_mfma_f32_16x16x32_bf16 v[38:41], v[230:233], v[204:207], v[38:41]
	v_mfma_f32_16x16x32_bf16 v[42:45], v[222:225], v[212:215], v[42:45]
	v_mfma_f32_16x16x32_bf16 v[34:37], v[230:233], v[212:215], v[34:37]
	s_barrier
	s_setprio 0
	s_mov_b32 m0, s25
	v_lshl_add_u64 v[234:235], s[88:89], 0, v[130:131]
	ds_read_b128 v[180:183], v177 offset:16384
	ds_read_b128 v[184:187], v177 offset:17408
	ds_read_b128 v[188:191], v177 offset:18432
	ds_read_b128 v[192:195], v177 offset:19456
	ds_read_b128 v[200:203], v177 offset:20480
	ds_read_b128 v[204:207], v177 offset:21504
	ds_read_b128 v[208:211], v177 offset:22528
	ds_read_b128 v[212:215], v177 offset:23552
	global_load_lds_dwordx4 v[234:235], off
	v_lshl_add_u64 v[236:237], s[88:89], 0, v[134:135]
	s_mov_b32 m0, s76
	s_nop 0
	global_load_lds_dwordx4 v[236:237], off
	s_setprio 1
	s_barrier
	s_waitcnt lgkmcnt(0)
	v_mfma_f32_16x16x32_bf16 v[94:97], v[142:145], v[180:183], v[94:97]
	v_mfma_f32_16x16x32_bf16 v[86:89], v[150:153], v[180:183], v[86:89]
	v_mfma_f32_16x16x32_bf16 v[90:93], v[142:145], v[188:191], v[90:93]
	v_mfma_f32_16x16x32_bf16 v[78:81], v[150:153], v[188:191], v[78:81]
	v_mfma_f32_16x16x32_bf16 v[82:85], v[142:145], v[200:203], v[82:85]
	v_mfma_f32_16x16x32_bf16 v[70:73], v[150:153], v[200:203], v[70:73]
	v_mfma_f32_16x16x32_bf16 v[74:77], v[142:145], v[208:211], v[74:77]
	v_mfma_f32_16x16x32_bf16 v[66:69], v[150:153], v[208:211], v[66:69]
	v_mfma_f32_16x16x32_bf16 v[94:97], v[146:149], v[184:187], v[94:97]
	v_mfma_f32_16x16x32_bf16 v[86:89], v[154:157], v[184:187], v[86:89]
	v_mfma_f32_16x16x32_bf16 v[90:93], v[146:149], v[192:195], v[90:93]
	v_mfma_f32_16x16x32_bf16 v[78:81], v[154:157], v[192:195], v[78:81]
	v_mfma_f32_16x16x32_bf16 v[82:85], v[146:149], v[204:207], v[82:85]
	v_mfma_f32_16x16x32_bf16 v[70:73], v[154:157], v[204:207], v[70:73]
	v_mfma_f32_16x16x32_bf16 v[74:77], v[146:149], v[212:215], v[74:77]
	v_mfma_f32_16x16x32_bf16 v[66:69], v[154:157], v[212:215], v[66:69]
	s_barrier
	s_setprio 0
	s_add_u32 s8, s86, 0x40000
	s_addc_u32 s9, s87, 0
	s_add_i32 s10, s11, s59
	v_lshl_add_u64 v[142:143], s[8:9], 0, v[132:133]
	s_mov_b32 m0, s10
	s_nop 0
	global_load_lds_dwordx4 v[142:143], off
	v_lshl_add_u64 v[142:143], s[8:9], 0, v[136:137]
	s_add_i32 m0, s10, 0x2000
	s_nop 0
	global_load_lds_dwordx4 v[142:143], off
	s_waitcnt vmcnt(6)
	s_setprio 1
	s_barrier
	v_mfma_f32_16x16x32_bf16 v[30:33], v[218:221], v[180:183], v[30:33]
	v_mfma_f32_16x16x32_bf16 v[22:25], v[226:229], v[180:183], v[22:25]
	v_mfma_f32_16x16x32_bf16 v[26:29], v[218:221], v[188:191], v[26:29]
	v_mfma_f32_16x16x32_bf16 v[14:17], v[226:229], v[188:191], v[14:17]
	v_mfma_f32_16x16x32_bf16 v[18:21], v[218:221], v[200:203], v[18:21]
	v_mfma_f32_16x16x32_bf16 v[6:9], v[226:229], v[200:203], v[6:9]
	v_mfma_f32_16x16x32_bf16 v[10:13], v[218:221], v[208:211], v[10:13]
	v_mfma_f32_16x16x32_bf16 v[2:5], v[226:229], v[208:211], v[2:5]
	v_mfma_f32_16x16x32_bf16 v[30:33], v[222:225], v[184:187], v[30:33]
	v_mfma_f32_16x16x32_bf16 v[22:25], v[230:233], v[184:187], v[22:25]
	v_mfma_f32_16x16x32_bf16 v[26:29], v[222:225], v[192:195], v[26:29]
	v_mfma_f32_16x16x32_bf16 v[14:17], v[230:233], v[192:195], v[14:17]
	v_mfma_f32_16x16x32_bf16 v[18:21], v[222:225], v[204:207], v[18:21]
	v_mfma_f32_16x16x32_bf16 v[6:9], v[230:233], v[204:207], v[6:9]
	v_mfma_f32_16x16x32_bf16 v[10:13], v[222:225], v[212:215], v[10:13]
	v_mfma_f32_16x16x32_bf16 v[2:5], v[230:233], v[212:215], v[2:5]
	s_barrier
	s_setprio 0
	s_add_i32 s10, 0, 0x18000
	v_add_u32_e32 v0, s10, v159
	ds_read_b128 v[142:145], v0
	ds_read_b128 v[146:149], v0 offset:1024
	ds_read_b128 v[150:153], v0 offset:2048
	ds_read_b128 v[154:157], v0 offset:3072
	s_add_u32 s8, s88, 0x40000
	s_addc_u32 s9, s89, 0
	s_mov_b32 m0, s79
	v_lshl_add_u64 v[218:219], s[8:9], 0, v[130:131]
	ds_read_b128 v[180:183], v177 offset:32768
	ds_read_b128 v[184:187], v177 offset:33792
	ds_read_b128 v[188:191], v177 offset:34816
	ds_read_b128 v[192:195], v177 offset:35840
	ds_read_b128 v[200:203], v177 offset:36864
	ds_read_b128 v[204:207], v177 offset:37888
	ds_read_b128 v[208:211], v177 offset:38912
	ds_read_b128 v[212:215], v177 offset:39936
	global_load_lds_dwordx4 v[218:219], off
	v_lshl_add_u64 v[218:219], s[8:9], 0, v[134:135]
	s_mov_b32 m0, s93
	s_nop 0
	global_load_lds_dwordx4 v[218:219], off
	s_waitcnt lgkmcnt(8)
	s_setprio 1
	s_barrier
	s_waitcnt lgkmcnt(0)
	v_mfma_f32_16x16x32_bf16 v[126:129], v[142:145], v[180:183], v[126:129]
	v_mfma_f32_16x16x32_bf16 v[118:121], v[150:153], v[180:183], v[118:121]
	v_mfma_f32_16x16x32_bf16 v[122:125], v[142:145], v[188:191], v[122:125]
	v_mfma_f32_16x16x32_bf16 v[110:113], v[150:153], v[188:191], v[110:113]
	v_mfma_f32_16x16x32_bf16 v[114:117], v[142:145], v[200:203], v[114:117]
	v_mfma_f32_16x16x32_bf16 v[102:105], v[150:153], v[200:203], v[102:105]
	v_mfma_f32_16x16x32_bf16 v[106:109], v[142:145], v[208:211], v[106:109]
	v_mfma_f32_16x16x32_bf16 v[98:101], v[150:153], v[208:211], v[98:101]
	v_mfma_f32_16x16x32_bf16 v[126:129], v[146:149], v[184:187], v[126:129]
	v_mfma_f32_16x16x32_bf16 v[118:121], v[154:157], v[184:187], v[118:121]
	v_mfma_f32_16x16x32_bf16 v[122:125], v[146:149], v[192:195], v[122:125]
	v_mfma_f32_16x16x32_bf16 v[110:113], v[154:157], v[192:195], v[110:113]
	v_mfma_f32_16x16x32_bf16 v[114:117], v[146:149], v[204:207], v[114:117]
	v_mfma_f32_16x16x32_bf16 v[102:105], v[154:157], v[204:207], v[102:105]
	v_mfma_f32_16x16x32_bf16 v[106:109], v[146:149], v[212:215], v[106:109]
	v_mfma_f32_16x16x32_bf16 v[98:101], v[154:157], v[212:215], v[98:101]
	s_barrier
	s_setprio 0
	s_add_i32 s11, 0, 0x1c000
	s_add_i32 s8, s10, s59
	v_add_u32_e32 v0, s11, v159
	v_lshl_add_u64 v[196:197], v[196:197], 0, s[48:49]
	s_mov_b32 m0, s8
	ds_read_b128 v[218:221], v0
	ds_read_b128 v[222:225], v0 offset:1024
	ds_read_b128 v[226:229], v0 offset:2048
	ds_read_b128 v[230:233], v0 offset:3072
	global_load_lds_dwordx4 v[196:197], off
	v_lshl_add_u64 v[196:197], v[198:199], 0, s[48:49]
	s_add_i32 m0, s8, 0x2000
	s_nop 0
	global_load_lds_dwordx4 v[196:197], off
	s_setprio 1
	s_barrier
	s_waitcnt lgkmcnt(0)
	v_mfma_f32_16x16x32_bf16 v[62:65], v[218:221], v[180:183], v[62:65]
	v_mfma_f32_16x16x32_bf16 v[54:57], v[226:229], v[180:183], v[54:57]
	v_mfma_f32_16x16x32_bf16 v[58:61], v[218:221], v[188:191], v[58:61]
	v_mfma_f32_16x16x32_bf16 v[46:49], v[226:229], v[188:191], v[46:49]
	v_mfma_f32_16x16x32_bf16 v[50:53], v[218:221], v[200:203], v[50:53]
	v_mfma_f32_16x16x32_bf16 v[38:41], v[226:229], v[200:203], v[38:41]
	v_mfma_f32_16x16x32_bf16 v[42:45], v[218:221], v[208:211], v[42:45]
	v_mfma_f32_16x16x32_bf16 v[34:37], v[226:229], v[208:211], v[34:37]
	v_mfma_f32_16x16x32_bf16 v[62:65], v[222:225], v[184:187], v[62:65]
	v_mfma_f32_16x16x32_bf16 v[54:57], v[230:233], v[184:187], v[54:57]
	v_mfma_f32_16x16x32_bf16 v[58:61], v[222:225], v[192:195], v[58:61]
	v_mfma_f32_16x16x32_bf16 v[46:49], v[230:233], v[192:195], v[46:49]
	v_mfma_f32_16x16x32_bf16 v[50:53], v[222:225], v[204:207], v[50:53]
	v_mfma_f32_16x16x32_bf16 v[38:41], v[230:233], v[204:207], v[38:41]
	v_mfma_f32_16x16x32_bf16 v[42:45], v[222:225], v[212:215], v[42:45]
	v_mfma_f32_16x16x32_bf16 v[34:37], v[230:233], v[212:215], v[34:37]
	s_barrier
	s_setprio 0
	s_mov_b32 m0, s94
	v_lshl_add_u64 v[196:197], v[234:235], 0, s[48:49]
	ds_read_b128 v[180:183], v177 offset:49152
	ds_read_b128 v[184:187], v177 offset:50176
	ds_read_b128 v[188:191], v177 offset:51200
	ds_read_b128 v[192:195], v177 offset:52224
	ds_read_b128 v[200:203], v177 offset:53248
	ds_read_b128 v[204:207], v177 offset:54272
	ds_read_b128 v[208:211], v177 offset:55296
	ds_read_b128 v[212:215], v177 offset:56320
	global_load_lds_dwordx4 v[196:197], off
	v_lshl_add_u64 v[196:197], v[236:237], 0, s[48:49]
	s_mov_b32 m0, s95
	s_nop 0
	global_load_lds_dwordx4 v[196:197], off
	s_setprio 1
	s_barrier
;     DEVI void operator()(AccRef acc, const pg8::Unit& u, int wr, int wc, int fr, int fq) const {
;         const int sel = u.pn >> 2; bf16_t* dst = (bf16_t*)(ws + (size_t)(sel + 1) * UNIT);
;         const int row0 = u.pm * 256 + wr * 64 + fr, col0 = (u.pn & 3) * 256 + wc * 32 + 8 * fq, bcol0 = u.pn * 256 + wc * 32 + 8 * fq + (u.pn >= 12 ? 8 : 0);
; #pragma unroll
;         for (int bj = 0; bj < 2; ++bj)
; #pragma unroll
;             for (int n = 0; n < 2; ++n) { const f32x4 bv = *(const f32x4*)(bias + bcol0 + bj * 128 + n * 4);
; #pragma unroll
;                 for (int ai = 0; ai < 2; ++ai)
; #pragma unroll
;                     for (int m = 0; m < 4; ++m) acc[ai][bj][m][n] += bv; }
	s_waitcnt lgkmcnt(0)
	v_mfma_f32_16x16x32_bf16 v[94:97], v[142:145], v[180:183], v[94:97]
	v_mfma_f32_16x16x32_bf16 v[86:89], v[150:153], v[180:183], v[86:89]
	v_mfma_f32_16x16x32_bf16 v[90:93], v[142:145], v[188:191], v[90:93]
	v_mfma_f32_16x16x32_bf16 v[78:81], v[150:153], v[188:191], v[78:81]
	v_mfma_f32_16x16x32_bf16 v[82:85], v[142:145], v[200:203], v[82:85]
	v_mfma_f32_16x16x32_bf16 v[70:73], v[150:153], v[200:203], v[70:73]
	v_mfma_f32_16x16x32_bf16 v[74:77], v[142:145], v[208:211], v[74:77]
	v_mfma_f32_16x16x32_bf16 v[66:69], v[150:153], v[208:211], v[66:69]
	v_mfma_f32_16x16x32_bf16 v[94:97], v[146:149], v[184:187], v[94:97]
	v_mfma_f32_16x16x32_bf16 v[86:89], v[154:157], v[184:187], v[86:89]
	v_mfma_f32_16x16x32_bf16 v[90:93], v[146:149], v[192:195], v[90:93]
	v_mfma_f32_16x16x32_bf16 v[78:81], v[154:157], v[192:195], v[78:81]
	v_mfma_f32_16x16x32_bf16 v[82:85], v[146:149], v[204:207], v[82:85]
	v_mfma_f32_16x16x32_bf16 v[70:73], v[154:157], v[204:207], v[70:73]
	v_mfma_f32_16x16x32_bf16 v[74:77], v[146:149], v[212:215], v[74:77]
	v_mfma_f32_16x16x32_bf16 v[66:69], v[154:157], v[212:215], v[66:69]
	s_barrier
	s_setprio 0
	s_add_u32 s8, s86, 0x40080
	s_addc_u32 s9, s87, 0
	s_add_i32 s10, s11, s59
	v_lshl_add_u64 v[142:143], s[8:9], 0, v[132:133]
	s_mov_b32 m0, s10
	s_nop 0
	global_load_lds_dwordx4 v[142:143], off
	v_lshl_add_u64 v[142:143], s[8:9], 0, v[136:137]
	s_add_i32 m0, s10, 0x2000
	s_nop 0
	global_load_lds_dwordx4 v[142:143], off
	s_waitcnt vmcnt(6)
	s_setprio 1
	s_barrier
	v_mfma_f32_16x16x32_bf16 v[30:33], v[218:221], v[180:183], v[30:33]
	v_mfma_f32_16x16x32_bf16 v[22:25], v[226:229], v[180:183], v[22:25]
	v_mfma_f32_16x16x32_bf16 v[26:29], v[218:221], v[188:191], v[26:29]
	v_mfma_f32_16x16x32_bf16 v[14:17], v[226:229], v[188:191], v[14:17]
	v_mfma_f32_16x16x32_bf16 v[18:21], v[218:221], v[200:203], v[18:21]
	v_mfma_f32_16x16x32_bf16 v[6:9], v[226:229], v[200:203], v[6:9]
	v_mfma_f32_16x16x32_bf16 v[10:13], v[218:221], v[208:211], v[10:13]
	v_mfma_f32_16x16x32_bf16 v[2:5], v[226:229], v[208:211], v[2:5]
	v_mfma_f32_16x16x32_bf16 v[30:33], v[222:225], v[184:187], v[30:33]
	v_mfma_f32_16x16x32_bf16 v[22:25], v[230:233], v[184:187], v[22:25]
	v_mfma_f32_16x16x32_bf16 v[26:29], v[222:225], v[192:195], v[26:29]
	v_mfma_f32_16x16x32_bf16 v[14:17], v[230:233], v[192:195], v[14:17]
	v_mfma_f32_16x16x32_bf16 v[18:21], v[222:225], v[204:207], v[18:21]
	v_mfma_f32_16x16x32_bf16 v[6:9], v[230:233], v[204:207], v[6:9]
	v_mfma_f32_16x16x32_bf16 v[10:13], v[222:225], v[212:215], v[10:13]
	v_mfma_f32_16x16x32_bf16 v[2:5], v[230:233], v[212:215], v[2:5]
	s_barrier
	s_setprio 0
	s_add_i32 s46, s46, 2
	s_add_u32 vcc_lo, vcc_lo, 0x100
	s_addc_u32 vcc_hi, vcc_hi, 0
	s_add_u32 s84, s84, 0x100
	s_addc_u32 s85, s85, 0
	s_cmp_gt_u32 s46, 13
	s_cbranch_scc0 .LBB0_409
	s_lshl_b32 s21, s24, 8
	s_cmp_gt_i32 s24, 11
	s_cselect_b32 s8, 8, 0
	v_or_b32_e32 v0, s21, v160
	v_add_u32_e32 v142, s8, v0
	v_ashrrev_i32_e32 v143, 31, v142
	v_lshl_add_u64 v[146:147], v[142:143], 2, s[16:17]
	global_load_dwordx4 v[148:151], v[146:147], off offset:16
	global_load_dwordx4 v[142:145], v[146:147], off
	global_load_dwordx4 v[238:241], v[146:147], off offset:528
	global_load_dwordx4 v[242:245], v[146:147], off offset:512
	s_cmp_gt_i32 s24, 7
	s_waitcnt vmcnt(0)
	v_pk_add_f32 v[128:129], v[128:129], v[144:145]
	v_pk_add_f32 v[126:127], v[126:127], v[142:143]
	v_pk_add_f32 v[124:125], v[124:125], v[144:145]
	v_pk_add_f32 v[122:123], v[122:123], v[142:143]
	v_pk_add_f32 v[116:117], v[116:117], v[144:145]
	v_pk_add_f32 v[114:115], v[114:115], v[142:143]
	v_pk_add_f32 v[108:109], v[108:109], v[144:145]
	v_pk_add_f32 v[106:107], v[106:107], v[142:143]
	v_pk_add_f32 v[96:97], v[96:97], v[144:145]
	v_pk_add_f32 v[94:95], v[94:95], v[142:143]
	v_pk_add_f32 v[92:93], v[92:93], v[144:145]
	v_pk_add_f32 v[90:91], v[90:91], v[142:143]
	v_pk_add_f32 v[84:85], v[84:85], v[144:145]
	v_pk_add_f32 v[82:83], v[82:83], v[142:143]
	v_pk_add_f32 v[76:77], v[76:77], v[144:145]
	v_pk_add_f32 v[74:75], v[74:75], v[142:143]
	v_pk_add_f32 v[142:143], v[120:121], v[150:151]
	v_pk_add_f32 v[144:145], v[118:119], v[148:149]
	v_pk_add_f32 v[118:119], v[112:113], v[150:151]
	v_pk_add_f32 v[120:121], v[110:111], v[148:149]
	v_pk_add_f32 v[110:111], v[104:105], v[150:151]
	v_pk_add_f32 v[112:113], v[102:103], v[148:149]
	v_pk_add_f32 v[102:103], v[100:101], v[150:151]
	v_pk_add_f32 v[104:105], v[98:99], v[148:149]
	v_pk_add_f32 v[98:99], v[88:89], v[150:151]
	v_pk_add_f32 v[100:101], v[86:87], v[148:149]
	v_pk_add_f32 v[86:87], v[80:81], v[150:151]
	v_pk_add_f32 v[88:89], v[78:79], v[148:149]
	v_pk_add_f32 v[78:79], v[72:73], v[150:151]
	v_pk_add_f32 v[80:81], v[70:71], v[148:149]
	v_pk_add_f32 v[70:71], v[68:69], v[150:151]
	v_pk_add_f32 v[72:73], v[66:67], v[148:149]
	v_pk_add_f32 v[154:155], v[56:57], v[240:241]
	v_pk_add_f32 v[150:151], v[64:65], v[244:245]
	v_pk_add_f32 v[152:153], v[62:63], v[242:243]
	v_pk_add_f32 v[62:63], v[60:61], v[244:245]
	v_pk_add_f32 v[64:65], v[58:59], v[242:243]
	v_pk_add_f32 v[58:59], v[52:53], v[244:245]
	v_pk_add_f32 v[60:61], v[50:51], v[242:243]
	v_pk_add_f32 v[50:51], v[44:45], v[244:245]
	v_pk_add_f32 v[52:53], v[42:43], v[242:243]
	v_pk_add_f32 v[42:43], v[32:33], v[244:245]
	v_pk_add_f32 v[44:45], v[30:31], v[242:243]
	v_pk_add_f32 v[30:31], v[28:29], v[244:245]
	v_pk_add_f32 v[32:33], v[26:27], v[242:243]
	v_pk_add_f32 v[26:27], v[20:21], v[244:245]
	v_pk_add_f32 v[28:29], v[18:19], v[242:243]
	v_pk_add_f32 v[18:19], v[12:13], v[244:245]
	v_pk_add_f32 v[20:21], v[10:11], v[242:243]
	v_pk_add_f32 v[156:157], v[54:55], v[238:239]
	v_pk_add_f32 v[146:147], v[48:49], v[240:241]
	v_pk_add_f32 v[148:149], v[46:47], v[238:239]
	v_pk_add_f32 v[54:55], v[40:41], v[240:241]
	v_pk_add_f32 v[56:57], v[38:39], v[238:239]
	v_pk_add_f32 v[46:47], v[36:37], v[240:241]
	v_pk_add_f32 v[48:49], v[34:35], v[238:239]
	v_pk_add_f32 v[38:39], v[24:25], v[240:241]
	v_pk_add_f32 v[40:41], v[22:23], v[238:239]
	v_pk_add_f32 v[34:35], v[16:17], v[240:241]
	v_pk_add_f32 v[36:37], v[14:15], v[238:239]
	v_pk_add_f32 v[22:23], v[8:9], v[240:241]
	v_pk_add_f32 v[24:25], v[6:7], v[238:239]
	v_pk_add_f32 v[14:15], v[4:5], v[240:241]
	v_pk_add_f32 v[16:17], v[2:3], v[238:239]
	s_cbranch_scc1 .LBB0_405
;     DEVI void operator()(AccRef acc, const pg8::Unit& u, int wr, int wc, int fr, int fq) const {
;     ...
;                     for (int bj = 0; bj < 2; ++bj) { const f32x4 a = acc[ai][bj][m][0], b = acc[ai][bj][m][1];
;                         float s = (a[0] * a[0] + a[1] * a[1]) + (a[2] * a[2] + a[3] * a[3]) + (b[0] * b[0] + b[1] * b[1]) + (b[2] * b[2] + b[3] * b[3]);
;                         s = xrow16_sum(s);
;                         if (fq == 0) Pt[((ai * 128 + wr * 64 + m * 16 + fr) * 2 + bj) * 4 + wc] = s; }
	v_mul_f32_e32 v0, v127, v127
	v_mul_f32_e32 v2, v129, v129
	v_fmac_f32_e32 v0, v126, v126
	v_fmac_f32_e32 v2, v128, v128
	v_add_f32_e32 v0, v0, v2
	v_mul_f32_e32 v2, v145, v145
	v_fmac_f32_e32 v2, v144, v144
	v_add_f32_e32 v0, v0, v2
	v_mul_f32_e32 v2, v143, v143
	v_fmac_f32_e32 v2, v142, v142
	v_add_f32_e32 v0, v2, v0
	v_mov_b32_e32 v2, v0
	s_nop 1
	v_permlane16_swap_b32_e32 v0, v2
	v_add_f32_e32 v0, v0, v2
	v_mov_b32_e32 v2, v0
	s_nop 1
	v_permlane32_swap_b32_e32 v0, v2
	s_and_saveexec_b64 s[60:61], s[4:5]
	v_add_f32_e32 v0, v0, v2
	ds_write_b32 v162, v0
	s_or_b64 exec, exec, s[60:61]
	v_mul_f32_e32 v0, v153, v153
	v_mul_f32_e32 v2, v151, v151
	v_fmac_f32_e32 v0, v152, v152
	v_fmac_f32_e32 v2, v150, v150
	v_add_f32_e32 v0, v0, v2
	v_mul_f32_e32 v2, v157, v157
	v_fmac_f32_e32 v2, v156, v156
	v_add_f32_e32 v0, v2, v0
	v_mul_f32_e32 v2, v155, v155
	v_fmac_f32_e32 v2, v154, v154
	v_add_f32_e32 v0, v2, v0
	v_mov_b32_e32 v2, v0
	s_nop 1
	v_permlane16_swap_b32_e32 v0, v2
	v_add_f32_e32 v0, v0, v2
	v_mov_b32_e32 v2, v0
	s_nop 1
	v_permlane32_swap_b32_e32 v0, v2
	s_and_saveexec_b64 s[60:61], s[4:5]
	v_add_f32_e32 v0, v0, v2
	ds_write_b32 v162, v0 offset:16
	s_or_b64 exec, exec, s[60:61]
	v_mul_f32_e32 v0, v123, v123
	v_mul_f32_e32 v2, v125, v125
	v_fmac_f32_e32 v0, v122, v122
	v_fmac_f32_e32 v2, v124, v124
	v_add_f32_e32 v0, v0, v2
	v_mul_f32_e32 v2, v121, v121
	v_fmac_f32_e32 v2, v120, v120
	v_add_f32_e32 v0, v0, v2
	v_mul_f32_e32 v2, v119, v119
	v_fmac_f32_e32 v2, v118, v118
	v_add_f32_e32 v0, v2, v0
	v_mov_b32_e32 v2, v0
	s_nop 1
	v_permlane16_swap_b32_e32 v0, v2
	v_add_f32_e32 v0, v0, v2
	v_mov_b32_e32 v2, v0
	s_nop 1
	v_permlane32_swap_b32_e32 v0, v2
	s_and_saveexec_b64 s[60:61], s[4:5]
	v_add_f32_e32 v0, v0, v2
	ds_write_b32 v163, v0
	s_or_b64 exec, exec, s[60:61]
	v_mul_f32_e32 v0, v65, v65
	v_mul_f32_e32 v2, v63, v63
	v_fmac_f32_e32 v0, v64, v64
	v_fmac_f32_e32 v2, v62, v62
	v_add_f32_e32 v0, v0, v2
	v_mul_f32_e32 v2, v149, v149
	v_fmac_f32_e32 v2, v148, v148
	v_add_f32_e32 v0, v0, v2
	v_mul_f32_e32 v2, v147, v147
	v_fmac_f32_e32 v2, v146, v146
	v_add_f32_e32 v0, v2, v0
	v_mov_b32_e32 v2, v0
	s_nop 1
	v_permlane16_swap_b32_e32 v0, v2
	v_add_f32_e32 v0, v0, v2
	v_mov_b32_e32 v2, v0
	s_nop 1
	v_permlane32_swap_b32_e32 v0, v2
	s_and_saveexec_b64 s[60:61], s[4:5]
	v_add_f32_e32 v0, v0, v2
	ds_write_b32 v163, v0 offset:16
	s_or_b64 exec, exec, s[60:61]
	v_mul_f32_e32 v0, v115, v115
	v_mul_f32_e32 v2, v117, v117
	v_fmac_f32_e32 v0, v114, v114
	v_fmac_f32_e32 v2, v116, v116
	v_add_f32_e32 v0, v0, v2
	v_mul_f32_e32 v2, v113, v113
	v_fmac_f32_e32 v2, v112, v112
	v_add_f32_e32 v0, v0, v2
	v_mul_f32_e32 v2, v111, v111
	v_fmac_f32_e32 v2, v110, v110
	v_add_f32_e32 v0, v2, v0
	v_mov_b32_e32 v2, v0
	s_nop 1
	v_permlane16_swap_b32_e32 v0, v2
	v_add_f32_e32 v0, v0, v2
	v_mov_b32_e32 v2, v0
	s_nop 1
	v_permlane32_swap_b32_e32 v0, v2
	s_and_saveexec_b64 s[60:61], s[4:5]
	v_add_f32_e32 v0, v0, v2
	ds_write_b32 v164, v0
	s_or_b64 exec, exec, s[60:61]
	v_mul_f32_e32 v0, v61, v61
	v_mul_f32_e32 v2, v59, v59
	v_fmac_f32_e32 v0, v60, v60
	v_fmac_f32_e32 v2, v58, v58
	v_add_f32_e32 v0, v0, v2
	v_mul_f32_e32 v2, v57, v57
	v_fmac_f32_e32 v2, v56, v56
	v_add_f32_e32 v0, v0, v2
	v_mul_f32_e32 v2, v55, v55
	v_fmac_f32_e32 v2, v54, v54
	v_add_f32_e32 v0, v2, v0
	v_mov_b32_e32 v2, v0
	s_nop 1
	v_permlane16_swap_b32_e32 v0, v2
	v_add_f32_e32 v0, v0, v2
	v_mov_b32_e32 v2, v0
	s_nop 1
	v_permlane32_swap_b32_e32 v0, v2
	s_and_saveexec_b64 s[60:61], s[4:5]
	v_add_f32_e32 v0, v0, v2
	ds_write_b32 v164, v0 offset:16
	s_or_b64 exec, exec, s[60:61]
	v_mul_f32_e32 v0, v107, v107
	v_mul_f32_e32 v2, v109, v109
	v_fmac_f32_e32 v0, v106, v106
	v_fmac_f32_e32 v2, v108, v108
	v_add_f32_e32 v0, v0, v2
	v_mul_f32_e32 v2, v105, v105
	v_fmac_f32_e32 v2, v104, v104
	v_add_f32_e32 v0, v0, v2
	v_mul_f32_e32 v2, v103, v103
	v_fmac_f32_e32 v2, v102, v102
	v_add_f32_e32 v0, v2, v0
	v_mov_b32_e32 v2, v0
	s_nop 1
	v_permlane16_swap_b32_e32 v0, v2
	v_add_f32_e32 v0, v0, v2
	v_mov_b32_e32 v2, v0
	s_nop 1
	v_permlane32_swap_b32_e32 v0, v2
	s_and_saveexec_b64 s[60:61], s[4:5]
	v_add_f32_e32 v0, v0, v2
	ds_write_b32 v165, v0
	s_or_b64 exec, exec, s[60:61]
	v_mul_f32_e32 v0, v53, v53
	v_mul_f32_e32 v2, v51, v51
	v_fmac_f32_e32 v0, v52, v52
	v_fmac_f32_e32 v2, v50, v50
	v_add_f32_e32 v0, v0, v2
	v_mul_f32_e32 v2, v49, v49
	v_fmac_f32_e32 v2, v48, v48
	v_add_f32_e32 v0, v0, v2
	v_mul_f32_e32 v2, v47, v47
	v_fmac_f32_e32 v2, v46, v46
	v_add_f32_e32 v0, v2, v0
	v_mov_b32_e32 v2, v0
	s_nop 1
	v_permlane16_swap_b32_e32 v0, v2
	v_add_f32_e32 v0, v0, v2
	v_mov_b32_e32 v2, v0
	s_nop 1
	v_permlane32_swap_b32_e32 v0, v2
	s_and_saveexec_b64 s[60:61], s[4:5]
	v_add_f32_e32 v0, v0, v2
	ds_write_b32 v165, v0 offset:16
;     DEVI void operator()(AccRef acc, const pg8::Unit& u, int wr, int wc, int fr, int fq) const {
;     ...
;                     for (int bj = 0; bj < 2; ++bj) { const f32x4 a = acc[ai][bj][m][0], b = acc[ai][bj][m][1];
;                         float s = (a[0] * a[0] + a[1] * a[1]) + (a[2] * a[2] + a[3] * a[3]) + (b[0] * b[0] + b[1] * b[1]) + (b[2] * b[2] + b[3] * b[3]);
;                         s = xrow16_sum(s);
;                         if (fq == 0) Pt[((ai * 128 + wr * 64 + m * 16 + fr) * 2 + bj) * 4 + wc] = s; }
	s_or_b64 exec, exec, s[60:61]
	v_mul_f32_e32 v0, v95, v95
	v_mul_f32_e32 v2, v97, v97
	v_fmac_f32_e32 v0, v94, v94
	v_fmac_f32_e32 v2, v96, v96
	v_add_f32_e32 v0, v0, v2
	v_mul_f32_e32 v2, v101, v101
	v_fmac_f32_e32 v2, v100, v100
	v_add_f32_e32 v0, v0, v2
	v_mul_f32_e32 v2, v99, v99
	v_fmac_f32_e32 v2, v98, v98
	v_add_f32_e32 v0, v2, v0
	v_mov_b32_e32 v2, v0
	s_nop 1
	v_permlane16_swap_b32_e32 v0, v2
	v_add_f32_e32 v0, v0, v2
	v_mov_b32_e32 v2, v0
	s_nop 1
	v_permlane32_swap_b32_e32 v0, v2
	s_and_saveexec_b64 s[60:61], s[4:5]
	v_add_f32_e32 v0, v0, v2
	ds_write_b32 v166, v0
	s_or_b64 exec, exec, s[60:61]
	v_mul_f32_e32 v0, v45, v45
	v_mul_f32_e32 v2, v43, v43
	v_fmac_f32_e32 v0, v44, v44
	v_fmac_f32_e32 v2, v42, v42
	v_add_f32_e32 v0, v0, v2
	v_mul_f32_e32 v2, v41, v41
	v_fmac_f32_e32 v2, v40, v40
	v_add_f32_e32 v0, v0, v2
	v_mul_f32_e32 v2, v39, v39
	v_fmac_f32_e32 v2, v38, v38
	v_add_f32_e32 v0, v2, v0
	v_mov_b32_e32 v2, v0
	s_nop 1
	v_permlane16_swap_b32_e32 v0, v2
	v_add_f32_e32 v0, v0, v2
	v_mov_b32_e32 v2, v0
	s_nop 1
	v_permlane32_swap_b32_e32 v0, v2
	s_and_saveexec_b64 s[60:61], s[4:5]
	v_add_f32_e32 v0, v0, v2
	ds_write_b32 v166, v0 offset:16
	s_or_b64 exec, exec, s[60:61]
	v_mul_f32_e32 v0, v91, v91
	v_mul_f32_e32 v2, v93, v93
	v_fmac_f32_e32 v0, v90, v90
	v_fmac_f32_e32 v2, v92, v92
	v_add_f32_e32 v0, v0, v2
	v_mul_f32_e32 v2, v89, v89
	v_fmac_f32_e32 v2, v88, v88
	v_add_f32_e32 v0, v0, v2
	v_mul_f32_e32 v2, v87, v87
	v_fmac_f32_e32 v2, v86, v86
	v_add_f32_e32 v0, v2, v0
	v_mov_b32_e32 v2, v0
	s_nop 1
	v_permlane16_swap_b32_e32 v0, v2
	v_add_f32_e32 v0, v0, v2
	v_mov_b32_e32 v2, v0
	s_nop 1
	v_permlane32_swap_b32_e32 v0, v2
	s_and_saveexec_b64 s[60:61], s[4:5]
	v_add_f32_e32 v0, v0, v2
	ds_write_b32 v167, v0
	s_or_b64 exec, exec, s[60:61]
	v_mul_f32_e32 v0, v33, v33
	v_mul_f32_e32 v2, v31, v31
	v_fmac_f32_e32 v0, v32, v32
	v_fmac_f32_e32 v2, v30, v30
	v_add_f32_e32 v0, v0, v2
	v_mul_f32_e32 v2, v37, v37
	v_fmac_f32_e32 v2, v36, v36
	v_add_f32_e32 v0, v0, v2
	v_mul_f32_e32 v2, v35, v35
	v_fmac_f32_e32 v2, v34, v34
	v_add_f32_e32 v0, v2, v0
	v_mov_b32_e32 v2, v0
	s_nop 1
	v_permlane16_swap_b32_e32 v0, v2
	v_add_f32_e32 v0, v0, v2
	v_mov_b32_e32 v2, v0
	s_nop 1
	v_permlane32_swap_b32_e32 v0, v2
	s_and_saveexec_b64 s[60:61], s[4:5]
	v_add_f32_e32 v0, v0, v2
	ds_write_b32 v167, v0 offset:16
	s_or_b64 exec, exec, s[60:61]
	v_mul_f32_e32 v0, v83, v83
	v_mul_f32_e32 v2, v85, v85
	v_fmac_f32_e32 v0, v82, v82
	v_fmac_f32_e32 v2, v84, v84
	v_add_f32_e32 v0, v0, v2
	v_mul_f32_e32 v2, v81, v81
	v_fmac_f32_e32 v2, v80, v80
	v_add_f32_e32 v0, v0, v2
	v_mul_f32_e32 v2, v79, v79
	v_fmac_f32_e32 v2, v78, v78
	v_add_f32_e32 v0, v2, v0
	v_mov_b32_e32 v2, v0
	s_nop 1
	v_permlane16_swap_b32_e32 v0, v2
	v_add_f32_e32 v0, v0, v2
	v_mov_b32_e32 v2, v0
	s_nop 1
	v_permlane32_swap_b32_e32 v0, v2
	s_and_saveexec_b64 s[60:61], s[4:5]
	v_add_f32_e32 v0, v0, v2
	ds_write_b32 v168, v0
	s_or_b64 exec, exec, s[60:61]
	v_mul_f32_e32 v0, v29, v29
	v_mul_f32_e32 v2, v27, v27
	v_fmac_f32_e32 v0, v28, v28
	v_fmac_f32_e32 v2, v26, v26
	v_add_f32_e32 v0, v0, v2
	v_mul_f32_e32 v2, v25, v25
	v_fmac_f32_e32 v2, v24, v24
	v_add_f32_e32 v0, v0, v2
	v_mul_f32_e32 v2, v23, v23
	v_fmac_f32_e32 v2, v22, v22
	v_add_f32_e32 v0, v2, v0
	v_mov_b32_e32 v2, v0
	s_nop 1
	v_permlane16_swap_b32_e32 v0, v2
	v_add_f32_e32 v0, v0, v2
	v_mov_b32_e32 v2, v0
	s_nop 1
	v_permlane32_swap_b32_e32 v0, v2
	s_and_saveexec_b64 s[60:61], s[4:5]
	v_add_f32_e32 v0, v0, v2
	ds_write_b32 v168, v0 offset:16
	s_or_b64 exec, exec, s[60:61]
	v_mul_f32_e32 v0, v75, v75
	v_mul_f32_e32 v2, v77, v77
	v_fmac_f32_e32 v0, v74, v74
	v_fmac_f32_e32 v2, v76, v76
	v_add_f32_e32 v0, v0, v2
	v_mul_f32_e32 v2, v73, v73
	v_fmac_f32_e32 v2, v72, v72
	v_add_f32_e32 v0, v0, v2
	v_mul_f32_e32 v2, v71, v71
	v_fmac_f32_e32 v2, v70, v70
	v_add_f32_e32 v0, v2, v0
	v_mov_b32_e32 v2, v0
	s_nop 1
	v_permlane16_swap_b32_e32 v0, v2
	v_add_f32_e32 v0, v0, v2
	v_mov_b32_e32 v2, v0
	s_nop 1
	v_permlane32_swap_b32_e32 v0, v2
	s_and_saveexec_b64 s[60:61], s[4:5]
	v_add_f32_e32 v0, v0, v2
	ds_write_b32 v169, v0
	s_or_b64 exec, exec, s[60:61]
	v_mul_f32_e32 v0, v21, v21
	v_mul_f32_e32 v2, v19, v19
	v_fmac_f32_e32 v0, v20, v20
	v_fmac_f32_e32 v2, v18, v18
	v_add_f32_e32 v0, v0, v2
	v_mul_f32_e32 v2, v17, v17
	v_fmac_f32_e32 v2, v16, v16
	v_add_f32_e32 v0, v0, v2
	v_mul_f32_e32 v2, v15, v15
	v_fmac_f32_e32 v2, v14, v14
	v_add_f32_e32 v0, v2, v0
	v_mov_b32_e32 v2, v0
	s_nop 1
	v_permlane16_swap_b32_e32 v0, v2
	v_add_f32_e32 v0, v0, v2
	v_mov_b32_e32 v2, v0
	s_nop 1
	v_permlane32_swap_b32_e32 v0, v2
	s_and_saveexec_b64 s[60:61], s[4:5]
	s_cbranch_execz .LBB0_404
	v_add_f32_e32 v0, v0, v2
	ds_write_b32 v169, v0 offset:16
	s_branch .LBB0_404

.LBB0_511:
	s_add_u32 s18, s14, 0x100
	s_addc_u32 s19, s15, 0
	s_add_i32 s84, 0, 0x10000
	v_add_u32_e32 v0, s84, v189
	ds_read_b128 v[122:125], v0
	ds_read_b128 v[126:129], v0 offset:1024
	ds_read_b128 v[130:133], v0 offset:2048
	ds_read_b128 v[134:137], v0 offset:3072
	s_cmp_eq_u32 s83, 40
	s_cselect_b32 s23, s9, s19
	s_cselect_b32 s22, s8, s18
	s_cselect_b32 s21, s11, s82
	s_cselect_b32 s20, s10, s81
	v_lshl_add_u64 v[186:187], s[14:15], 0, v[184:185]
	s_add_i32 m0, s46, 0xc000
	ds_read_b128 v[146:149], v193
	ds_read_b128 v[150:153], v193 offset:1024
	ds_read_b128 v[154:157], v193 offset:2048
	ds_read_b128 v[158:161], v193 offset:3072
	ds_read_b128 v[162:165], v193 offset:4096
	ds_read_b128 v[166:169], v193 offset:5120
	ds_read_b128 v[170:173], v193 offset:6144
	ds_read_b128 v[174:177], v193 offset:7168
	global_load_lds_dwordx4 v[186:187], off
	v_lshl_add_u64 v[186:187], s[14:15], 0, v[182:183]
	s_add_i32 m0, s46, 0xe000
	s_nop 0
	global_load_lds_dwordx4 v[186:187], off
	s_waitcnt lgkmcnt(8)
	s_setprio 1
	s_barrier
	s_waitcnt lgkmcnt(0)
	v_mfma_f32_16x16x32_bf16 v[142:145], v[122:125], v[146:149], v[142:145]
	v_mfma_f32_16x16x32_bf16 v[138:141], v[130:133], v[146:149], v[138:141]
	v_mfma_f32_16x16x32_bf16 v[110:113], v[122:125], v[154:157], v[110:113]
	v_mfma_f32_16x16x32_bf16 v[106:109], v[130:133], v[154:157], v[106:109]
	v_mfma_f32_16x16x32_bf16 v[94:97], v[122:125], v[162:165], v[94:97]
	v_mfma_f32_16x16x32_bf16 v[90:93], v[130:133], v[162:165], v[90:93]
	v_mfma_f32_16x16x32_bf16 v[78:81], v[122:125], v[170:173], v[78:81]
	v_mfma_f32_16x16x32_bf16 v[74:77], v[130:133], v[170:173], v[74:77]
	v_mfma_f32_16x16x32_bf16 v[142:145], v[126:129], v[150:153], v[142:145]
	v_mfma_f32_16x16x32_bf16 v[138:141], v[134:137], v[150:153], v[138:141]
	v_mfma_f32_16x16x32_bf16 v[110:113], v[126:129], v[158:161], v[110:113]
	v_mfma_f32_16x16x32_bf16 v[106:109], v[134:137], v[158:161], v[106:109]
	v_mfma_f32_16x16x32_bf16 v[94:97], v[126:129], v[166:169], v[94:97]
	v_mfma_f32_16x16x32_bf16 v[90:93], v[134:137], v[166:169], v[90:93]
	v_mfma_f32_16x16x32_bf16 v[78:81], v[126:129], v[174:177], v[78:81]
	v_mfma_f32_16x16x32_bf16 v[74:77], v[134:137], v[174:177], v[74:77]
	s_barrier
	s_setprio 0
	s_add_i32 s85, 0, 0x14000
	s_add_i32 s14, s84, s25
	v_add_u32_e32 v0, s85, v189
	v_lshl_add_u64 v[186:187], s[20:21], 0, v[180:181]
	s_mov_b32 m0, s14
	ds_read_b128 v[194:197], v0
	ds_read_b128 v[200:203], v0 offset:1024
	ds_read_b128 v[204:207], v0 offset:2048
	ds_read_b128 v[208:211], v0 offset:3072
	global_load_lds_dwordx4 v[186:187], off
	v_lshl_add_u64 v[198:199], s[20:21], 0, v[178:179]
	s_add_i32 m0, s14, 0x2000
	s_nop 0
	global_load_lds_dwordx4 v[198:199], off
	s_setprio 1
	s_barrier
	s_waitcnt lgkmcnt(0)
	v_mfma_f32_16x16x32_bf16 v[118:121], v[194:197], v[146:149], v[118:121]
	v_mfma_f32_16x16x32_bf16 v[114:117], v[204:207], v[146:149], v[114:117]
	v_mfma_f32_16x16x32_bf16 v[102:105], v[194:197], v[154:157], v[102:105]
	v_mfma_f32_16x16x32_bf16 v[98:101], v[204:207], v[154:157], v[98:101]
	v_mfma_f32_16x16x32_bf16 v[86:89], v[194:197], v[162:165], v[86:89]
	v_mfma_f32_16x16x32_bf16 v[82:85], v[204:207], v[162:165], v[82:85]
	v_mfma_f32_16x16x32_bf16 v[70:73], v[194:197], v[170:173], v[70:73]
	v_mfma_f32_16x16x32_bf16 v[66:69], v[204:207], v[170:173], v[66:69]
	v_mfma_f32_16x16x32_bf16 v[118:121], v[200:203], v[150:153], v[118:121]
	v_mfma_f32_16x16x32_bf16 v[114:117], v[208:211], v[150:153], v[114:117]
	v_mfma_f32_16x16x32_bf16 v[102:105], v[200:203], v[158:161], v[102:105]
	v_mfma_f32_16x16x32_bf16 v[98:101], v[208:211], v[158:161], v[98:101]
	v_mfma_f32_16x16x32_bf16 v[86:89], v[200:203], v[166:169], v[86:89]
	v_mfma_f32_16x16x32_bf16 v[82:85], v[208:211], v[166:169], v[82:85]
	v_mfma_f32_16x16x32_bf16 v[70:73], v[200:203], v[174:177], v[70:73]
	v_mfma_f32_16x16x32_bf16 v[66:69], v[208:211], v[174:177], v[66:69]
	s_barrier
	s_setprio 0
	s_mov_b32 m0, s46
	v_lshl_add_u64 v[212:213], s[22:23], 0, v[180:181]
	ds_read_b128 v[146:149], v193 offset:16384
	ds_read_b128 v[150:153], v193 offset:17408
	ds_read_b128 v[154:157], v193 offset:18432
	ds_read_b128 v[158:161], v193 offset:19456
	ds_read_b128 v[162:165], v193 offset:20480
	ds_read_b128 v[166:169], v193 offset:21504
	ds_read_b128 v[170:173], v193 offset:22528
	ds_read_b128 v[174:177], v193 offset:23552
	global_load_lds_dwordx4 v[212:213], off
	v_lshl_add_u64 v[214:215], s[22:23], 0, v[178:179]
	s_mov_b32 m0, s57
	s_nop 0
	global_load_lds_dwordx4 v[214:215], off
	s_setprio 1
	s_barrier
	s_waitcnt lgkmcnt(0)
	v_mfma_f32_16x16x32_bf16 v[62:65], v[122:125], v[146:149], v[62:65]
	v_mfma_f32_16x16x32_bf16 v[58:61], v[130:133], v[146:149], v[58:61]
	v_mfma_f32_16x16x32_bf16 v[46:49], v[122:125], v[154:157], v[46:49]
	v_mfma_f32_16x16x32_bf16 v[42:45], v[130:133], v[154:157], v[42:45]
	v_mfma_f32_16x16x32_bf16 v[30:33], v[122:125], v[162:165], v[30:33]
	v_mfma_f32_16x16x32_bf16 v[26:29], v[130:133], v[162:165], v[26:29]
	v_mfma_f32_16x16x32_bf16 v[14:17], v[122:125], v[170:173], v[14:17]
	v_mfma_f32_16x16x32_bf16 v[10:13], v[130:133], v[170:173], v[10:13]
	v_mfma_f32_16x16x32_bf16 v[62:65], v[126:129], v[150:153], v[62:65]
	v_mfma_f32_16x16x32_bf16 v[58:61], v[134:137], v[150:153], v[58:61]
	v_mfma_f32_16x16x32_bf16 v[46:49], v[126:129], v[158:161], v[46:49]
	v_mfma_f32_16x16x32_bf16 v[42:45], v[134:137], v[158:161], v[42:45]
	v_mfma_f32_16x16x32_bf16 v[30:33], v[126:129], v[166:169], v[30:33]
	v_mfma_f32_16x16x32_bf16 v[26:29], v[134:137], v[166:169], v[26:29]
	v_mfma_f32_16x16x32_bf16 v[14:17], v[126:129], v[174:177], v[14:17]
	v_mfma_f32_16x16x32_bf16 v[10:13], v[134:137], v[174:177], v[10:13]
	s_barrier
	s_setprio 0
	s_add_u32 s14, s20, 0xb0000
	s_addc_u32 s15, s21, 0
	s_add_i32 s84, s85, s25
	v_lshl_add_u64 v[122:123], s[14:15], 0, v[180:181]
	s_mov_b32 m0, s84
	s_nop 0
	global_load_lds_dwordx4 v[122:123], off
	v_lshl_add_u64 v[122:123], s[14:15], 0, v[178:179]
	s_add_i32 m0, s84, 0x2000
	s_nop 0
	global_load_lds_dwordx4 v[122:123], off
	s_waitcnt vmcnt(6)
	s_setprio 1
	s_barrier
	v_mfma_f32_16x16x32_bf16 v[54:57], v[194:197], v[146:149], v[54:57]
	v_mfma_f32_16x16x32_bf16 v[50:53], v[204:207], v[146:149], v[50:53]
	v_mfma_f32_16x16x32_bf16 v[38:41], v[194:197], v[154:157], v[38:41]
	v_mfma_f32_16x16x32_bf16 v[34:37], v[204:207], v[154:157], v[34:37]
	v_mfma_f32_16x16x32_bf16 v[22:25], v[194:197], v[162:165], v[22:25]
	v_mfma_f32_16x16x32_bf16 v[18:21], v[204:207], v[162:165], v[18:21]
	v_mfma_f32_16x16x32_bf16 v[6:9], v[194:197], v[170:173], v[6:9]
	v_mfma_f32_16x16x32_bf16 v[2:5], v[204:207], v[170:173], v[2:5]
	v_mfma_f32_16x16x32_bf16 v[54:57], v[200:203], v[150:153], v[54:57]
	v_mfma_f32_16x16x32_bf16 v[50:53], v[208:211], v[150:153], v[50:53]
	v_mfma_f32_16x16x32_bf16 v[38:41], v[200:203], v[158:161], v[38:41]
	v_mfma_f32_16x16x32_bf16 v[34:37], v[208:211], v[158:161], v[34:37]
	v_mfma_f32_16x16x32_bf16 v[22:25], v[200:203], v[166:169], v[22:25]
	v_mfma_f32_16x16x32_bf16 v[18:21], v[208:211], v[166:169], v[18:21]
	v_mfma_f32_16x16x32_bf16 v[6:9], v[200:203], v[174:177], v[6:9]
	v_mfma_f32_16x16x32_bf16 v[2:5], v[208:211], v[174:177], v[2:5]
	s_barrier
	s_setprio 0
	s_add_i32 s84, 0, 0x18000
	v_add_u32_e32 v0, s84, v189
	ds_read_b128 v[122:125], v0
	ds_read_b128 v[126:129], v0 offset:1024
	ds_read_b128 v[130:133], v0 offset:2048
	ds_read_b128 v[134:137], v0 offset:3072
	s_add_u32 s14, s22, 0xb0000
	s_addc_u32 s15, s23, 0
	s_mov_b32 m0, s59
	v_lshl_add_u64 v[194:195], s[14:15], 0, v[180:181]
	ds_read_b128 v[146:149], v193 offset:32768
	ds_read_b128 v[150:153], v193 offset:33792
	ds_read_b128 v[154:157], v193 offset:34816
	ds_read_b128 v[158:161], v193 offset:35840
	ds_read_b128 v[162:165], v193 offset:36864
	ds_read_b128 v[166:169], v193 offset:37888
	ds_read_b128 v[170:173], v193 offset:38912
	ds_read_b128 v[174:177], v193 offset:39936
	global_load_lds_dwordx4 v[194:195], off
	v_lshl_add_u64 v[194:195], s[14:15], 0, v[178:179]
	s_mov_b32 m0, s60
	s_nop 0
	global_load_lds_dwordx4 v[194:195], off
	s_waitcnt lgkmcnt(8)
	s_setprio 1
	s_barrier
	s_waitcnt lgkmcnt(0)
	v_mfma_f32_16x16x32_bf16 v[142:145], v[122:125], v[146:149], v[142:145]
	v_mfma_f32_16x16x32_bf16 v[138:141], v[130:133], v[146:149], v[138:141]
	v_mfma_f32_16x16x32_bf16 v[110:113], v[122:125], v[154:157], v[110:113]
	v_mfma_f32_16x16x32_bf16 v[106:109], v[130:133], v[154:157], v[106:109]
	v_mfma_f32_16x16x32_bf16 v[94:97], v[122:125], v[162:165], v[94:97]
	v_mfma_f32_16x16x32_bf16 v[90:93], v[130:133], v[162:165], v[90:93]
	v_mfma_f32_16x16x32_bf16 v[78:81], v[122:125], v[170:173], v[78:81]
	v_mfma_f32_16x16x32_bf16 v[74:77], v[130:133], v[170:173], v[74:77]
	v_mfma_f32_16x16x32_bf16 v[142:145], v[126:129], v[150:153], v[142:145]
	v_mfma_f32_16x16x32_bf16 v[138:141], v[134:137], v[150:153], v[138:141]
	v_mfma_f32_16x16x32_bf16 v[110:113], v[126:129], v[158:161], v[110:113]
	v_mfma_f32_16x16x32_bf16 v[106:109], v[134:137], v[158:161], v[106:109]
	v_mfma_f32_16x16x32_bf16 v[94:97], v[126:129], v[166:169], v[94:97]
	v_mfma_f32_16x16x32_bf16 v[90:93], v[134:137], v[166:169], v[90:93]
	v_mfma_f32_16x16x32_bf16 v[78:81], v[126:129], v[174:177], v[78:81]
	v_mfma_f32_16x16x32_bf16 v[74:77], v[134:137], v[174:177], v[74:77]
	s_barrier
	s_setprio 0
	s_add_i32 s22, 0, 0x1c000
	s_add_i32 s14, s84, s25
	v_add_u32_e32 v0, s22, v189
	v_lshl_add_u64 v[186:187], v[186:187], 0, s[48:49]
	s_mov_b32 m0, s14
	ds_read_b128 v[194:197], v0
	ds_read_b128 v[200:203], v0 offset:1024
	ds_read_b128 v[204:207], v0 offset:2048
	ds_read_b128 v[208:211], v0 offset:3072
	global_load_lds_dwordx4 v[186:187], off
	v_lshl_add_u64 v[186:187], v[198:199], 0, s[48:49]
	s_add_i32 m0, s14, 0x2000
	s_nop 0
	global_load_lds_dwordx4 v[186:187], off
	s_setprio 1
	s_barrier
	s_waitcnt lgkmcnt(0)
	v_mfma_f32_16x16x32_bf16 v[118:121], v[194:197], v[146:149], v[118:121]
	v_mfma_f32_16x16x32_bf16 v[114:117], v[204:207], v[146:149], v[114:117]
	v_mfma_f32_16x16x32_bf16 v[102:105], v[194:197], v[154:157], v[102:105]
	v_mfma_f32_16x16x32_bf16 v[98:101], v[204:207], v[154:157], v[98:101]
	v_mfma_f32_16x16x32_bf16 v[86:89], v[194:197], v[162:165], v[86:89]
	v_mfma_f32_16x16x32_bf16 v[82:85], v[204:207], v[162:165], v[82:85]
	v_mfma_f32_16x16x32_bf16 v[70:73], v[194:197], v[170:173], v[70:73]
	v_mfma_f32_16x16x32_bf16 v[66:69], v[204:207], v[170:173], v[66:69]
	v_mfma_f32_16x16x32_bf16 v[118:121], v[200:203], v[150:153], v[118:121]
	v_mfma_f32_16x16x32_bf16 v[114:117], v[208:211], v[150:153], v[114:117]
	v_mfma_f32_16x16x32_bf16 v[102:105], v[200:203], v[158:161], v[102:105]
	v_mfma_f32_16x16x32_bf16 v[98:101], v[208:211], v[158:161], v[98:101]
	v_mfma_f32_16x16x32_bf16 v[86:89], v[200:203], v[166:169], v[86:89]
	v_mfma_f32_16x16x32_bf16 v[82:85], v[208:211], v[166:169], v[82:85]
	v_mfma_f32_16x16x32_bf16 v[70:73], v[200:203], v[174:177], v[70:73]
	v_mfma_f32_16x16x32_bf16 v[66:69], v[208:211], v[174:177], v[66:69]
	s_barrier
	s_setprio 0
	s_mov_b32 m0, s74
	v_lshl_add_u64 v[186:187], v[212:213], 0, s[48:49]
	ds_read_b128 v[146:149], v193 offset:49152
	ds_read_b128 v[150:153], v193 offset:50176
	ds_read_b128 v[154:157], v193 offset:51200
	ds_read_b128 v[158:161], v193 offset:52224
	ds_read_b128 v[162:165], v193 offset:53248
	ds_read_b128 v[166:169], v193 offset:54272
	ds_read_b128 v[170:173], v193 offset:55296
	ds_read_b128 v[174:177], v193 offset:56320
	global_load_lds_dwordx4 v[186:187], off
	v_lshl_add_u64 v[186:187], v[214:215], 0, s[48:49]
	s_mov_b32 m0, s75
	s_nop 0
	global_load_lds_dwordx4 v[186:187], off
	s_setprio 1
	s_barrier
;     DEVI void operator()(AccRef acc, const pg8::Unit& u, int wr, int wc, int fr, int fq) const {
;         unsigned o = (unsigned)((u.pm * 256 + wr * 64 + fr) * DM + u.pn * 256 + wc * 32 + 4 * fq) * 4u;
;         const bool lo = fr < 8;
;         unsigned os = (unsigned)((u.pm * 256 + wr * 64 + (fr & 7)) * DM + u.pn * 256 + wc * 32 + 4 * fq) * 4u + (lo ? 0u : 64u);
; #pragma unroll
;         for (int ai = 0; ai < 2; ++ai) {
;             asm volatile("" : "+v"(o), "+v"(os));
;             f32x4 b[4][2][2];
; #pragma unroll
;             for (int m = 0; m < 4; ++m)
; #pragma unroll
;                 for (int bj = 0; bj < 2; ++bj)
; #pragma unroll
;                     for (int n = 0; n < 2; ++n) b[m][bj][n] = *(const f32x4*)((const char*)base + o + (unsigned)(m * 16 * DM * 4 + bj * 512 + n * 64));
	s_waitcnt lgkmcnt(0)
	v_mfma_f32_16x16x32_bf16 v[62:65], v[122:125], v[146:149], v[62:65]
	v_mfma_f32_16x16x32_bf16 v[58:61], v[130:133], v[146:149], v[58:61]
	v_mfma_f32_16x16x32_bf16 v[46:49], v[122:125], v[154:157], v[46:49]
	v_mfma_f32_16x16x32_bf16 v[42:45], v[130:133], v[154:157], v[42:45]
	v_mfma_f32_16x16x32_bf16 v[30:33], v[122:125], v[162:165], v[30:33]
	v_mfma_f32_16x16x32_bf16 v[26:29], v[130:133], v[162:165], v[26:29]
	v_mfma_f32_16x16x32_bf16 v[14:17], v[122:125], v[170:173], v[14:17]
	v_mfma_f32_16x16x32_bf16 v[10:13], v[130:133], v[170:173], v[10:13]
	v_mfma_f32_16x16x32_bf16 v[62:65], v[126:129], v[150:153], v[62:65]
	v_mfma_f32_16x16x32_bf16 v[58:61], v[134:137], v[150:153], v[58:61]
	v_mfma_f32_16x16x32_bf16 v[46:49], v[126:129], v[158:161], v[46:49]
	v_mfma_f32_16x16x32_bf16 v[42:45], v[134:137], v[158:161], v[42:45]
	v_mfma_f32_16x16x32_bf16 v[30:33], v[126:129], v[166:169], v[30:33]
	v_mfma_f32_16x16x32_bf16 v[26:29], v[134:137], v[166:169], v[26:29]
	v_mfma_f32_16x16x32_bf16 v[14:17], v[126:129], v[174:177], v[14:17]
	v_mfma_f32_16x16x32_bf16 v[10:13], v[134:137], v[174:177], v[10:13]
	s_barrier
	s_setprio 0
	s_add_u32 s14, s20, 0xb0080
	s_addc_u32 s15, s21, 0
	s_add_i32 s20, s22, s25
	v_lshl_add_u64 v[122:123], s[14:15], 0, v[180:181]
	s_mov_b32 m0, s20
	s_nop 0
	global_load_lds_dwordx4 v[122:123], off
	v_lshl_add_u64 v[122:123], s[14:15], 0, v[178:179]
	s_add_i32 m0, s20, 0x2000
	s_nop 0
	global_load_lds_dwordx4 v[122:123], off
	s_waitcnt vmcnt(6)
	s_setprio 1
	s_barrier
	v_mfma_f32_16x16x32_bf16 v[54:57], v[194:197], v[146:149], v[54:57]
	v_mfma_f32_16x16x32_bf16 v[50:53], v[204:207], v[146:149], v[50:53]
	v_mfma_f32_16x16x32_bf16 v[38:41], v[194:197], v[154:157], v[38:41]
	v_mfma_f32_16x16x32_bf16 v[34:37], v[204:207], v[154:157], v[34:37]
	v_mfma_f32_16x16x32_bf16 v[22:25], v[194:197], v[162:165], v[22:25]
	v_mfma_f32_16x16x32_bf16 v[18:21], v[204:207], v[162:165], v[18:21]
	v_mfma_f32_16x16x32_bf16 v[6:9], v[194:197], v[170:173], v[6:9]
	v_mfma_f32_16x16x32_bf16 v[2:5], v[204:207], v[170:173], v[2:5]
	v_mfma_f32_16x16x32_bf16 v[54:57], v[200:203], v[150:153], v[54:57]
	v_mfma_f32_16x16x32_bf16 v[50:53], v[208:211], v[150:153], v[50:53]
	v_mfma_f32_16x16x32_bf16 v[38:41], v[200:203], v[158:161], v[38:41]
	v_mfma_f32_16x16x32_bf16 v[34:37], v[208:211], v[158:161], v[34:37]
	v_mfma_f32_16x16x32_bf16 v[22:25], v[200:203], v[166:169], v[22:25]
	v_mfma_f32_16x16x32_bf16 v[18:21], v[208:211], v[166:169], v[18:21]
	v_mfma_f32_16x16x32_bf16 v[6:9], v[200:203], v[174:177], v[6:9]
	v_mfma_f32_16x16x32_bf16 v[2:5], v[208:211], v[174:177], v[2:5]
	s_barrier
	s_setprio 0
	s_add_i32 s83, s83, 2
	s_add_u32 s81, s81, 0x100
	s_addc_u32 s82, s82, 0
	s_cmp_gt_u32 s83, 41
	s_mov_b64 s[14:15], s[18:19]
	s_cbranch_scc0 .LBB0_511
	s_lshl_b32 s14, s79, 8
	s_add_i32 s14, s14, s61
	v_or_b32_e32 v0, s14, v188
	s_lshl_b32 s15, s80, 8
	v_or_b32_e32 v122, s14, v190
	v_lshl_add_u32 v0, v0, 10, s15
	v_lshl_add_u32 v122, v122, 10, s15
	v_or_b32_e32 v0, v0, v192
	v_or_b32_e32 v122, v122, v192
	v_lshlrev_b32_e32 v0, 2, v0
	v_lshl_or_b32 v186, v122, 2, v191
	s_mov_b32 s80, s77
	s_mov_b32 s79, s78
	s_mov_b64 s[18:19], s[10:11]
	s_mov_b64 s[14:15], s[8:9]
	v_add_u32_e32 v187, 0x8000, v186
	s_add_u32 s98, s12, 0x0
	s_addc_u32 s99, s13, 0
	global_load_dwordx4 v[194:197], v0, s[98:99]
	global_load_dwordx4 v[200:203], v0, s[98:99] offset:64
	global_load_dwordx4 v[204:207], v0, s[98:99] offset:512
	global_load_dwordx4 v[208:211], v0, s[98:99] offset:576
	s_add_u32 s98, s12, 0x10000
	s_addc_u32 s99, s13, 0
	global_load_dwordx4 v[174:177], v0, s[98:99]
	global_load_dwordx4 v[170:173], v0, s[98:99] offset:64
	global_load_dwordx4 v[166:169], v0, s[98:99] offset:512
	global_load_dwordx4 v[162:165], v0, s[98:99] offset:576
	s_add_u32 s98, s12, 0x20000
	s_addc_u32 s99, s13, 0
	global_load_dwordx4 v[158:161], v0, s[98:99]
	global_load_dwordx4 v[154:157], v0, s[98:99] offset:64
	global_load_dwordx4 v[150:153], v0, s[98:99] offset:512
	global_load_dwordx4 v[146:149], v0, s[98:99] offset:576
	s_add_u32 s98, s12, 0x30000
	s_addc_u32 s99, s13, 0
	global_load_dwordx4 v[134:137], v0, s[98:99]
	global_load_dwordx4 v[130:133], v0, s[98:99] offset:64
	global_load_dwordx4 v[126:129], v0, s[98:99] offset:512
	global_load_dwordx4 v[122:125], v0, s[98:99] offset:576
	s_waitcnt vmcnt(12)
; template <int CTRL> DEVI float dpp(float x) { return __builtin_bit_cast(float, __builtin_amdgcn_mov_dpp(__builtin_bit_cast(int, x), CTRL, 0xf, 0xf, true)); }
;     DEVI void operator()(AccRef acc, const pg8::Unit& u, int wr, int wc, int fr, int fq) const {
;     ...
;                     for (int n = 0; n < 2; ++n) b[m][bj][n] = *(const f32x4*)((const char*)base + o + (unsigned)(m * 16 * DM * 4 + bj * 512 + n * 64));
; #pragma unroll
;             for (int m = 0; m < 4; ++m)
; #pragma unroll
;                 for (int bj = 0; bj < 2; ++bj) { const f32x4 d0 = b[m][bj][0] + alpha * acc[ai][bj][m][0], d1 = b[m][bj][1] + alpha * acc[ai][bj][m][1];
;                     f32x4 t0, t1;
; #pragma unroll
;                     for (int i = 0; i < 4; ++i) { t0[i] = dpp<0x128>(d0[i]); t1[i] = dpp<0x128>(d1[i]); }
;                     const f32x4 sa = lo ? d0 : t1, sb = lo ? t0 : d1;
;                     const unsigned oo = os + (unsigned)(m * 16 * DM * 4 + bj * 512);
;                     *(f32x4*)((char*)out + oo) = sa; *(f32x4*)((char*)out + oo + 8u * DM * 4u) = sb; }
;             o += 128u * DM * 4u; os += 128u * DM * 4u; }
	v_pk_fma_f32 v[142:143], v[142:143], 0.5, v[194:195] op_sel_hi:[1,0,1]
	v_pk_fma_f32 v[144:145], v[144:145], 0.5, v[196:197] op_sel_hi:[1,0,1]
	v_pk_fma_f32 v[138:139], v[138:139], 0.5, v[200:201] op_sel_hi:[1,0,1]
	v_pk_fma_f32 v[140:141], v[140:141], 0.5, v[202:203] op_sel_hi:[1,0,1]
	v_pk_fma_f32 v[118:119], v[118:119], 0.5, v[204:205] op_sel_hi:[1,0,1]
	v_pk_fma_f32 v[120:121], v[120:121], 0.5, v[206:207] op_sel_hi:[1,0,1]
	v_pk_fma_f32 v[114:115], v[114:115], 0.5, v[208:209] op_sel_hi:[1,0,1]
	v_pk_fma_f32 v[116:117], v[116:117], 0.5, v[210:211] op_sel_hi:[1,0,1]
	s_mov_b64 vcc, s[4:5]
	v_cndmask_b32_dpp v194, v138, v142, vcc row_ror:8 row_mask:0xf bank_mask:0xf bound_ctrl:1
	v_cndmask_b32_dpp v195, v139, v143, vcc row_ror:8 row_mask:0xf bank_mask:0xf bound_ctrl:1
	v_cndmask_b32_dpp v196, v140, v144, vcc row_ror:8 row_mask:0xf bank_mask:0xf bound_ctrl:1
	v_cndmask_b32_dpp v197, v141, v145, vcc row_ror:8 row_mask:0xf bank_mask:0xf bound_ctrl:1
	v_cndmask_b32_dpp v204, v114, v118, vcc row_ror:8 row_mask:0xf bank_mask:0xf bound_ctrl:1
	v_cndmask_b32_dpp v205, v115, v119, vcc row_ror:8 row_mask:0xf bank_mask:0xf bound_ctrl:1
	v_cndmask_b32_dpp v206, v116, v120, vcc row_ror:8 row_mask:0xf bank_mask:0xf bound_ctrl:1
	v_cndmask_b32_dpp v207, v117, v121, vcc row_ror:8 row_mask:0xf bank_mask:0xf bound_ctrl:1
	s_not_b64 vcc, s[4:5]
	v_cndmask_b32_dpp v200, v142, v138, vcc row_ror:8 row_mask:0xf bank_mask:0xf bound_ctrl:1
	v_cndmask_b32_dpp v201, v143, v139, vcc row_ror:8 row_mask:0xf bank_mask:0xf bound_ctrl:1
	v_cndmask_b32_dpp v202, v144, v140, vcc row_ror:8 row_mask:0xf bank_mask:0xf bound_ctrl:1
	v_cndmask_b32_dpp v203, v145, v141, vcc row_ror:8 row_mask:0xf bank_mask:0xf bound_ctrl:1
	v_cndmask_b32_dpp v208, v118, v114, vcc row_ror:8 row_mask:0xf bank_mask:0xf bound_ctrl:1
	v_cndmask_b32_dpp v209, v119, v115, vcc row_ror:8 row_mask:0xf bank_mask:0xf bound_ctrl:1
	v_cndmask_b32_dpp v210, v120, v116, vcc row_ror:8 row_mask:0xf bank_mask:0xf bound_ctrl:1
	v_cndmask_b32_dpp v211, v121, v117, vcc row_ror:8 row_mask:0xf bank_mask:0xf bound_ctrl:1
	s_add_u32 s100, s28, 0x0
	s_addc_u32 s101, s29, 0
	global_store_dwordx4 v186, v[194:197], s[100:101]
	global_store_dwordx4 v187, v[200:203], s[100:101]
	global_store_dwordx4 v186, v[204:207], s[100:101] offset:512
	global_store_dwordx4 v187, v[208:211], s[100:101] offset:512
	s_add_u32 s98, s12, 0x80000
	s_addc_u32 s99, s13, 0
	global_load_dwordx4 v[142:145], v0, s[98:99]
	global_load_dwordx4 v[138:141], v0, s[98:99] offset:64
	global_load_dwordx4 v[118:121], v0, s[98:99] offset:512
	global_load_dwordx4 v[114:117], v0, s[98:99] offset:576
	s_waitcnt vmcnt(16)
	v_pk_fma_f32 v[110:111], v[110:111], 0.5, v[174:175] op_sel_hi:[1,0,1]
	v_pk_fma_f32 v[112:113], v[112:113], 0.5, v[176:177] op_sel_hi:[1,0,1]
	v_pk_fma_f32 v[106:107], v[106:107], 0.5, v[170:171] op_sel_hi:[1,0,1]
	v_pk_fma_f32 v[108:109], v[108:109], 0.5, v[172:173] op_sel_hi:[1,0,1]
	v_pk_fma_f32 v[102:103], v[102:103], 0.5, v[166:167] op_sel_hi:[1,0,1]
	v_pk_fma_f32 v[104:105], v[104:105], 0.5, v[168:169] op_sel_hi:[1,0,1]
	v_pk_fma_f32 v[98:99], v[98:99], 0.5, v[162:163] op_sel_hi:[1,0,1]
	v_pk_fma_f32 v[100:101], v[100:101], 0.5, v[164:165] op_sel_hi:[1,0,1]
	s_mov_b64 vcc, s[4:5]
	v_cndmask_b32_dpp v174, v106, v110, vcc row_ror:8 row_mask:0xf bank_mask:0xf bound_ctrl:1
	v_cndmask_b32_dpp v175, v107, v111, vcc row_ror:8 row_mask:0xf bank_mask:0xf bound_ctrl:1
	v_cndmask_b32_dpp v176, v108, v112, vcc row_ror:8 row_mask:0xf bank_mask:0xf bound_ctrl:1
	v_cndmask_b32_dpp v177, v109, v113, vcc row_ror:8 row_mask:0xf bank_mask:0xf bound_ctrl:1
	v_cndmask_b32_dpp v166, v98, v102, vcc row_ror:8 row_mask:0xf bank_mask:0xf bound_ctrl:1
	v_cndmask_b32_dpp v167, v99, v103, vcc row_ror:8 row_mask:0xf bank_mask:0xf bound_ctrl:1
	v_cndmask_b32_dpp v168, v100, v104, vcc row_ror:8 row_mask:0xf bank_mask:0xf bound_ctrl:1
	v_cndmask_b32_dpp v169, v101, v105, vcc row_ror:8 row_mask:0xf bank_mask:0xf bound_ctrl:1
	s_not_b64 vcc, s[4:5]
	v_cndmask_b32_dpp v170, v110, v106, vcc row_ror:8 row_mask:0xf bank_mask:0xf bound_ctrl:1
	v_cndmask_b32_dpp v171, v111, v107, vcc row_ror:8 row_mask:0xf bank_mask:0xf bound_ctrl:1
	v_cndmask_b32_dpp v172, v112, v108, vcc row_ror:8 row_mask:0xf bank_mask:0xf bound_ctrl:1
	v_cndmask_b32_dpp v173, v113, v109, vcc row_ror:8 row_mask:0xf bank_mask:0xf bound_ctrl:1
	v_cndmask_b32_dpp v162, v102, v98, vcc row_ror:8 row_mask:0xf bank_mask:0xf bound_ctrl:1
	v_cndmask_b32_dpp v163, v103, v99, vcc row_ror:8 row_mask:0xf bank_mask:0xf bound_ctrl:1
	v_cndmask_b32_dpp v164, v104, v100, vcc row_ror:8 row_mask:0xf bank_mask:0xf bound_ctrl:1
	v_cndmask_b32_dpp v165, v105, v101, vcc row_ror:8 row_mask:0xf bank_mask:0xf bound_ctrl:1
	s_add_u32 s100, s28, 0x10000
	s_addc_u32 s101, s29, 0
	global_store_dwordx4 v186, v[174:177], s[100:101]
	global_store_dwordx4 v187, v[170:173], s[100:101]
	global_store_dwordx4 v186, v[166:169], s[100:101] offset:512
	global_store_dwordx4 v187, v[162:165], s[100:101] offset:512
	s_add_u32 s98, s12, 0x90000
	s_addc_u32 s99, s13, 0
	global_load_dwordx4 v[110:113], v0, s[98:99]
	global_load_dwordx4 v[106:109], v0, s[98:99] offset:64
	global_load_dwordx4 v[102:105], v0, s[98:99] offset:512
	global_load_dwordx4 v[98:101], v0, s[98:99] offset:576
	s_waitcnt vmcnt(20)
; template <int CTRL> DEVI float dpp(float x) { return __builtin_bit_cast(float, __builtin_amdgcn_mov_dpp(__builtin_bit_cast(int, x), CTRL, 0xf, 0xf, true)); }
;     DEVI void operator()(AccRef acc, const pg8::Unit& u, int wr, int wc, int fr, int fq) const {
;         unsigned o = (unsigned)((u.pm * 256 + wr * 64 + fr) * DM + u.pn * 256 + wc * 32 + 4 * fq) * 4u;
;         const bool lo = fr < 8;
;         unsigned os = (unsigned)((u.pm * 256 + wr * 64 + (fr & 7)) * DM + u.pn * 256 + wc * 32 + 4 * fq) * 4u + (lo ? 0u : 64u);
; #pragma unroll
;         for (int ai = 0; ai < 2; ++ai) {
;             asm volatile("" : "+v"(o), "+v"(os));
;             f32x4 b[4][2][2];
; #pragma unroll
;             for (int m = 0; m < 4; ++m)
; #pragma unroll
;                 for (int bj = 0; bj < 2; ++bj)
; #pragma unroll
;                     for (int n = 0; n < 2; ++n) b[m][bj][n] = *(const f32x4*)((const char*)base + o + (unsigned)(m * 16 * DM * 4 + bj * 512 + n * 64));
; #pragma unroll
;             for (int m = 0; m < 4; ++m)
; #pragma unroll
;                 for (int bj = 0; bj < 2; ++bj) { const f32x4 d0 = b[m][bj][0] + alpha * acc[ai][bj][m][0], d1 = b[m][bj][1] + alpha * acc[ai][bj][m][1];
;                     f32x4 t0, t1;
; #pragma unroll
;                     for (int i = 0; i < 4; ++i) { t0[i] = dpp<0x128>(d0[i]); t1[i] = dpp<0x128>(d1[i]); }
;                     const f32x4 sa = lo ? d0 : t1, sb = lo ? t0 : d1;
;                     const unsigned oo = os + (unsigned)(m * 16 * DM * 4 + bj * 512);
;                     *(f32x4*)((char*)out + oo) = sa; *(f32x4*)((char*)out + oo + 8u * DM * 4u) = sb; }
;             o += 128u * DM * 4u; os += 128u * DM * 4u; }
;     }
	v_pk_fma_f32 v[94:95], v[94:95], 0.5, v[158:159] op_sel_hi:[1,0,1]
	v_pk_fma_f32 v[96:97], v[96:97], 0.5, v[160:161] op_sel_hi:[1,0,1]
	v_pk_fma_f32 v[90:91], v[90:91], 0.5, v[154:155] op_sel_hi:[1,0,1]
	v_pk_fma_f32 v[92:93], v[92:93], 0.5, v[156:157] op_sel_hi:[1,0,1]
	v_pk_fma_f32 v[86:87], v[86:87], 0.5, v[150:151] op_sel_hi:[1,0,1]
	v_pk_fma_f32 v[88:89], v[88:89], 0.5, v[152:153] op_sel_hi:[1,0,1]
	v_pk_fma_f32 v[82:83], v[82:83], 0.5, v[146:147] op_sel_hi:[1,0,1]
	v_pk_fma_f32 v[84:85], v[84:85], 0.5, v[148:149] op_sel_hi:[1,0,1]
	s_mov_b64 vcc, s[4:5]
	v_cndmask_b32_dpp v158, v90, v94, vcc row_ror:8 row_mask:0xf bank_mask:0xf bound_ctrl:1
	v_cndmask_b32_dpp v159, v91, v95, vcc row_ror:8 row_mask:0xf bank_mask:0xf bound_ctrl:1
	v_cndmask_b32_dpp v160, v92, v96, vcc row_ror:8 row_mask:0xf bank_mask:0xf bound_ctrl:1
	v_cndmask_b32_dpp v161, v93, v97, vcc row_ror:8 row_mask:0xf bank_mask:0xf bound_ctrl:1
	v_cndmask_b32_dpp v150, v82, v86, vcc row_ror:8 row_mask:0xf bank_mask:0xf bound_ctrl:1
	v_cndmask_b32_dpp v151, v83, v87, vcc row_ror:8 row_mask:0xf bank_mask:0xf bound_ctrl:1
	v_cndmask_b32_dpp v152, v84, v88, vcc row_ror:8 row_mask:0xf bank_mask:0xf bound_ctrl:1
	v_cndmask_b32_dpp v153, v85, v89, vcc row_ror:8 row_mask:0xf bank_mask:0xf bound_ctrl:1
	s_not_b64 vcc, s[4:5]
	v_cndmask_b32_dpp v154, v94, v90, vcc row_ror:8 row_mask:0xf bank_mask:0xf bound_ctrl:1
	v_cndmask_b32_dpp v155, v95, v91, vcc row_ror:8 row_mask:0xf bank_mask:0xf bound_ctrl:1
	v_cndmask_b32_dpp v156, v96, v92, vcc row_ror:8 row_mask:0xf bank_mask:0xf bound_ctrl:1
	v_cndmask_b32_dpp v157, v97, v93, vcc row_ror:8 row_mask:0xf bank_mask:0xf bound_ctrl:1
	v_cndmask_b32_dpp v146, v86, v82, vcc row_ror:8 row_mask:0xf bank_mask:0xf bound_ctrl:1
	v_cndmask_b32_dpp v147, v87, v83, vcc row_ror:8 row_mask:0xf bank_mask:0xf bound_ctrl:1
	v_cndmask_b32_dpp v148, v88, v84, vcc row_ror:8 row_mask:0xf bank_mask:0xf bound_ctrl:1
	v_cndmask_b32_dpp v149, v89, v85, vcc row_ror:8 row_mask:0xf bank_mask:0xf bound_ctrl:1
	s_add_u32 s100, s28, 0x20000
	s_addc_u32 s101, s29, 0
	global_store_dwordx4 v186, v[158:161], s[100:101]
	global_store_dwordx4 v187, v[154:157], s[100:101]
	global_store_dwordx4 v186, v[150:153], s[100:101] offset:512
	global_store_dwordx4 v187, v[146:149], s[100:101] offset:512
	s_add_u32 s98, s12, 0xa0000
	s_addc_u32 s99, s13, 0
	global_load_dwordx4 v[94:97], v0, s[98:99]
	global_load_dwordx4 v[90:93], v0, s[98:99] offset:64
	global_load_dwordx4 v[86:89], v0, s[98:99] offset:512
	global_load_dwordx4 v[82:85], v0, s[98:99] offset:576
	s_waitcnt vmcnt(24)
	v_pk_fma_f32 v[78:79], v[78:79], 0.5, v[134:135] op_sel_hi:[1,0,1]
	v_pk_fma_f32 v[80:81], v[80:81], 0.5, v[136:137] op_sel_hi:[1,0,1]
	v_pk_fma_f32 v[74:75], v[74:75], 0.5, v[130:131] op_sel_hi:[1,0,1]
	v_pk_fma_f32 v[76:77], v[76:77], 0.5, v[132:133] op_sel_hi:[1,0,1]
	v_pk_fma_f32 v[70:71], v[70:71], 0.5, v[126:127] op_sel_hi:[1,0,1]
	v_pk_fma_f32 v[72:73], v[72:73], 0.5, v[128:129] op_sel_hi:[1,0,1]
	v_pk_fma_f32 v[66:67], v[66:67], 0.5, v[122:123] op_sel_hi:[1,0,1]
	v_pk_fma_f32 v[68:69], v[68:69], 0.5, v[124:125] op_sel_hi:[1,0,1]
	s_mov_b64 vcc, s[4:5]
	v_cndmask_b32_dpp v134, v74, v78, vcc row_ror:8 row_mask:0xf bank_mask:0xf bound_ctrl:1
	v_cndmask_b32_dpp v135, v75, v79, vcc row_ror:8 row_mask:0xf bank_mask:0xf bound_ctrl:1
	v_cndmask_b32_dpp v136, v76, v80, vcc row_ror:8 row_mask:0xf bank_mask:0xf bound_ctrl:1
	v_cndmask_b32_dpp v137, v77, v81, vcc row_ror:8 row_mask:0xf bank_mask:0xf bound_ctrl:1
	v_cndmask_b32_dpp v126, v66, v70, vcc row_ror:8 row_mask:0xf bank_mask:0xf bound_ctrl:1
	v_cndmask_b32_dpp v127, v67, v71, vcc row_ror:8 row_mask:0xf bank_mask:0xf bound_ctrl:1
	v_cndmask_b32_dpp v128, v68, v72, vcc row_ror:8 row_mask:0xf bank_mask:0xf bound_ctrl:1
	v_cndmask_b32_dpp v129, v69, v73, vcc row_ror:8 row_mask:0xf bank_mask:0xf bound_ctrl:1
	s_not_b64 vcc, s[4:5]
	v_cndmask_b32_dpp v130, v78, v74, vcc row_ror:8 row_mask:0xf bank_mask:0xf bound_ctrl:1
	v_cndmask_b32_dpp v131, v79, v75, vcc row_ror:8 row_mask:0xf bank_mask:0xf bound_ctrl:1
	v_cndmask_b32_dpp v132, v80, v76, vcc row_ror:8 row_mask:0xf bank_mask:0xf bound_ctrl:1
	v_cndmask_b32_dpp v133, v81, v77, vcc row_ror:8 row_mask:0xf bank_mask:0xf bound_ctrl:1
	v_cndmask_b32_dpp v122, v70, v66, vcc row_ror:8 row_mask:0xf bank_mask:0xf bound_ctrl:1
	v_cndmask_b32_dpp v123, v71, v67, vcc row_ror:8 row_mask:0xf bank_mask:0xf bound_ctrl:1
	v_cndmask_b32_dpp v124, v72, v68, vcc row_ror:8 row_mask:0xf bank_mask:0xf bound_ctrl:1
	v_cndmask_b32_dpp v125, v73, v69, vcc row_ror:8 row_mask:0xf bank_mask:0xf bound_ctrl:1
	s_add_u32 s100, s28, 0x30000
	s_addc_u32 s101, s29, 0
	global_store_dwordx4 v186, v[134:137], s[100:101]
	global_store_dwordx4 v187, v[130:133], s[100:101]
	global_store_dwordx4 v186, v[126:129], s[100:101] offset:512
	global_store_dwordx4 v187, v[122:125], s[100:101] offset:512
	s_add_u32 s98, s12, 0xb0000
	s_addc_u32 s99, s13, 0
	global_load_dwordx4 v[78:81], v0, s[98:99]
	global_load_dwordx4 v[74:77], v0, s[98:99] offset:64
	global_load_dwordx4 v[70:73], v0, s[98:99] offset:512
	global_load_dwordx4 v[66:69], v0, s[98:99] offset:576
	s_waitcnt vmcnt(24)
; template <int CTRL> DEVI float dpp(float x) { return __builtin_bit_cast(float, __builtin_amdgcn_mov_dpp(__builtin_bit_cast(int, x), CTRL, 0xf, 0xf, true)); }
;     DEVI void operator()(AccRef acc, const pg8::Unit& u, int wr, int wc, int fr, int fq) const {
;         unsigned o = (unsigned)((u.pm * 256 + wr * 64 + fr) * DM + u.pn * 256 + wc * 32 + 4 * fq) * 4u;
;         const bool lo = fr < 8;
;         unsigned os = (unsigned)((u.pm * 256 + wr * 64 + (fr & 7)) * DM + u.pn * 256 + wc * 32 + 4 * fq) * 4u + (lo ? 0u : 64u);
; #pragma unroll
;         for (int ai = 0; ai < 2; ++ai) {
;             asm volatile("" : "+v"(o), "+v"(os));
;             f32x4 b[4][2][2];
; #pragma unroll
;             for (int m = 0; m < 4; ++m)
; #pragma unroll
;                 for (int bj = 0; bj < 2; ++bj)
; #pragma unroll
;                     for (int n = 0; n < 2; ++n) b[m][bj][n] = *(const f32x4*)((const char*)base + o + (unsigned)(m * 16 * DM * 4 + bj * 512 + n * 64));
; #pragma unroll
;             for (int m = 0; m < 4; ++m)
; #pragma unroll
;                 for (int bj = 0; bj < 2; ++bj) { const f32x4 d0 = b[m][bj][0] + alpha * acc[ai][bj][m][0], d1 = b[m][bj][1] + alpha * acc[ai][bj][m][1];
;                     f32x4 t0, t1;
; #pragma unroll
;                     for (int i = 0; i < 4; ++i) { t0[i] = dpp<0x128>(d0[i]); t1[i] = dpp<0x128>(d1[i]); }
;                     const f32x4 sa = lo ? d0 : t1, sb = lo ? t0 : d1;
;                     const unsigned oo = os + (unsigned)(m * 16 * DM * 4 + bj * 512);
;                     *(f32x4*)((char*)out + oo) = sa; *(f32x4*)((char*)out + oo + 8u * DM * 4u) = sb; }
;             o += 128u * DM * 4u; os += 128u * DM * 4u; }
;     }
	v_pk_fma_f32 v[62:63], v[62:63], 0.5, v[142:143] op_sel_hi:[1,0,1]
	v_pk_fma_f32 v[64:65], v[64:65], 0.5, v[144:145] op_sel_hi:[1,0,1]
	v_pk_fma_f32 v[58:59], v[58:59], 0.5, v[138:139] op_sel_hi:[1,0,1]
	v_pk_fma_f32 v[60:61], v[60:61], 0.5, v[140:141] op_sel_hi:[1,0,1]
	v_pk_fma_f32 v[54:55], v[54:55], 0.5, v[118:119] op_sel_hi:[1,0,1]
	v_pk_fma_f32 v[56:57], v[56:57], 0.5, v[120:121] op_sel_hi:[1,0,1]
	v_pk_fma_f32 v[50:51], v[50:51], 0.5, v[114:115] op_sel_hi:[1,0,1]
	v_pk_fma_f32 v[52:53], v[52:53], 0.5, v[116:117] op_sel_hi:[1,0,1]
	s_mov_b64 vcc, s[4:5]
	v_cndmask_b32_dpp v142, v58, v62, vcc row_ror:8 row_mask:0xf bank_mask:0xf bound_ctrl:1
	v_cndmask_b32_dpp v143, v59, v63, vcc row_ror:8 row_mask:0xf bank_mask:0xf bound_ctrl:1
	v_cndmask_b32_dpp v144, v60, v64, vcc row_ror:8 row_mask:0xf bank_mask:0xf bound_ctrl:1
	v_cndmask_b32_dpp v145, v61, v65, vcc row_ror:8 row_mask:0xf bank_mask:0xf bound_ctrl:1
	v_cndmask_b32_dpp v118, v50, v54, vcc row_ror:8 row_mask:0xf bank_mask:0xf bound_ctrl:1
	v_cndmask_b32_dpp v119, v51, v55, vcc row_ror:8 row_mask:0xf bank_mask:0xf bound_ctrl:1
	v_cndmask_b32_dpp v120, v52, v56, vcc row_ror:8 row_mask:0xf bank_mask:0xf bound_ctrl:1
	v_cndmask_b32_dpp v121, v53, v57, vcc row_ror:8 row_mask:0xf bank_mask:0xf bound_ctrl:1
	s_not_b64 vcc, s[4:5]
	v_cndmask_b32_dpp v138, v62, v58, vcc row_ror:8 row_mask:0xf bank_mask:0xf bound_ctrl:1
	v_cndmask_b32_dpp v139, v63, v59, vcc row_ror:8 row_mask:0xf bank_mask:0xf bound_ctrl:1
	v_cndmask_b32_dpp v140, v64, v60, vcc row_ror:8 row_mask:0xf bank_mask:0xf bound_ctrl:1
	v_cndmask_b32_dpp v141, v65, v61, vcc row_ror:8 row_mask:0xf bank_mask:0xf bound_ctrl:1
	v_cndmask_b32_dpp v114, v54, v50, vcc row_ror:8 row_mask:0xf bank_mask:0xf bound_ctrl:1
	v_cndmask_b32_dpp v115, v55, v51, vcc row_ror:8 row_mask:0xf bank_mask:0xf bound_ctrl:1
	v_cndmask_b32_dpp v116, v56, v52, vcc row_ror:8 row_mask:0xf bank_mask:0xf bound_ctrl:1
	v_cndmask_b32_dpp v117, v57, v53, vcc row_ror:8 row_mask:0xf bank_mask:0xf bound_ctrl:1
	s_add_u32 s100, s28, 0x80000
	s_addc_u32 s101, s29, 0
	global_store_dwordx4 v186, v[142:145], s[100:101]
	global_store_dwordx4 v187, v[138:141], s[100:101]
	global_store_dwordx4 v186, v[118:121], s[100:101] offset:512
	global_store_dwordx4 v187, v[114:117], s[100:101] offset:512
	s_waitcnt vmcnt(20)
	v_pk_fma_f32 v[46:47], v[46:47], 0.5, v[110:111] op_sel_hi:[1,0,1]
	v_pk_fma_f32 v[48:49], v[48:49], 0.5, v[112:113] op_sel_hi:[1,0,1]
	v_pk_fma_f32 v[42:43], v[42:43], 0.5, v[106:107] op_sel_hi:[1,0,1]
	v_pk_fma_f32 v[44:45], v[44:45], 0.5, v[108:109] op_sel_hi:[1,0,1]
	v_pk_fma_f32 v[38:39], v[38:39], 0.5, v[102:103] op_sel_hi:[1,0,1]
	v_pk_fma_f32 v[40:41], v[40:41], 0.5, v[104:105] op_sel_hi:[1,0,1]
	v_pk_fma_f32 v[34:35], v[34:35], 0.5, v[98:99] op_sel_hi:[1,0,1]
	v_pk_fma_f32 v[36:37], v[36:37], 0.5, v[100:101] op_sel_hi:[1,0,1]
	s_mov_b64 vcc, s[4:5]
	v_cndmask_b32_dpp v110, v42, v46, vcc row_ror:8 row_mask:0xf bank_mask:0xf bound_ctrl:1
	v_cndmask_b32_dpp v111, v43, v47, vcc row_ror:8 row_mask:0xf bank_mask:0xf bound_ctrl:1
	v_cndmask_b32_dpp v112, v44, v48, vcc row_ror:8 row_mask:0xf bank_mask:0xf bound_ctrl:1
	v_cndmask_b32_dpp v113, v45, v49, vcc row_ror:8 row_mask:0xf bank_mask:0xf bound_ctrl:1
	v_cndmask_b32_dpp v102, v34, v38, vcc row_ror:8 row_mask:0xf bank_mask:0xf bound_ctrl:1
	v_cndmask_b32_dpp v103, v35, v39, vcc row_ror:8 row_mask:0xf bank_mask:0xf bound_ctrl:1
	v_cndmask_b32_dpp v104, v36, v40, vcc row_ror:8 row_mask:0xf bank_mask:0xf bound_ctrl:1
	v_cndmask_b32_dpp v105, v37, v41, vcc row_ror:8 row_mask:0xf bank_mask:0xf bound_ctrl:1
	s_not_b64 vcc, s[4:5]
	v_cndmask_b32_dpp v106, v46, v42, vcc row_ror:8 row_mask:0xf bank_mask:0xf bound_ctrl:1
	v_cndmask_b32_dpp v107, v47, v43, vcc row_ror:8 row_mask:0xf bank_mask:0xf bound_ctrl:1
	v_cndmask_b32_dpp v108, v48, v44, vcc row_ror:8 row_mask:0xf bank_mask:0xf bound_ctrl:1
	v_cndmask_b32_dpp v109, v49, v45, vcc row_ror:8 row_mask:0xf bank_mask:0xf bound_ctrl:1
	v_cndmask_b32_dpp v98, v38, v34, vcc row_ror:8 row_mask:0xf bank_mask:0xf bound_ctrl:1
	v_cndmask_b32_dpp v99, v39, v35, vcc row_ror:8 row_mask:0xf bank_mask:0xf bound_ctrl:1
	v_cndmask_b32_dpp v100, v40, v36, vcc row_ror:8 row_mask:0xf bank_mask:0xf bound_ctrl:1
	v_cndmask_b32_dpp v101, v41, v37, vcc row_ror:8 row_mask:0xf bank_mask:0xf bound_ctrl:1
	s_add_u32 s100, s28, 0x90000
	s_addc_u32 s101, s29, 0
	global_store_dwordx4 v186, v[110:113], s[100:101]
	global_store_dwordx4 v187, v[106:109], s[100:101]
	global_store_dwordx4 v186, v[102:105], s[100:101] offset:512
	global_store_dwordx4 v187, v[98:101], s[100:101] offset:512
	s_waitcnt vmcnt(16)
; template <int CTRL> DEVI float dpp(float x) { return __builtin_bit_cast(float, __builtin_amdgcn_mov_dpp(__builtin_bit_cast(int, x), CTRL, 0xf, 0xf, true)); }
; #define PG8_WAIT_V(n) asm volatile("s_waitcnt vmcnt(" #n ")" ::: "memory")
; #define PG8_BAR __builtin_amdgcn_s_barrier()
; template <class Epi, class Sched>
; __device__ __forceinline__ void gemm_phase(PG8_LAS unsigned char* lds, const Gemm g, const Sched& S, const Epi& E, int wv) {
;     ...
;         if (!has_next) break;
; #pragma unroll
;         for (int a = 0; a < 2; ++a)
; #pragma unroll
;             for (int b = 0; b < 2; ++b)
; #pragma unroll
;                 for (int m = 0; m < 4; ++m)
; #pragma unroll
;                     for (int n = 0; n < 2; ++n) acc[a][b][m][n] = (f32x4){0.f, 0.f, 0.f, 0.f};
;         cur = nxt; cA = nA; cB = nB; ++ui;
;     }
;     PG8_WAIT_V(0);
;     if (wr == 0) PG8_BAR;
;     PG8_BAR;
;     DEVI void operator()(AccRef acc, const pg8::Unit& u, int wr, int wc, int fr, int fq) const {
;     ...
; #pragma unroll
;             for (int m = 0; m < 4; ++m)
; #pragma unroll
;                 for (int bj = 0; bj < 2; ++bj) { const f32x4 d0 = b[m][bj][0] + alpha * acc[ai][bj][m][0], d1 = b[m][bj][1] + alpha * acc[ai][bj][m][1];
;                     f32x4 t0, t1;
; #pragma unroll
;                     for (int i = 0; i < 4; ++i) { t0[i] = dpp<0x128>(d0[i]); t1[i] = dpp<0x128>(d1[i]); }
;                     const f32x4 sa = lo ? d0 : t1, sb = lo ? t0 : d1;
;                     const unsigned oo = os + (unsigned)(m * 16 * DM * 4 + bj * 512);
;                     *(f32x4*)((char*)out + oo) = sa; *(f32x4*)((char*)out + oo + 8u * DM * 4u) = sb; }
;             o += 128u * DM * 4u; os += 128u * DM * 4u; }
;     }
	v_pk_fma_f32 v[30:31], v[30:31], 0.5, v[94:95] op_sel_hi:[1,0,1]
	v_pk_fma_f32 v[32:33], v[32:33], 0.5, v[96:97] op_sel_hi:[1,0,1]
	v_pk_fma_f32 v[26:27], v[26:27], 0.5, v[90:91] op_sel_hi:[1,0,1]
	v_pk_fma_f32 v[28:29], v[28:29], 0.5, v[92:93] op_sel_hi:[1,0,1]
	v_pk_fma_f32 v[22:23], v[22:23], 0.5, v[86:87] op_sel_hi:[1,0,1]
	v_pk_fma_f32 v[24:25], v[24:25], 0.5, v[88:89] op_sel_hi:[1,0,1]
	v_pk_fma_f32 v[18:19], v[18:19], 0.5, v[82:83] op_sel_hi:[1,0,1]
	v_pk_fma_f32 v[20:21], v[20:21], 0.5, v[84:85] op_sel_hi:[1,0,1]
	s_mov_b64 vcc, s[4:5]
	v_cndmask_b32_dpp v94, v26, v30, vcc row_ror:8 row_mask:0xf bank_mask:0xf bound_ctrl:1
	v_cndmask_b32_dpp v95, v27, v31, vcc row_ror:8 row_mask:0xf bank_mask:0xf bound_ctrl:1
	v_cndmask_b32_dpp v96, v28, v32, vcc row_ror:8 row_mask:0xf bank_mask:0xf bound_ctrl:1
	v_cndmask_b32_dpp v97, v29, v33, vcc row_ror:8 row_mask:0xf bank_mask:0xf bound_ctrl:1
	v_cndmask_b32_dpp v86, v18, v22, vcc row_ror:8 row_mask:0xf bank_mask:0xf bound_ctrl:1
	v_cndmask_b32_dpp v87, v19, v23, vcc row_ror:8 row_mask:0xf bank_mask:0xf bound_ctrl:1
	v_cndmask_b32_dpp v88, v20, v24, vcc row_ror:8 row_mask:0xf bank_mask:0xf bound_ctrl:1
	v_cndmask_b32_dpp v89, v21, v25, vcc row_ror:8 row_mask:0xf bank_mask:0xf bound_ctrl:1
	s_not_b64 vcc, s[4:5]
	v_cndmask_b32_dpp v90, v30, v26, vcc row_ror:8 row_mask:0xf bank_mask:0xf bound_ctrl:1
	v_cndmask_b32_dpp v91, v31, v27, vcc row_ror:8 row_mask:0xf bank_mask:0xf bound_ctrl:1
	v_cndmask_b32_dpp v92, v32, v28, vcc row_ror:8 row_mask:0xf bank_mask:0xf bound_ctrl:1
	v_cndmask_b32_dpp v93, v33, v29, vcc row_ror:8 row_mask:0xf bank_mask:0xf bound_ctrl:1
	v_cndmask_b32_dpp v82, v22, v18, vcc row_ror:8 row_mask:0xf bank_mask:0xf bound_ctrl:1
	v_cndmask_b32_dpp v83, v23, v19, vcc row_ror:8 row_mask:0xf bank_mask:0xf bound_ctrl:1
	v_cndmask_b32_dpp v84, v24, v20, vcc row_ror:8 row_mask:0xf bank_mask:0xf bound_ctrl:1
	v_cndmask_b32_dpp v85, v25, v21, vcc row_ror:8 row_mask:0xf bank_mask:0xf bound_ctrl:1
	s_add_u32 s100, s28, 0xa0000
	s_addc_u32 s101, s29, 0
	global_store_dwordx4 v186, v[94:97], s[100:101]
	global_store_dwordx4 v187, v[90:93], s[100:101]
	global_store_dwordx4 v186, v[86:89], s[100:101] offset:512
	global_store_dwordx4 v187, v[82:85], s[100:101] offset:512
	s_waitcnt vmcnt(12)
	v_pk_fma_f32 v[14:15], v[14:15], 0.5, v[78:79] op_sel_hi:[1,0,1]
	v_pk_fma_f32 v[16:17], v[16:17], 0.5, v[80:81] op_sel_hi:[1,0,1]
	v_pk_fma_f32 v[10:11], v[10:11], 0.5, v[74:75] op_sel_hi:[1,0,1]
	v_pk_fma_f32 v[12:13], v[12:13], 0.5, v[76:77] op_sel_hi:[1,0,1]
	v_pk_fma_f32 v[6:7], v[6:7], 0.5, v[70:71] op_sel_hi:[1,0,1]
	v_pk_fma_f32 v[8:9], v[8:9], 0.5, v[72:73] op_sel_hi:[1,0,1]
	v_pk_fma_f32 v[2:3], v[2:3], 0.5, v[66:67] op_sel_hi:[1,0,1]
	v_pk_fma_f32 v[4:5], v[4:5], 0.5, v[68:69] op_sel_hi:[1,0,1]
	s_mov_b64 vcc, s[4:5]
	v_cndmask_b32_dpp v78, v10, v14, vcc row_ror:8 row_mask:0xf bank_mask:0xf bound_ctrl:1
	v_cndmask_b32_dpp v79, v11, v15, vcc row_ror:8 row_mask:0xf bank_mask:0xf bound_ctrl:1
	v_cndmask_b32_dpp v80, v12, v16, vcc row_ror:8 row_mask:0xf bank_mask:0xf bound_ctrl:1
	v_cndmask_b32_dpp v81, v13, v17, vcc row_ror:8 row_mask:0xf bank_mask:0xf bound_ctrl:1
	v_cndmask_b32_dpp v70, v2, v6, vcc row_ror:8 row_mask:0xf bank_mask:0xf bound_ctrl:1
	v_cndmask_b32_dpp v71, v3, v7, vcc row_ror:8 row_mask:0xf bank_mask:0xf bound_ctrl:1
	v_cndmask_b32_dpp v72, v4, v8, vcc row_ror:8 row_mask:0xf bank_mask:0xf bound_ctrl:1
	v_cndmask_b32_dpp v73, v5, v9, vcc row_ror:8 row_mask:0xf bank_mask:0xf bound_ctrl:1
	s_not_b64 vcc, s[4:5]
	v_cndmask_b32_dpp v74, v14, v10, vcc row_ror:8 row_mask:0xf bank_mask:0xf bound_ctrl:1
	v_cndmask_b32_dpp v75, v15, v11, vcc row_ror:8 row_mask:0xf bank_mask:0xf bound_ctrl:1
	v_cndmask_b32_dpp v76, v16, v12, vcc row_ror:8 row_mask:0xf bank_mask:0xf bound_ctrl:1
	v_cndmask_b32_dpp v77, v17, v13, vcc row_ror:8 row_mask:0xf bank_mask:0xf bound_ctrl:1
	v_cndmask_b32_dpp v66, v6, v2, vcc row_ror:8 row_mask:0xf bank_mask:0xf bound_ctrl:1
	v_cndmask_b32_dpp v67, v7, v3, vcc row_ror:8 row_mask:0xf bank_mask:0xf bound_ctrl:1
	v_cndmask_b32_dpp v68, v8, v4, vcc row_ror:8 row_mask:0xf bank_mask:0xf bound_ctrl:1
	v_cndmask_b32_dpp v69, v9, v5, vcc row_ror:8 row_mask:0xf bank_mask:0xf bound_ctrl:1
	s_add_u32 s100, s28, 0xb0000
	s_addc_u32 s101, s29, 0
	global_store_dwordx4 v186, v[78:81], s[100:101]
	global_store_dwordx4 v187, v[74:77], s[100:101]
	global_store_dwordx4 v186, v[70:73], s[100:101] offset:512
	global_store_dwordx4 v187, v[66:69], s[100:101] offset:512
	s_and_b64 vcc, exec, s[6:7]
	s_cbranch_vccz .LBB0_500
	s_waitcnt vmcnt(0)
	s_cmpk_gt_u32 s24, 0xff
	s_cbranch_scc1 .LBB0_515
	s_barrier

.LBB0_524:
	s_and_b64 vcc, exec, s[22:23]
	s_cbranch_vccz .LBB0_526
	s_add_i32 s7, 0, 0x10000
	v_add_u32_e32 v0, s7, v147
	ds_read_b128 v[2:5], v0
	ds_read_b128 v[6:9], v0 offset:1024
	ds_read_b128 v[10:13], v0 offset:2048
	ds_read_b128 v[14:17], v0 offset:3072
	ds_read_b128 v[18:21], v149
	ds_read_b128 v[22:25], v149 offset:1024
	ds_read_b128 v[26:29], v149 offset:2048
	ds_read_b128 v[30:33], v149 offset:3072
	ds_read_b128 v[34:37], v149 offset:4096
	ds_read_b128 v[38:41], v149 offset:5120
	ds_read_b128 v[42:45], v149 offset:6144
	ds_read_b128 v[46:49], v149 offset:7168
	s_waitcnt lgkmcnt(8)
	s_setprio 1
	s_barrier
	s_waitcnt lgkmcnt(0)
	v_mfma_f32_16x16x32_bf16 v[50:53], v[2:5], v[18:21], 0
	v_mfma_f32_16x16x32_bf16 v[62:65], v[10:13], v[26:29], 0
	v_mfma_f32_16x16x32_bf16 v[66:69], v[2:5], v[34:37], 0
	v_mfma_f32_16x16x32_bf16 v[70:73], v[10:13], v[34:37], 0
	v_mfma_f32_16x16x32_bf16 v[74:77], v[2:5], v[42:45], 0
	v_mfma_f32_16x16x32_bf16 v[78:81], v[10:13], v[42:45], 0
	v_mfma_f32_16x16x32_bf16 v[50:53], v[6:9], v[22:25], v[50:53]
	v_mfma_f32_16x16x32_bf16 v[54:57], v[10:13], v[18:21], 0
	v_mfma_f32_16x16x32_bf16 v[58:61], v[2:5], v[26:29], 0
	v_mfma_f32_16x16x32_bf16 v[62:65], v[14:17], v[30:33], v[62:65]
	v_mfma_f32_16x16x32_bf16 v[66:69], v[6:9], v[38:41], v[66:69]
	v_mfma_f32_16x16x32_bf16 v[70:73], v[14:17], v[38:41], v[70:73]
	v_mfma_f32_16x16x32_bf16 v[74:77], v[6:9], v[46:49], v[74:77]
	v_mfma_f32_16x16x32_bf16 v[80:83], v[14:17], v[46:49], v[78:81]
	v_mfma_f32_16x16x32_bf16 v[194:197], v[14:17], v[22:25], v[54:57]
	v_mfma_f32_16x16x32_bf16 v[212:215], v[6:9], v[30:33], v[58:61]
	s_barrier
	s_setprio 0
	s_add_i32 s9, 0, 0x14000
	v_lshl_add_u64 v[144:145], s[18:19], 0, v[136:137]
	s_add_i32 s7, s7, s25
	v_add_u32_e32 v0, s9, v147
	v_lshl_add_u64 v[78:79], v[144:145], 0, s[50:51]
	s_mov_b32 m0, s7
	v_lshl_add_u64 v[198:199], s[18:19], 0, v[132:133]
	ds_read_b128 v[84:87], v0
	ds_read_b128 v[88:91], v0 offset:1024
	ds_read_b128 v[92:95], v0 offset:2048
	ds_read_b128 v[96:99], v0 offset:3072
	global_load_lds_dwordx4 v[78:79], off
	v_lshl_add_u64 v[78:79], v[198:199], 0, s[50:51]
	s_add_i32 m0, s7, 0x2000
	s_nop 0
	global_load_lds_dwordx4 v[78:79], off
	s_setprio 1
	s_barrier
	s_waitcnt lgkmcnt(0)
	v_mfma_f32_16x16x32_bf16 v[100:103], v[84:87], v[18:21], 0
	v_mfma_f32_16x16x32_bf16 v[18:21], v[92:95], v[18:21], 0
	v_mfma_f32_16x16x32_bf16 v[104:107], v[88:91], v[22:25], v[100:103]
	v_mfma_f32_16x16x32_bf16 v[18:21], v[96:99], v[22:25], v[18:21]
	v_mfma_f32_16x16x32_bf16 v[22:25], v[84:87], v[26:29], 0
	v_mfma_f32_16x16x32_bf16 v[26:29], v[92:95], v[26:29], 0
	v_mfma_f32_16x16x32_bf16 v[22:25], v[88:91], v[30:33], v[22:25]
	v_mfma_f32_16x16x32_bf16 v[26:29], v[96:99], v[30:33], v[26:29]
	v_mfma_f32_16x16x32_bf16 v[30:33], v[84:87], v[34:37], 0
	v_mfma_f32_16x16x32_bf16 v[34:37], v[92:95], v[34:37], 0
	v_mfma_f32_16x16x32_bf16 v[30:33], v[88:91], v[38:41], v[30:33]
	v_mfma_f32_16x16x32_bf16 v[34:37], v[96:99], v[38:41], v[34:37]
	v_mfma_f32_16x16x32_bf16 v[38:41], v[84:87], v[42:45], 0
	v_mfma_f32_16x16x32_bf16 v[42:45], v[92:95], v[42:45], 0
	v_mfma_f32_16x16x32_bf16 v[38:41], v[88:91], v[46:49], v[38:41]
	v_mfma_f32_16x16x32_bf16 v[42:45], v[96:99], v[46:49], v[42:45]
	s_barrier
	s_setprio 0
	v_lshl_add_u64 v[140:141], s[20:21], 0, v[138:139]
	s_mov_b32 m0, s11
	v_lshl_add_u64 v[78:79], v[140:141], 0, s[50:51]
	v_lshl_add_u64 v[142:143], s[20:21], 0, v[134:135]
	ds_read_b128 v[46:49], v149 offset:16384
	ds_read_b128 v[100:103], v149 offset:17408
	ds_read_b128 v[108:111], v149 offset:18432
	ds_read_b128 v[112:115], v149 offset:19456
	ds_read_b128 v[116:119], v149 offset:20480
	ds_read_b128 v[120:123], v149 offset:21504
	ds_read_b128 v[124:127], v149 offset:22528
	ds_read_b128 v[128:131], v149 offset:23552
	global_load_lds_dwordx4 v[78:79], off
	v_lshl_add_u64 v[78:79], v[142:143], 0, s[50:51]
	s_mov_b32 m0, s57
	s_nop 0
	global_load_lds_dwordx4 v[78:79], off
	s_setprio 1
	s_barrier
	s_waitcnt lgkmcnt(0)
	v_mfma_f32_16x16x32_bf16 v[150:153], v[2:5], v[46:49], 0
	v_mfma_f32_16x16x32_bf16 v[154:157], v[10:13], v[46:49], 0
	v_mfma_f32_16x16x32_bf16 v[158:161], v[2:5], v[108:111], 0
	v_mfma_f32_16x16x32_bf16 v[166:169], v[2:5], v[116:119], 0
	v_mfma_f32_16x16x32_bf16 v[2:5], v[2:5], v[124:127], 0
	v_mfma_f32_16x16x32_bf16 v[54:57], v[6:9], v[100:103], v[150:153]
	v_mfma_f32_16x16x32_bf16 v[152:155], v[14:17], v[100:103], v[154:157]
	v_mfma_f32_16x16x32_bf16 v[156:159], v[6:9], v[112:115], v[158:161]
	v_mfma_f32_16x16x32_bf16 v[166:169], v[6:9], v[120:123], v[166:169]
	v_mfma_f32_16x16x32_bf16 v[2:5], v[6:9], v[128:131], v[2:5]
	v_mfma_f32_16x16x32_bf16 v[6:9], v[10:13], v[124:127], 0
	v_mfma_f32_16x16x32_bf16 v[162:165], v[10:13], v[108:111], 0
	v_mfma_f32_16x16x32_bf16 v[170:173], v[10:13], v[116:119], 0
	v_mfma_f32_16x16x32_bf16 v[6:9], v[14:17], v[128:131], v[6:9]
	v_mfma_f32_16x16x32_bf16 v[160:163], v[14:17], v[112:115], v[162:165]
	v_mfma_f32_16x16x32_bf16 v[170:173], v[14:17], v[120:123], v[170:173]
	s_barrier
	s_setprio 0
	s_add_u32 s14, s18, 0x40100
	s_addc_u32 s15, s19, 0
	s_add_i32 s7, s9, s25
	v_lshl_add_u64 v[10:11], s[14:15], 0, v[136:137]
	s_mov_b32 m0, s7
	s_nop 0
	global_load_lds_dwordx4 v[10:11], off
	v_lshl_add_u64 v[10:11], s[14:15], 0, v[132:133]
	s_add_i32 m0, s7, 0x2000
	s_nop 0
	global_load_lds_dwordx4 v[10:11], off
	s_setprio 1
	s_barrier
	v_mfma_f32_16x16x32_bf16 v[10:13], v[84:87], v[46:49], 0
	v_mfma_f32_16x16x32_bf16 v[174:177], v[88:91], v[100:103], v[10:13]
	v_mfma_f32_16x16x32_bf16 v[10:13], v[92:95], v[46:49], 0
	v_mfma_f32_16x16x32_bf16 v[178:181], v[96:99], v[100:103], v[10:13]
	v_mfma_f32_16x16x32_bf16 v[10:13], v[84:87], v[108:111], 0
	v_mfma_f32_16x16x32_bf16 v[182:185], v[88:91], v[112:115], v[10:13]
	v_mfma_f32_16x16x32_bf16 v[10:13], v[92:95], v[108:111], 0
	v_mfma_f32_16x16x32_bf16 v[186:189], v[96:99], v[112:115], v[10:13]
	v_mfma_f32_16x16x32_bf16 v[10:13], v[84:87], v[116:119], 0
	v_mfma_f32_16x16x32_bf16 v[190:193], v[88:91], v[120:123], v[10:13]
	v_mfma_f32_16x16x32_bf16 v[10:13], v[92:95], v[116:119], 0
	v_mfma_f32_16x16x32_bf16 v[200:203], v[96:99], v[120:123], v[10:13]
	v_mfma_f32_16x16x32_bf16 v[10:13], v[84:87], v[124:127], 0
	v_mfma_f32_16x16x32_bf16 v[204:207], v[88:91], v[128:131], v[10:13]
	v_mfma_f32_16x16x32_bf16 v[10:13], v[92:95], v[124:127], 0
	v_mfma_f32_16x16x32_bf16 v[208:211], v[96:99], v[128:131], v[10:13]
	s_barrier
	s_setprio 0
	s_add_i32 s7, 0, 0x18000
	v_add_u32_e32 v0, s7, v147
	s_nop 2
	ds_read_b128 v[10:13], v0
	ds_read_b128 v[14:17], v0 offset:1024
	v_mov_b64_e32 v[164:165], v[220:221]
	ds_read_b128 v[218:221], v0 offset:2048
	v_mov_b64_e32 v[58:59], v[222:223]
	ds_read_b128 v[222:225], v0 offset:3072
	s_add_u32 s14, s20, 0x40100
	s_addc_u32 s15, s21, 0
	s_mov_b32 m0, s58
	v_lshl_add_u64 v[78:79], s[14:15], 0, v[138:139]
	ds_read_b128 v[46:49], v149 offset:32768
	ds_read_b128 v[88:91], v149 offset:33792
	ds_read_b128 v[96:99], v149 offset:34816
	ds_read_b128 v[226:229], v149 offset:35840
	ds_read_b128 v[230:233], v149 offset:36864
	ds_read_b128 v[234:237], v149 offset:37888
	ds_read_b128 v[238:241], v149 offset:38912
	ds_read_b128 v[242:245], v149 offset:39936
	global_load_lds_dwordx4 v[78:79], off
	v_lshl_add_u64 v[78:79], s[14:15], 0, v[134:135]
	s_mov_b32 m0, s59
	v_mov_b32_e32 v151, v1
	global_load_lds_dwordx4 v[78:79], off
	s_waitcnt lgkmcnt(8)
	s_setprio 1
	s_barrier
	s_waitcnt lgkmcnt(0)
	v_mfma_f32_16x16x32_bf16 v[50:53], v[10:13], v[46:49], v[50:53]
	v_mfma_f32_16x16x32_bf16 v[124:127], v[14:17], v[88:91], v[50:53]
	v_mfma_f32_16x16x32_bf16 v[50:53], v[218:221], v[46:49], v[194:197]
	v_mfma_f32_16x16x32_bf16 v[116:119], v[222:225], v[88:91], v[50:53]
	v_mfma_f32_16x16x32_bf16 v[50:53], v[10:13], v[96:99], v[212:215]
	v_mfma_f32_16x16x32_bf16 v[108:111], v[14:17], v[226:229], v[50:53]
	v_mfma_f32_16x16x32_bf16 v[50:53], v[218:221], v[96:99], v[62:65]
	v_mfma_f32_16x16x32_bf16 v[100:103], v[222:225], v[226:229], v[50:53]
	v_mfma_f32_16x16x32_bf16 v[50:53], v[10:13], v[230:233], v[66:69]
	v_mfma_f32_16x16x32_bf16 v[92:95], v[14:17], v[234:237], v[50:53]
	v_mfma_f32_16x16x32_bf16 v[50:53], v[218:221], v[230:233], v[70:73]
	v_mfma_f32_16x16x32_bf16 v[84:87], v[222:225], v[234:237], v[50:53]
	v_mfma_f32_16x16x32_bf16 v[50:53], v[10:13], v[238:241], v[74:77]
	v_mfma_f32_16x16x32_bf16 v[76:79], v[14:17], v[242:245], v[50:53]
	v_mfma_f32_16x16x32_bf16 v[50:53], v[218:221], v[238:241], v[80:83]
	v_mfma_f32_16x16x32_bf16 v[64:67], v[222:225], v[242:245], v[50:53]
	s_barrier
	s_setprio 0
	s_add_i32 s9, 0, 0x1c000
	s_add_i32 s7, s7, s25
	v_add_u32_e32 v0, s9, v147
	s_nop 1
	v_lshl_add_u64 v[50:51], v[144:145], 0, s[62:63]
	s_mov_b32 m0, s7
	ds_read_b128 v[246:249], v0
	v_mov_b32_e32 v150, v148
	v_mov_b32_e32 v148, v254
	v_mov_b32_e32 v254, v216
	v_mov_b32_e32 v1, v217
	v_mov_b64_e32 v[216:217], v[252:253]
	ds_read_b128 v[250:253], v0 offset:1024
	ds_read_b128 v[194:197], v0 offset:2048
	ds_read_b128 v[212:215], v0 offset:3072
	global_load_lds_dwordx4 v[50:51], off
	v_lshl_add_u64 v[50:51], v[198:199], 0, s[62:63]
	s_add_i32 m0, s7, 0x2000
	s_nop 0
	global_load_lds_dwordx4 v[50:51], off
	s_setprio 1
	s_barrier
	s_waitcnt lgkmcnt(0)
	v_mfma_f32_16x16x32_bf16 v[18:21], v[194:197], v[46:49], v[18:21]
	v_mfma_f32_16x16x32_bf16 v[120:123], v[212:215], v[88:91], v[18:21]
	v_mfma_f32_16x16x32_bf16 v[18:21], v[246:249], v[96:99], v[22:25]
	v_mfma_f32_16x16x32_bf16 v[112:115], v[250:253], v[226:229], v[18:21]
	v_mfma_f32_16x16x32_bf16 v[18:21], v[194:197], v[96:99], v[26:29]
	v_mfma_f32_16x16x32_bf16 v[50:53], v[246:249], v[46:49], v[104:107]
	v_mfma_f32_16x16x32_bf16 v[104:107], v[212:215], v[226:229], v[18:21]
	v_mfma_f32_16x16x32_bf16 v[18:21], v[246:249], v[230:233], v[30:33]
	v_mfma_f32_16x16x32_bf16 v[96:99], v[250:253], v[234:237], v[18:21]
	v_mfma_f32_16x16x32_bf16 v[18:21], v[194:197], v[230:233], v[34:37]
	v_mfma_f32_16x16x32_bf16 v[128:131], v[250:253], v[88:91], v[50:53]
	v_mfma_f32_16x16x32_bf16 v[88:91], v[212:215], v[234:237], v[18:21]
	v_mfma_f32_16x16x32_bf16 v[18:21], v[246:249], v[238:241], v[38:41]
	v_mfma_f32_16x16x32_bf16 v[80:83], v[250:253], v[242:245], v[18:21]
	v_mfma_f32_16x16x32_bf16 v[18:21], v[194:197], v[238:241], v[42:45]
	v_mfma_f32_16x16x32_bf16 v[72:75], v[212:215], v[242:245], v[18:21]
	s_setprio 0
	s_mov_b32 m0, s60
	s_nop 4
	v_lshl_add_u64 v[18:19], v[140:141], 0, s[62:63]
	s_barrier
	ds_read_b128 v[24:27], v149 offset:49152
	ds_read_b128 v[32:35], v149 offset:50176
	ds_read_b128 v[40:43], v149 offset:51200
	ds_read_b128 v[226:229], v149 offset:52224
	ds_read_b128 v[230:233], v149 offset:53248
	ds_read_b128 v[234:237], v149 offset:54272
	ds_read_b128 v[238:241], v149 offset:55296
	ds_read_b128 v[242:245], v149 offset:56320
	global_load_lds_dwordx4 v[18:19], off
	v_lshl_add_u64 v[18:19], v[142:143], 0, s[62:63]
	s_mov_b32 m0, s61
	s_nop 0
	global_load_lds_dwordx4 v[18:19], off
	s_setprio 1
	s_barrier
	s_waitcnt lgkmcnt(0)
	v_mfma_f32_16x16x32_bf16 v[18:21], v[10:13], v[24:27], v[54:57]
	v_mfma_f32_16x16x32_bf16 v[60:63], v[14:17], v[32:35], v[18:21]
	v_mfma_f32_16x16x32_bf16 v[18:21], v[218:221], v[24:27], v[152:155]
	v_mfma_f32_16x16x32_bf16 v[52:55], v[222:225], v[32:35], v[18:21]
	v_mfma_f32_16x16x32_bf16 v[18:21], v[10:13], v[40:43], v[156:159]
	v_mfma_f32_16x16x32_bf16 v[44:47], v[14:17], v[226:229], v[18:21]
	v_mfma_f32_16x16x32_bf16 v[18:21], v[218:221], v[40:43], v[160:163]
	v_mfma_f32_16x16x32_bf16 v[36:39], v[222:225], v[226:229], v[18:21]
	v_mfma_f32_16x16x32_bf16 v[18:21], v[10:13], v[230:233], v[166:169]
	v_mfma_f32_16x16x32_bf16 v[2:5], v[10:13], v[238:241], v[2:5]
	v_mfma_f32_16x16x32_bf16 v[28:31], v[14:17], v[234:237], v[18:21]
	v_mfma_f32_16x16x32_bf16 v[18:21], v[218:221], v[230:233], v[170:173]
	v_mfma_f32_16x16x32_bf16 v[12:15], v[14:17], v[242:245], v[2:5]
	v_mfma_f32_16x16x32_bf16 v[2:5], v[218:221], v[238:241], v[6:9]
	v_mov_b64_e32 v[220:221], v[164:165]
	v_mfma_f32_16x16x32_bf16 v[20:23], v[222:225], v[234:237], v[18:21]
	v_mfma_f32_16x16x32_bf16 v[4:7], v[222:225], v[242:245], v[2:5]
	v_mov_b64_e32 v[222:223], v[58:59]
	s_setprio 0
	s_barrier
	s_add_u32 s14, s18, 0x40180
	s_addc_u32 s15, s19, 0
	s_add_i32 s7, s9, s25
	v_lshl_add_u64 v[2:3], s[14:15], 0, v[136:137]
	s_mov_b32 m0, s7
	s_nop 0
	global_load_lds_dwordx4 v[2:3], off
	v_lshl_add_u64 v[2:3], s[14:15], 0, v[132:133]
	s_add_i32 m0, s7, 0x2000
	s_nop 0
	global_load_lds_dwordx4 v[2:3], off
	s_waitcnt vmcnt(6)
	s_setprio 1
	s_barrier
	v_mfma_f32_16x16x32_bf16 v[8:11], v[246:249], v[24:27], v[174:177]
	v_mfma_f32_16x16x32_bf16 v[68:71], v[250:253], v[32:35], v[8:11]
	v_mfma_f32_16x16x32_bf16 v[8:11], v[194:197], v[24:27], v[178:181]
	v_mfma_f32_16x16x32_bf16 v[56:59], v[212:215], v[32:35], v[8:11]
	v_mfma_f32_16x16x32_bf16 v[8:11], v[246:249], v[40:43], v[182:185]
	v_mfma_f32_16x16x32_bf16 v[48:51], v[250:253], v[226:229], v[8:11]
	v_mfma_f32_16x16x32_bf16 v[8:11], v[194:197], v[40:43], v[186:189]
	v_mfma_f32_16x16x32_bf16 v[40:43], v[212:215], v[226:229], v[8:11]
	v_mfma_f32_16x16x32_bf16 v[8:11], v[246:249], v[230:233], v[190:193]
	v_mfma_f32_16x16x32_bf16 v[32:35], v[250:253], v[234:237], v[8:11]
	v_mfma_f32_16x16x32_bf16 v[8:11], v[194:197], v[230:233], v[200:203]
	v_mfma_f32_16x16x32_bf16 v[24:27], v[212:215], v[234:237], v[8:11]
	v_mfma_f32_16x16x32_bf16 v[8:11], v[246:249], v[238:241], v[204:207]
	v_mfma_f32_16x16x32_bf16 v[16:19], v[250:253], v[242:245], v[8:11]
	v_mov_b64_e32 v[252:253], v[216:217]
	v_mov_b32_e32 v217, v1
	v_mov_b32_e32 v216, v254
	v_mfma_f32_16x16x32_bf16 v[8:11], v[194:197], v[238:241], v[208:211]
	v_mov_b32_e32 v254, v148
	v_mov_b32_e32 v148, v150
	v_mov_b32_e32 v1, v151
	v_mfma_f32_16x16x32_bf16 v[8:11], v[212:215], v[242:245], v[8:11]
	s_barrier
	s_setprio 0
	s_mov_b32 s22, 2
	s_branch .LBB0_527

.LBB0_528:
	s_add_u32 s20, s81, s46
	s_addc_u32 s21, s82, 0
	s_add_u32 s83, s79, s46
	s_addc_u32 s84, s80, 0
	s_add_i32 s85, 0, 0x10000
	v_add_u32_e32 v0, s85, v147
	ds_read_b128 v[150:153], v0
	ds_read_b128 v[154:157], v0 offset:1024
	ds_read_b128 v[158:161], v0 offset:2048
	ds_read_b128 v[162:165], v0 offset:3072
	s_cmp_eq_u32 s46, s18
	s_cselect_b32 s23, s9, s21
	s_cselect_b32 s22, s76, s20
	s_cselect_b32 s21, s7, s84
	s_cselect_b32 s20, s77, s83
	s_add_i32 s84, s11, 0xc000
	v_lshl_add_u64 v[140:141], v[144:145], 0, s[46:47]
	s_mov_b32 m0, s84
	s_add_i32 s83, s11, 0xe000
	ds_read_b128 v[166:169], v149
	ds_read_b128 v[170:173], v149 offset:1024
	ds_read_b128 v[174:177], v149 offset:2048
	ds_read_b128 v[178:181], v149 offset:3072
	ds_read_b128 v[182:185], v149 offset:4096
	ds_read_b128 v[186:189], v149 offset:5120
	ds_read_b128 v[190:193], v149 offset:6144
	ds_read_b128 v[194:197], v149 offset:7168
	global_load_lds_dwordx4 v[140:141], off
	v_lshl_add_u64 v[140:141], v[2:3], 0, s[46:47]
	s_mov_b32 m0, s83
	s_nop 0
	global_load_lds_dwordx4 v[140:141], off
	s_waitcnt lgkmcnt(8)
	s_setprio 1
	s_barrier
	s_waitcnt lgkmcnt(0)
	v_mfma_f32_16x16x32_bf16 v[124:127], v[150:153], v[166:169], v[124:127]
	v_mfma_f32_16x16x32_bf16 v[116:119], v[158:161], v[166:169], v[116:119]
	v_mfma_f32_16x16x32_bf16 v[108:111], v[150:153], v[174:177], v[108:111]
	v_mfma_f32_16x16x32_bf16 v[100:103], v[158:161], v[174:177], v[100:103]
	v_mfma_f32_16x16x32_bf16 v[92:95], v[150:153], v[182:185], v[92:95]
	v_mfma_f32_16x16x32_bf16 v[84:87], v[158:161], v[182:185], v[84:87]
	v_mfma_f32_16x16x32_bf16 v[76:79], v[150:153], v[190:193], v[76:79]
	v_mfma_f32_16x16x32_bf16 v[64:67], v[158:161], v[190:193], v[64:67]
	v_mfma_f32_16x16x32_bf16 v[124:127], v[154:157], v[170:173], v[124:127]
	v_mfma_f32_16x16x32_bf16 v[116:119], v[162:165], v[170:173], v[116:119]
	v_mfma_f32_16x16x32_bf16 v[108:111], v[154:157], v[178:181], v[108:111]
	v_mfma_f32_16x16x32_bf16 v[100:103], v[162:165], v[178:181], v[100:103]
	v_mfma_f32_16x16x32_bf16 v[92:95], v[154:157], v[186:189], v[92:95]
	v_mfma_f32_16x16x32_bf16 v[84:87], v[162:165], v[186:189], v[84:87]
	v_mfma_f32_16x16x32_bf16 v[76:79], v[154:157], v[194:197], v[76:79]
	v_mfma_f32_16x16x32_bf16 v[64:67], v[162:165], v[194:197], v[64:67]
	s_barrier
	s_setprio 0
	s_add_i32 s88, 0, 0x14000
	s_add_i32 s85, s85, s25
	v_add_u32_e32 v0, s88, v147
	v_lshl_add_u64 v[140:141], s[20:21], 0, v[136:137]
	s_mov_b32 m0, s85
	ds_read_b128 v[200:203], v0
	ds_read_b128 v[204:207], v0 offset:1024
	ds_read_b128 v[208:211], v0 offset:2048
	ds_read_b128 v[212:215], v0 offset:3072
	global_load_lds_dwordx4 v[140:141], off
	v_lshl_add_u64 v[142:143], s[20:21], 0, v[132:133]
	s_add_i32 m0, s85, 0x2000
	s_nop 0
	global_load_lds_dwordx4 v[142:143], off
	s_setprio 1
	s_barrier
	s_waitcnt lgkmcnt(0)
	v_mfma_f32_16x16x32_bf16 v[128:131], v[200:203], v[166:169], v[128:131]
	v_mfma_f32_16x16x32_bf16 v[120:123], v[208:211], v[166:169], v[120:123]
	v_mfma_f32_16x16x32_bf16 v[112:115], v[200:203], v[174:177], v[112:115]
	v_mfma_f32_16x16x32_bf16 v[104:107], v[208:211], v[174:177], v[104:107]
	v_mfma_f32_16x16x32_bf16 v[96:99], v[200:203], v[182:185], v[96:99]
	v_mfma_f32_16x16x32_bf16 v[88:91], v[208:211], v[182:185], v[88:91]
	v_mfma_f32_16x16x32_bf16 v[80:83], v[200:203], v[190:193], v[80:83]
	v_mfma_f32_16x16x32_bf16 v[72:75], v[208:211], v[190:193], v[72:75]
	v_mfma_f32_16x16x32_bf16 v[128:131], v[204:207], v[170:173], v[128:131]
	v_mfma_f32_16x16x32_bf16 v[120:123], v[212:215], v[170:173], v[120:123]
	v_mfma_f32_16x16x32_bf16 v[112:115], v[204:207], v[178:181], v[112:115]
	v_mfma_f32_16x16x32_bf16 v[104:107], v[212:215], v[178:181], v[104:107]
	v_mfma_f32_16x16x32_bf16 v[96:99], v[204:207], v[186:189], v[96:99]
	v_mfma_f32_16x16x32_bf16 v[88:91], v[212:215], v[186:189], v[88:91]
	v_mfma_f32_16x16x32_bf16 v[80:83], v[204:207], v[194:197], v[80:83]
	v_mfma_f32_16x16x32_bf16 v[72:75], v[212:215], v[194:197], v[72:75]
	s_barrier
	s_setprio 0
	s_mov_b32 m0, s11
	v_lshl_add_u64 v[198:199], s[22:23], 0, v[138:139]
	ds_read_b128 v[166:169], v149 offset:16384
	ds_read_b128 v[170:173], v149 offset:17408
	ds_read_b128 v[174:177], v149 offset:18432
	ds_read_b128 v[178:181], v149 offset:19456
	ds_read_b128 v[182:185], v149 offset:20480
	ds_read_b128 v[186:189], v149 offset:21504
	ds_read_b128 v[190:193], v149 offset:22528
	ds_read_b128 v[194:197], v149 offset:23552
	global_load_lds_dwordx4 v[198:199], off
	v_lshl_add_u64 v[218:219], s[22:23], 0, v[134:135]
	s_mov_b32 m0, s57
	s_nop 0
	global_load_lds_dwordx4 v[218:219], off
	s_setprio 1
	s_barrier
	s_waitcnt lgkmcnt(0)
	v_mfma_f32_16x16x32_bf16 v[60:63], v[150:153], v[166:169], v[60:63]
	v_mfma_f32_16x16x32_bf16 v[52:55], v[158:161], v[166:169], v[52:55]
	v_mfma_f32_16x16x32_bf16 v[44:47], v[150:153], v[174:177], v[44:47]
	v_mfma_f32_16x16x32_bf16 v[36:39], v[158:161], v[174:177], v[36:39]
	v_mfma_f32_16x16x32_bf16 v[28:31], v[150:153], v[182:185], v[28:31]
	v_mfma_f32_16x16x32_bf16 v[20:23], v[158:161], v[182:185], v[20:23]
	v_mfma_f32_16x16x32_bf16 v[12:15], v[150:153], v[190:193], v[12:15]
	v_mfma_f32_16x16x32_bf16 v[4:7], v[158:161], v[190:193], v[4:7]
	v_mfma_f32_16x16x32_bf16 v[60:63], v[154:157], v[170:173], v[60:63]
	v_mfma_f32_16x16x32_bf16 v[52:55], v[162:165], v[170:173], v[52:55]
	v_mfma_f32_16x16x32_bf16 v[44:47], v[154:157], v[178:181], v[44:47]
	v_mfma_f32_16x16x32_bf16 v[36:39], v[162:165], v[178:181], v[36:39]
	v_mfma_f32_16x16x32_bf16 v[28:31], v[154:157], v[186:189], v[28:31]
	v_mfma_f32_16x16x32_bf16 v[20:23], v[162:165], v[186:189], v[20:23]
	v_mfma_f32_16x16x32_bf16 v[12:15], v[154:157], v[194:197], v[12:15]
	v_mfma_f32_16x16x32_bf16 v[4:7], v[162:165], v[194:197], v[4:7]
	s_barrier
	s_setprio 0
	s_add_u32 s86, s20, 0x40000
	s_addc_u32 s87, s21, 0
	s_add_i32 s85, s88, s25
	v_lshl_add_u64 v[150:151], s[86:87], 0, v[136:137]
	s_mov_b32 m0, s85
	s_nop 0
	global_load_lds_dwordx4 v[150:151], off
	v_lshl_add_u64 v[150:151], s[86:87], 0, v[132:133]
	s_add_i32 m0, s85, 0x2000
	s_nop 0
	global_load_lds_dwordx4 v[150:151], off
	s_waitcnt vmcnt(6)
	s_setprio 1
	s_barrier
	v_mfma_f32_16x16x32_bf16 v[68:71], v[200:203], v[166:169], v[68:71]
	v_mfma_f32_16x16x32_bf16 v[56:59], v[208:211], v[166:169], v[56:59]
	v_mfma_f32_16x16x32_bf16 v[48:51], v[200:203], v[174:177], v[48:51]
	v_mfma_f32_16x16x32_bf16 v[40:43], v[208:211], v[174:177], v[40:43]
	v_mfma_f32_16x16x32_bf16 v[32:35], v[200:203], v[182:185], v[32:35]
	v_mfma_f32_16x16x32_bf16 v[24:27], v[208:211], v[182:185], v[24:27]
	v_mfma_f32_16x16x32_bf16 v[16:19], v[200:203], v[190:193], v[16:19]
	v_mfma_f32_16x16x32_bf16 v[8:11], v[208:211], v[190:193], v[8:11]
	v_mfma_f32_16x16x32_bf16 v[68:71], v[204:207], v[170:173], v[68:71]
	v_mfma_f32_16x16x32_bf16 v[56:59], v[212:215], v[170:173], v[56:59]
	v_mfma_f32_16x16x32_bf16 v[48:51], v[204:207], v[178:181], v[48:51]
	v_mfma_f32_16x16x32_bf16 v[40:43], v[212:215], v[178:181], v[40:43]
	v_mfma_f32_16x16x32_bf16 v[32:35], v[204:207], v[186:189], v[32:35]
	v_mfma_f32_16x16x32_bf16 v[24:27], v[212:215], v[186:189], v[24:27]
	v_mfma_f32_16x16x32_bf16 v[16:19], v[204:207], v[194:197], v[16:19]
	v_mfma_f32_16x16x32_bf16 v[8:11], v[212:215], v[194:197], v[8:11]
	s_barrier
	s_setprio 0
	s_add_i32 s85, 0, 0x18000
	v_add_u32_e32 v0, s85, v147
	ds_read_b128 v[150:153], v0
	ds_read_b128 v[154:157], v0 offset:1024
	ds_read_b128 v[158:161], v0 offset:2048
	ds_read_b128 v[162:165], v0 offset:3072
	s_add_u32 s22, s22, 0x40000
	s_addc_u32 s23, s23, 0
	s_mov_b32 m0, s58
	v_lshl_add_u64 v[200:201], s[22:23], 0, v[138:139]
	ds_read_b128 v[166:169], v149 offset:32768
	ds_read_b128 v[170:173], v149 offset:33792
	ds_read_b128 v[174:177], v149 offset:34816
	ds_read_b128 v[178:181], v149 offset:35840
	ds_read_b128 v[182:185], v149 offset:36864
	ds_read_b128 v[186:189], v149 offset:37888
	ds_read_b128 v[190:193], v149 offset:38912
	ds_read_b128 v[194:197], v149 offset:39936
	global_load_lds_dwordx4 v[200:201], off
	v_lshl_add_u64 v[200:201], s[22:23], 0, v[134:135]
	s_mov_b32 m0, s59
	s_nop 0
	global_load_lds_dwordx4 v[200:201], off
	s_waitcnt lgkmcnt(8)
	s_setprio 1
	s_barrier
	s_waitcnt lgkmcnt(0)
	v_mfma_f32_16x16x32_bf16 v[124:127], v[150:153], v[166:169], v[124:127]
	v_mfma_f32_16x16x32_bf16 v[116:119], v[158:161], v[166:169], v[116:119]
	v_mfma_f32_16x16x32_bf16 v[108:111], v[150:153], v[174:177], v[108:111]
	v_mfma_f32_16x16x32_bf16 v[100:103], v[158:161], v[174:177], v[100:103]
	v_mfma_f32_16x16x32_bf16 v[92:95], v[150:153], v[182:185], v[92:95]
	v_mfma_f32_16x16x32_bf16 v[84:87], v[158:161], v[182:185], v[84:87]
	v_mfma_f32_16x16x32_bf16 v[76:79], v[150:153], v[190:193], v[76:79]
	v_mfma_f32_16x16x32_bf16 v[64:67], v[158:161], v[190:193], v[64:67]
	v_mfma_f32_16x16x32_bf16 v[124:127], v[154:157], v[170:173], v[124:127]
	v_mfma_f32_16x16x32_bf16 v[116:119], v[162:165], v[170:173], v[116:119]
	v_mfma_f32_16x16x32_bf16 v[108:111], v[154:157], v[178:181], v[108:111]
	v_mfma_f32_16x16x32_bf16 v[100:103], v[162:165], v[178:181], v[100:103]
	v_mfma_f32_16x16x32_bf16 v[92:95], v[154:157], v[186:189], v[92:95]
	v_mfma_f32_16x16x32_bf16 v[84:87], v[162:165], v[186:189], v[84:87]
	v_mfma_f32_16x16x32_bf16 v[76:79], v[154:157], v[194:197], v[76:79]
	v_mfma_f32_16x16x32_bf16 v[64:67], v[162:165], v[194:197], v[64:67]
	s_barrier
	s_setprio 0
	s_add_i32 s22, 0, 0x1c000
	s_add_i32 s23, s85, s25
	v_add_u32_e32 v0, s22, v147
	v_lshl_add_u64 v[140:141], v[140:141], 0, s[48:49]
	s_mov_b32 m0, s23
	ds_read_b128 v[200:203], v0
	ds_read_b128 v[204:207], v0 offset:1024
	ds_read_b128 v[208:211], v0 offset:2048
	ds_read_b128 v[212:215], v0 offset:3072
	global_load_lds_dwordx4 v[140:141], off
	v_lshl_add_u64 v[140:141], v[142:143], 0, s[48:49]
	s_add_i32 m0, s23, 0x2000
	s_nop 0
	global_load_lds_dwordx4 v[140:141], off
	s_setprio 1
	s_barrier
	s_waitcnt lgkmcnt(0)
	v_mfma_f32_16x16x32_bf16 v[128:131], v[200:203], v[166:169], v[128:131]
	v_mfma_f32_16x16x32_bf16 v[120:123], v[208:211], v[166:169], v[120:123]
	v_mfma_f32_16x16x32_bf16 v[112:115], v[200:203], v[174:177], v[112:115]
	v_mfma_f32_16x16x32_bf16 v[104:107], v[208:211], v[174:177], v[104:107]
	v_mfma_f32_16x16x32_bf16 v[96:99], v[200:203], v[182:185], v[96:99]
	v_mfma_f32_16x16x32_bf16 v[88:91], v[208:211], v[182:185], v[88:91]
	v_mfma_f32_16x16x32_bf16 v[80:83], v[200:203], v[190:193], v[80:83]
	v_mfma_f32_16x16x32_bf16 v[72:75], v[208:211], v[190:193], v[72:75]
	v_mfma_f32_16x16x32_bf16 v[128:131], v[204:207], v[170:173], v[128:131]
	v_mfma_f32_16x16x32_bf16 v[120:123], v[212:215], v[170:173], v[120:123]
	v_mfma_f32_16x16x32_bf16 v[112:115], v[204:207], v[178:181], v[112:115]
	v_mfma_f32_16x16x32_bf16 v[104:107], v[212:215], v[178:181], v[104:107]
	v_mfma_f32_16x16x32_bf16 v[96:99], v[204:207], v[186:189], v[96:99]
	v_mfma_f32_16x16x32_bf16 v[88:91], v[212:215], v[186:189], v[88:91]
	v_mfma_f32_16x16x32_bf16 v[80:83], v[204:207], v[194:197], v[80:83]
	v_mfma_f32_16x16x32_bf16 v[72:75], v[212:215], v[194:197], v[72:75]
	s_barrier
	s_setprio 0
	s_mov_b32 m0, s60
	v_lshl_add_u64 v[140:141], v[198:199], 0, s[48:49]
	ds_read_b128 v[166:169], v149 offset:49152
	ds_read_b128 v[170:173], v149 offset:50176
	ds_read_b128 v[174:177], v149 offset:51200
	ds_read_b128 v[178:181], v149 offset:52224
	ds_read_b128 v[182:185], v149 offset:53248
	ds_read_b128 v[186:189], v149 offset:54272
	ds_read_b128 v[190:193], v149 offset:55296
	ds_read_b128 v[194:197], v149 offset:56320
	global_load_lds_dwordx4 v[140:141], off
	v_lshl_add_u64 v[140:141], v[218:219], 0, s[48:49]
	s_mov_b32 m0, s61
	s_nop 0
	global_load_lds_dwordx4 v[140:141], off
	s_setprio 1
	s_barrier
; #define PG8_STAGE(bufoff, gbase, voff) do { _Pragma("unroll") for (int _i = 0; _i < 2; ++_i) \
;         __builtin_amdgcn_global_load_lds((const unsigned*)((const char*)(gbase) + (voff)[_i]), (PG8_LAS unsigned*)(lds + (bufoff) + ldsw + _i * 8192), 16, 0, 0); } while (0)
; template <class Epi, class Sched>
; __device__ __forceinline__ void gemm_phase(PG8_LAS unsigned char* lds, const Gemm g, const Sched& S, const Epi& E, int wv) {
;     ...
;         for (int t = t0_; t < nt; t += 2) { PG8_ITER_N(t); }
;         if constexpr (Epi::HOIST) PG8_STAGE(PG8_SA(1, 1), nA + kstep + hstepA, voffA);
	s_waitcnt lgkmcnt(0)
	v_mfma_f32_16x16x32_bf16 v[60:63], v[150:153], v[166:169], v[60:63]
	v_mfma_f32_16x16x32_bf16 v[52:55], v[158:161], v[166:169], v[52:55]
	v_mfma_f32_16x16x32_bf16 v[44:47], v[150:153], v[174:177], v[44:47]
	v_mfma_f32_16x16x32_bf16 v[36:39], v[158:161], v[174:177], v[36:39]
	v_mfma_f32_16x16x32_bf16 v[28:31], v[150:153], v[182:185], v[28:31]
	v_mfma_f32_16x16x32_bf16 v[20:23], v[158:161], v[182:185], v[20:23]
	v_mfma_f32_16x16x32_bf16 v[12:15], v[150:153], v[190:193], v[12:15]
	v_mfma_f32_16x16x32_bf16 v[4:7], v[158:161], v[190:193], v[4:7]
	v_mfma_f32_16x16x32_bf16 v[60:63], v[154:157], v[170:173], v[60:63]
	v_mfma_f32_16x16x32_bf16 v[52:55], v[162:165], v[170:173], v[52:55]
	v_mfma_f32_16x16x32_bf16 v[44:47], v[154:157], v[178:181], v[44:47]
	v_mfma_f32_16x16x32_bf16 v[36:39], v[162:165], v[178:181], v[36:39]
	v_mfma_f32_16x16x32_bf16 v[28:31], v[154:157], v[186:189], v[28:31]
	v_mfma_f32_16x16x32_bf16 v[20:23], v[162:165], v[186:189], v[20:23]
	v_mfma_f32_16x16x32_bf16 v[12:15], v[154:157], v[194:197], v[12:15]
	v_mfma_f32_16x16x32_bf16 v[4:7], v[162:165], v[194:197], v[4:7]
	s_barrier
	s_setprio 0
	s_add_u32 s20, s20, 0x40080
	s_addc_u32 s21, s21, 0
	s_add_i32 s22, s22, s25
	v_lshl_add_u64 v[140:141], s[20:21], 0, v[136:137]
	s_mov_b32 m0, s22
	s_nop 0
	global_load_lds_dwordx4 v[140:141], off
	v_lshl_add_u64 v[140:141], s[20:21], 0, v[132:133]
	s_add_i32 m0, s22, 0x2000
	s_nop 0
	global_load_lds_dwordx4 v[140:141], off
	s_waitcnt vmcnt(6)
	s_setprio 1
	s_barrier
	v_mfma_f32_16x16x32_bf16 v[68:71], v[200:203], v[166:169], v[68:71]
	v_mfma_f32_16x16x32_bf16 v[56:59], v[208:211], v[166:169], v[56:59]
	v_mfma_f32_16x16x32_bf16 v[48:51], v[200:203], v[174:177], v[48:51]
	v_mfma_f32_16x16x32_bf16 v[40:43], v[208:211], v[174:177], v[40:43]
	v_mfma_f32_16x16x32_bf16 v[32:35], v[200:203], v[182:185], v[32:35]
	v_mfma_f32_16x16x32_bf16 v[24:27], v[208:211], v[182:185], v[24:27]
	v_mfma_f32_16x16x32_bf16 v[16:19], v[200:203], v[190:193], v[16:19]
	v_mfma_f32_16x16x32_bf16 v[8:11], v[208:211], v[190:193], v[8:11]
	v_mfma_f32_16x16x32_bf16 v[68:71], v[204:207], v[170:173], v[68:71]
	v_mfma_f32_16x16x32_bf16 v[56:59], v[212:215], v[170:173], v[56:59]
	v_mfma_f32_16x16x32_bf16 v[48:51], v[204:207], v[178:181], v[48:51]
	v_mfma_f32_16x16x32_bf16 v[40:43], v[212:215], v[178:181], v[40:43]
	v_mfma_f32_16x16x32_bf16 v[32:35], v[204:207], v[186:189], v[32:35]
	v_mfma_f32_16x16x32_bf16 v[24:27], v[212:215], v[186:189], v[24:27]
	v_mfma_f32_16x16x32_bf16 v[16:19], v[204:207], v[194:197], v[16:19]
	v_mfma_f32_16x16x32_bf16 v[8:11], v[212:215], v[194:197], v[8:11]
	s_barrier
	s_setprio 0
	s_add_i32 s78, s78, 2
	s_add_u32 s79, s79, 0x100
	s_addc_u32 s80, s80, 0
	s_add_u32 s81, s81, 0x100
	s_addc_u32 s82, s82, 0
	s_add_u32 s18, s18, 0xffffff00
	s_addc_u32 s19, s19, -1
	v_lshl_add_u64 v[2:3], v[2:3], 0, s[50:51]
	s_cmp_gt_u32 s78, 13
	v_lshl_add_u64 v[144:145], v[144:145], 0, s[50:51]
	s_cbranch_scc0 .LBB0_528
	s_add_u32 s18, s76, 0x40080
	s_addc_u32 s19, s9, 0
	s_mov_b32 m0, s84
	v_lshl_add_u64 v[2:3], s[18:19], 0, v[138:139]
	global_load_lds_dwordx4 v[2:3], off
	v_lshl_add_u64 v[2:3], s[18:19], 0, v[134:135]
	s_mov_b32 m0, s83
	v_lshl_or_b32 v140, s75, 7, v148
	global_load_lds_dwordx4 v[2:3], off
	v_mul_f32_e32 v2, 0xbfb8aa3b, v124
	v_exp_f32_e32 v142, v2
	v_mul_f32_e32 v2, 0xbfb8aa3b, v125
	v_exp_f32_e32 v143, v2
	v_lshl_add_u32 v0, s10, 8, v146
	v_add_f32_e32 v142, 1.0, v142
	v_rcp_f32_e32 v144, v142
	v_add_f32_e32 v142, 1.0, v143
	v_rcp_f32_e32 v145, v142
	v_ashrrev_i32_e32 v141, 31, v140
	v_mul_f32_e32 v124, v124, v144
	v_mul_f32_e32 v124, v124, v128
	v_mul_f32_e32 v128, 0xbfb8aa3b, v126
	v_mul_f32_e32 v144, 0xbfb8aa3b, v127
	v_exp_f32_e32 v128, v128
	v_exp_f32_e32 v144, v144
	v_mul_f32_e32 v125, v125, v145
	v_mul_f32_e32 v125, v125, v129
	v_add_f32_e32 v128, 1.0, v128
	v_add_f32_e32 v129, 1.0, v144
	v_mul_f32_e32 v144, 0xbfb8aa3b, v116
	v_rcp_f32_e32 v128, v128
	v_exp_f32_e32 v144, v144
	v_rcp_f32_e32 v129, v129
	v_mov_b64_e32 v[2:3], s[68:69]
	v_mul_f32_e32 v126, v126, v128
	v_add_f32_e32 v128, 1.0, v144
	v_mul_f32_e32 v127, v127, v129
	v_rcp_f32_e32 v128, v128
	v_mul_f32_e32 v129, 0xbfb8aa3b, v117
	v_exp_f32_e32 v129, v129
	v_mad_i64_i32 v[142:143], s[18:19], v0, s3, v[2:3]
	v_mul_f32_e32 v116, v116, v128
	v_mul_f32_e32 v120, v116, v120
	v_add_f32_e32 v116, 1.0, v129
	v_mul_f32_e32 v128, 0xbfb8aa3b, v118
	v_rcp_f32_e32 v116, v116
	v_exp_f32_e32 v128, v128
	v_mul_f32_e32 v129, 0xbfb8aa3b, v119
	v_exp_f32_e32 v129, v129
	v_mul_f32_e32 v116, v117, v116
	v_add_f32_e32 v117, 1.0, v128
	v_rcp_f32_e32 v117, v117
	v_mul_f32_e32 v121, v116, v121
	v_add_f32_e32 v128, 1.0, v129
	v_rcp_f32_e32 v128, v128
	v_mul_f32_e32 v116, v118, v117
	v_cvt_pk_bf16_f32 v118, v124, v125
	v_mul_f32_e32 v124, 0xbfb8aa3b, v108
	v_exp_f32_e32 v124, v124
	v_mul_f32_e32 v125, 0xbfb8aa3b, v109
	v_exp_f32_e32 v125, v125
	v_mul_f32_e32 v129, v116, v122
	v_add_f32_e32 v124, 1.0, v124
	v_rcp_f32_e32 v124, v124
	v_mul_f32_e32 v116, v119, v128
	v_mul_f32_e32 v128, v116, v123
	v_lshlrev_b64 v[116:117], 1, v[140:141]
	v_lshl_add_u64 v[122:123], v[142:143], 0, v[116:117]
	v_add_f32_e32 v125, 1.0, v125
	v_mul_f32_e32 v108, v108, v124
	v_mul_f32_e32 v126, v126, v130
	v_mul_f32_e32 v127, v127, v131
	v_cvt_pk_bf16_f32 v119, v126, v127
	v_cvt_pk_bf16_f32 v120, v120, v121
	v_cvt_pk_bf16_f32 v121, v129, v128
	s_waitcnt vmcnt(0)
; DEVI unsigned cvtpk(float lo, float hi) { unsigned r; asm volatile("v_cvt_pk_bf16_f32 %0, %1, %2" : "=v"(r) : "v"(lo), "v"(hi)); return r; }
; DEVI float sigmoidf_(float x) { return __builtin_amdgcn_rcpf(1.f + __expf(-x)); }
;     DEVI void operator()(AccRef acc, const pg8::Unit& u, int wr, int wc, int fr, int fq) const {
;     ...
;             for (int m = 0; m < 4; ++m) { bf16_t* rowp = Hm + (size_t)(row0 + ai * 128 + m * 16) * DFF + col; float h[8];
; #pragma unroll
;                 for (int j = 0; j < 8; ++j) { const float gt = acc[ai][0][m][j >> 2][j & 3], up = acc[ai][1][m][j >> 2][j & 3]; h[j] = gt * sigmoidf_(gt) * up; }
;                 u32x4 w; w.x = cvtpk(h[0], h[1]); w.y = cvtpk(h[2], h[3]); w.z = cvtpk(h[4], h[5]); w.w = cvtpk(h[6], h[7]);
;                 if (ai == 0 && m == 0) asm volatile("s_waitcnt vmcnt(0)" ::: "memory");
;                 __builtin_nontemporal_store(w, (u32x4*)rowp); }
	v_rcp_f32_e32 v125, v125
	flat_store_dwordx4 v[122:123], v[118:121]
	v_mul_f32_e32 v108, v108, v112
	v_mul_f32_e32 v112, 0xbfb8aa3b, v110
	v_mul_f32_e32 v118, 0xbfb8aa3b, v111
	v_exp_f32_e32 v112, v112
	v_exp_f32_e32 v118, v118
	v_mul_f32_e32 v109, v109, v125
	v_mul_f32_e32 v109, v109, v113
	v_add_f32_e32 v112, 1.0, v112
	v_add_f32_e32 v113, 1.0, v118
	v_mul_f32_e32 v118, 0xbfb8aa3b, v100
	v_rcp_f32_e32 v112, v112
	v_exp_f32_e32 v118, v118
	v_rcp_f32_e32 v113, v113
	s_mov_b64 s[22:23], -1
	v_mul_f32_e32 v110, v110, v112
	v_add_f32_e32 v112, 1.0, v118
	v_mul_f32_e32 v111, v111, v113
	v_rcp_f32_e32 v112, v112
	v_mul_f32_e32 v113, 0xbfb8aa3b, v101
	v_exp_f32_e32 v113, v113
	v_mul_f32_e32 v110, v110, v114
	v_mul_f32_e32 v100, v100, v112
	v_mul_f32_e32 v104, v100, v104
	v_add_f32_e32 v100, 1.0, v113
	v_mul_f32_e32 v112, 0xbfb8aa3b, v102
	v_rcp_f32_e32 v100, v100
	v_exp_f32_e32 v112, v112
	v_mul_f32_e32 v113, 0xbfb8aa3b, v103
	v_exp_f32_e32 v113, v113
	v_mul_f32_e32 v100, v101, v100
	v_add_f32_e32 v101, 1.0, v112
	v_rcp_f32_e32 v101, v101
	v_add_f32_e32 v112, 1.0, v113
	v_rcp_f32_e32 v112, v112
	v_mul_f32_e32 v105, v100, v105
	v_mul_f32_e32 v100, v102, v101
	v_mul_f32_e32 v106, v100, v106
	v_mul_f32_e32 v100, v103, v112
	v_mul_f32_e32 v103, v100, v107
	v_mul_f32_e32 v111, v111, v115
	v_cvt_pk_bf16_f32 v100, v108, v109
	v_cvt_pk_bf16_f32 v101, v110, v111
	v_cvt_pk_bf16_f32 v102, v104, v105
	v_cvt_pk_bf16_f32 v103, v106, v103
	v_mul_f32_e32 v106, 0xbfb8aa3b, v92
	v_exp_f32_e32 v106, v106
	v_mul_f32_e32 v107, 0xbfb8aa3b, v93
	v_exp_f32_e32 v107, v107
	v_or_b32_e32 v104, 16, v0
	v_add_f32_e32 v106, 1.0, v106
	v_rcp_f32_e32 v106, v106
	v_mad_i64_i32 v[104:105], s[18:19], v104, s3, v[2:3]
	v_lshl_add_u64 v[104:105], v[104:105], 0, v[116:117]
	v_add_f32_e32 v107, 1.0, v107
	v_mul_f32_e32 v92, v92, v106
	v_rcp_f32_e32 v107, v107
	flat_store_dwordx4 v[104:105], v[100:103]
	v_mul_f32_e32 v92, v92, v96
	v_mul_f32_e32 v96, 0xbfb8aa3b, v94
	v_mul_f32_e32 v100, 0xbfb8aa3b, v95
	v_exp_f32_e32 v96, v96
	v_exp_f32_e32 v100, v100
	v_mul_f32_e32 v93, v93, v107
	v_mul_f32_e32 v93, v93, v97
	v_add_f32_e32 v96, 1.0, v96
	v_add_f32_e32 v97, 1.0, v100
	v_mul_f32_e32 v100, 0xbfb8aa3b, v84
	v_rcp_f32_e32 v96, v96
	v_exp_f32_e32 v100, v100
	v_rcp_f32_e32 v97, v97
	s_and_b64 vcc, exec, s[4:5]
	v_mul_f32_e32 v94, v94, v96
	v_add_f32_e32 v96, 1.0, v100
	v_mul_f32_e32 v95, v95, v97
	v_rcp_f32_e32 v96, v96
	v_mul_f32_e32 v97, 0xbfb8aa3b, v85
	v_exp_f32_e32 v97, v97
	v_mul_f32_e32 v94, v94, v98
	v_mul_f32_e32 v84, v84, v96
	v_mul_f32_e32 v88, v84, v88
	v_add_f32_e32 v84, 1.0, v97
	v_mul_f32_e32 v96, 0xbfb8aa3b, v86
	v_rcp_f32_e32 v84, v84
	v_exp_f32_e32 v96, v96
	v_mul_f32_e32 v97, 0xbfb8aa3b, v87
	v_exp_f32_e32 v97, v97
	v_mul_f32_e32 v84, v85, v84
	v_add_f32_e32 v85, 1.0, v96
	v_rcp_f32_e32 v85, v85
	v_add_f32_e32 v96, 1.0, v97
	v_rcp_f32_e32 v96, v96
	v_mul_f32_e32 v89, v84, v89
	v_mul_f32_e32 v84, v86, v85
	v_mul_f32_e32 v90, v84, v90
	v_mul_f32_e32 v84, v87, v96
	v_mul_f32_e32 v87, v84, v91
	v_mul_f32_e32 v95, v95, v99
	v_cvt_pk_bf16_f32 v84, v92, v93
	v_cvt_pk_bf16_f32 v85, v94, v95
	v_cvt_pk_bf16_f32 v86, v88, v89
	v_cvt_pk_bf16_f32 v87, v90, v87
	v_mul_f32_e32 v90, 0xbfb8aa3b, v76
	v_exp_f32_e32 v90, v90
	v_mul_f32_e32 v91, 0xbfb8aa3b, v77
	v_exp_f32_e32 v91, v91
	v_or_b32_e32 v88, 32, v0
	v_add_f32_e32 v90, 1.0, v90
	v_rcp_f32_e32 v90, v90
	v_mad_i64_i32 v[88:89], s[18:19], v88, s3, v[2:3]
	v_lshl_add_u64 v[88:89], v[88:89], 0, v[116:117]
	v_add_f32_e32 v91, 1.0, v91
	v_mul_f32_e32 v76, v76, v90
	v_rcp_f32_e32 v91, v91
	flat_store_dwordx4 v[88:89], v[84:87]
	v_mul_f32_e32 v76, v76, v80
	v_mul_f32_e32 v80, 0xbfb8aa3b, v78
	v_mul_f32_e32 v84, 0xbfb8aa3b, v79
	v_exp_f32_e32 v80, v80
	v_exp_f32_e32 v84, v84
	v_mul_f32_e32 v77, v77, v91
	v_mul_f32_e32 v77, v77, v81
	v_add_f32_e32 v80, 1.0, v80
	v_add_f32_e32 v81, 1.0, v84
	v_mul_f32_e32 v84, 0xbfb8aa3b, v64
	v_rcp_f32_e32 v80, v80
	v_exp_f32_e32 v84, v84
	v_rcp_f32_e32 v81, v81
	s_mov_b32 s75, s6
	v_mul_f32_e32 v78, v78, v80
	v_add_f32_e32 v80, 1.0, v84
	v_mul_f32_e32 v79, v79, v81
	v_rcp_f32_e32 v80, v80
	v_mul_f32_e32 v81, 0xbfb8aa3b, v65
	v_exp_f32_e32 v81, v81
	v_mul_f32_e32 v78, v78, v82
	v_mul_f32_e32 v64, v64, v80
	v_mul_f32_e32 v72, v64, v72
	v_add_f32_e32 v64, 1.0, v81
	v_mul_f32_e32 v80, 0xbfb8aa3b, v66
	v_rcp_f32_e32 v64, v64
	v_exp_f32_e32 v80, v80
	v_mul_f32_e32 v81, 0xbfb8aa3b, v67
	v_exp_f32_e32 v81, v81
	v_mul_f32_e32 v64, v65, v64
	v_add_f32_e32 v65, 1.0, v80
	v_rcp_f32_e32 v65, v65
	v_add_f32_e32 v80, 1.0, v81
	v_rcp_f32_e32 v80, v80
	v_mul_f32_e32 v73, v64, v73
	v_mul_f32_e32 v64, v66, v65
	v_mul_f32_e32 v74, v64, v74
	v_mul_f32_e32 v64, v67, v80
	v_mul_f32_e32 v79, v79, v83
	v_mul_f32_e32 v67, v64, v75
	v_cvt_pk_bf16_f32 v64, v76, v77
	v_cvt_pk_bf16_f32 v65, v78, v79
	v_cvt_pk_bf16_f32 v66, v72, v73
	v_or_b32_e32 v72, 48, v0
	v_mad_i64_i32 v[72:73], s[18:19], v72, s3, v[2:3]
	v_lshl_add_u64 v[72:73], v[72:73], 0, v[116:117]
	v_cvt_pk_bf16_f32 v67, v74, v67
	flat_store_dwordx4 v[72:73], v[64:67]
	v_mul_f32_e32 v74, 0xbfb8aa3b, v60
	v_mul_f32_e32 v75, 0xbfb8aa3b, v61
	v_mul_f32_e32 v64, 0xbfb8aa3b, v62
	v_exp_f32_e32 v64, v64
	v_mul_f32_e32 v65, 0xbfb8aa3b, v63
	v_exp_f32_e32 v65, v65
	v_mul_f32_e32 v66, 0xbfb8aa3b, v52
	v_add_f32_e32 v64, 1.0, v64
	v_rcp_f32_e32 v64, v64
	v_add_f32_e32 v65, 1.0, v65
	v_exp_f32_e32 v66, v66
	v_rcp_f32_e32 v65, v65
	v_mul_f32_e32 v62, v62, v64
	v_exp_f32_e32 v74, v74
	v_add_f32_e32 v64, 1.0, v66
	v_mul_f32_e32 v63, v63, v65
	v_rcp_f32_e32 v64, v64
	v_mul_f32_e32 v65, 0xbfb8aa3b, v53
	v_exp_f32_e32 v65, v65
	v_exp_f32_e32 v75, v75
	v_mul_f32_e32 v52, v52, v64
; DEVI unsigned cvtpk(float lo, float hi) { unsigned r; asm volatile("v_cvt_pk_bf16_f32 %0, %1, %2" : "=v"(r) : "v"(lo), "v"(hi)); return r; }
; DEVI float sigmoidf_(float x) { return __builtin_amdgcn_rcpf(1.f + __expf(-x)); }
; #define PG8_WAIT_V(n) asm volatile("s_waitcnt vmcnt(" #n ")" ::: "memory")
; #define PG8_BAR __builtin_amdgcn_s_barrier()
; template <class Epi, class Sched>
; __device__ __forceinline__ void gemm_phase(PG8_LAS unsigned char* lds, const Gemm g, const Sched& S, const Epi& E, int wv) {
;     ...
;         if (!has_next) break;
; #pragma unroll
;         for (int a = 0; a < 2; ++a)
; #pragma unroll
;             for (int b = 0; b < 2; ++b)
; #pragma unroll
;                 for (int m = 0; m < 4; ++m)
; #pragma unroll
;                     for (int n = 0; n < 2; ++n) acc[a][b][m][n] = (f32x4){0.f, 0.f, 0.f, 0.f};
;         cur = nxt; cA = nA; cB = nB; ++ui;
;     }
;     PG8_WAIT_V(0);
;     if (wr == 0) PG8_BAR;
;     PG8_BAR;
;     DEVI void operator()(AccRef acc, const pg8::Unit& u, int wr, int wc, int fr, int fq) const {
;     ...
;         for (int ai = 0; ai < 2; ++ai)
; #pragma unroll
;             for (int m = 0; m < 4; ++m) { bf16_t* rowp = Hm + (size_t)(row0 + ai * 128 + m * 16) * DFF + col; float h[8];
; #pragma unroll
;                 for (int j = 0; j < 8; ++j) { const float gt = acc[ai][0][m][j >> 2][j & 3], up = acc[ai][1][m][j >> 2][j & 3]; h[j] = gt * sigmoidf_(gt) * up; }
;                 u32x4 w; w.x = cvtpk(h[0], h[1]); w.y = cvtpk(h[2], h[3]); w.z = cvtpk(h[4], h[5]); w.w = cvtpk(h[6], h[7]);
;                 if (ai == 0 && m == 0) asm volatile("s_waitcnt vmcnt(0)" ::: "memory");
;                 __builtin_nontemporal_store(w, (u32x4*)rowp); }
	v_mul_f32_e32 v56, v52, v56
	v_add_f32_e32 v52, 1.0, v65
	v_mul_f32_e32 v64, 0xbfb8aa3b, v54
	v_rcp_f32_e32 v52, v52
	v_exp_f32_e32 v64, v64
	v_mul_f32_e32 v65, 0xbfb8aa3b, v55
	v_exp_f32_e32 v65, v65
	v_mul_f32_e32 v52, v53, v52
	v_add_f32_e32 v53, 1.0, v64
	v_rcp_f32_e32 v53, v53
	v_add_f32_e32 v64, 1.0, v65
	v_add_f32_e32 v74, 1.0, v74
	v_add_f32_e32 v75, 1.0, v75
	v_rcp_f32_e32 v64, v64
	v_rcp_f32_e32 v74, v74
	v_rcp_f32_e32 v75, v75
	v_mul_f32_e32 v57, v52, v57
	v_mul_f32_e32 v52, v54, v53
	v_mul_f32_e32 v58, v52, v58
	v_mul_f32_e32 v52, v55, v64
	v_mul_f32_e32 v60, v60, v74
	v_mul_f32_e32 v61, v61, v75
	v_mul_f32_e32 v55, v52, v59
	v_mul_f32_e32 v60, v60, v68
	v_mul_f32_e32 v61, v61, v69
	v_mul_f32_e32 v62, v62, v70
	v_mul_f32_e32 v63, v63, v71
	v_cvt_pk_bf16_f32 v52, v60, v61
	v_cvt_pk_bf16_f32 v53, v62, v63
	v_cvt_pk_bf16_f32 v54, v56, v57
	v_cvt_pk_bf16_f32 v55, v58, v55
	v_mul_f32_e32 v58, 0xbfb8aa3b, v44
	v_exp_f32_e32 v58, v58
	v_mul_f32_e32 v59, 0xbfb8aa3b, v45
	v_exp_f32_e32 v59, v59
	v_add_u32_e32 v56, 0x80, v0
	v_add_f32_e32 v58, 1.0, v58
	v_rcp_f32_e32 v58, v58
	v_mad_i64_i32 v[56:57], s[18:19], v56, s3, v[2:3]
	v_lshl_add_u64 v[56:57], v[56:57], 0, v[116:117]
	v_add_f32_e32 v59, 1.0, v59
	v_mul_f32_e32 v44, v44, v58
	v_rcp_f32_e32 v59, v59
	flat_store_dwordx4 v[56:57], v[52:55]
	v_mul_f32_e32 v44, v44, v48
	v_mul_f32_e32 v48, 0xbfb8aa3b, v46
	v_mul_f32_e32 v52, 0xbfb8aa3b, v47
	v_exp_f32_e32 v48, v48
	v_exp_f32_e32 v52, v52
	v_mul_f32_e32 v45, v45, v59
	v_mul_f32_e32 v45, v45, v49
	v_add_f32_e32 v48, 1.0, v48
	v_add_f32_e32 v49, 1.0, v52
	v_mul_f32_e32 v52, 0xbfb8aa3b, v36
	v_rcp_f32_e32 v48, v48
	v_exp_f32_e32 v52, v52
	v_rcp_f32_e32 v49, v49
	s_mov_b32 s10, s8
	v_mul_f32_e32 v46, v46, v48
	v_add_f32_e32 v48, 1.0, v52
	v_mul_f32_e32 v47, v47, v49
	v_rcp_f32_e32 v48, v48
	v_mul_f32_e32 v49, 0xbfb8aa3b, v37
	v_exp_f32_e32 v49, v49
	v_mul_f32_e32 v46, v46, v50
	v_mul_f32_e32 v36, v36, v48
	v_mul_f32_e32 v40, v36, v40
	v_add_f32_e32 v36, 1.0, v49
	v_mul_f32_e32 v48, 0xbfb8aa3b, v38
	v_rcp_f32_e32 v36, v36
	v_exp_f32_e32 v48, v48
	v_mul_f32_e32 v49, 0xbfb8aa3b, v39
	v_exp_f32_e32 v49, v49
	v_mul_f32_e32 v36, v37, v36
	v_add_f32_e32 v37, 1.0, v48
	v_rcp_f32_e32 v37, v37
	v_add_f32_e32 v48, 1.0, v49
	v_rcp_f32_e32 v48, v48
	v_mul_f32_e32 v41, v36, v41
	v_mul_f32_e32 v36, v38, v37
	v_mul_f32_e32 v42, v36, v42
	v_mul_f32_e32 v36, v39, v48
	v_mul_f32_e32 v39, v36, v43
	v_mul_f32_e32 v47, v47, v51
	v_cvt_pk_bf16_f32 v36, v44, v45
	v_cvt_pk_bf16_f32 v37, v46, v47
	v_cvt_pk_bf16_f32 v38, v40, v41
	v_cvt_pk_bf16_f32 v39, v42, v39
	v_mul_f32_e32 v42, 0xbfb8aa3b, v28
	v_exp_f32_e32 v42, v42
	v_mul_f32_e32 v43, 0xbfb8aa3b, v29
	v_exp_f32_e32 v43, v43
	v_add_u32_e32 v40, 0x90, v0
	v_add_f32_e32 v42, 1.0, v42
	v_rcp_f32_e32 v42, v42
	v_mad_i64_i32 v[40:41], s[18:19], v40, s3, v[2:3]
	v_lshl_add_u64 v[40:41], v[40:41], 0, v[116:117]
	v_add_f32_e32 v43, 1.0, v43
	v_mul_f32_e32 v28, v28, v42
	v_rcp_f32_e32 v43, v43
	flat_store_dwordx4 v[40:41], v[36:39]
	v_mul_f32_e32 v28, v28, v32
	v_mul_f32_e32 v32, 0xbfb8aa3b, v30
	v_mul_f32_e32 v36, 0xbfb8aa3b, v31
	v_exp_f32_e32 v32, v32
	v_exp_f32_e32 v36, v36
	v_mul_f32_e32 v29, v29, v43
	v_mul_f32_e32 v29, v29, v33
	v_add_f32_e32 v32, 1.0, v32
	v_add_f32_e32 v33, 1.0, v36
	v_mul_f32_e32 v36, 0xbfb8aa3b, v20
	v_rcp_f32_e32 v32, v32
	v_exp_f32_e32 v36, v36
	v_rcp_f32_e32 v33, v33
	s_mov_b64 s[20:21], s[12:13]
	v_mul_f32_e32 v30, v30, v32
	v_add_f32_e32 v32, 1.0, v36
	v_mul_f32_e32 v31, v31, v33
	v_rcp_f32_e32 v32, v32
	v_mul_f32_e32 v33, 0xbfb8aa3b, v21
	v_exp_f32_e32 v33, v33
	v_mul_f32_e32 v30, v30, v34
	v_mul_f32_e32 v20, v20, v32
	v_mul_f32_e32 v24, v20, v24
	v_add_f32_e32 v20, 1.0, v33
	v_mul_f32_e32 v32, 0xbfb8aa3b, v22
	v_rcp_f32_e32 v20, v20
	v_exp_f32_e32 v32, v32
	v_mul_f32_e32 v33, 0xbfb8aa3b, v23
	v_exp_f32_e32 v33, v33
	v_mul_f32_e32 v20, v21, v20
	v_add_f32_e32 v21, 1.0, v32
	v_rcp_f32_e32 v21, v21
	v_add_f32_e32 v32, 1.0, v33
	v_rcp_f32_e32 v32, v32
	v_mul_f32_e32 v25, v20, v25
	v_mul_f32_e32 v20, v22, v21
	v_mul_f32_e32 v26, v20, v26
	v_mul_f32_e32 v20, v23, v32
	v_mul_f32_e32 v23, v20, v27
	v_mul_f32_e32 v31, v31, v35
	v_cvt_pk_bf16_f32 v20, v28, v29
	v_cvt_pk_bf16_f32 v21, v30, v31
	v_cvt_pk_bf16_f32 v22, v24, v25
	v_cvt_pk_bf16_f32 v23, v26, v23
	v_mul_f32_e32 v26, 0xbfb8aa3b, v12
	v_exp_f32_e32 v26, v26
	v_mul_f32_e32 v27, 0xbfb8aa3b, v13
	v_exp_f32_e32 v27, v27
	v_add_u32_e32 v24, 0xa0, v0
	v_add_f32_e32 v26, 1.0, v26
	v_rcp_f32_e32 v26, v26
	v_mad_i64_i32 v[24:25], s[18:19], v24, s3, v[2:3]
	v_lshl_add_u64 v[24:25], v[24:25], 0, v[116:117]
	v_add_f32_e32 v27, 1.0, v27
	v_mul_f32_e32 v12, v12, v26
	v_rcp_f32_e32 v27, v27
	flat_store_dwordx4 v[24:25], v[20:23]
	v_mul_f32_e32 v12, v12, v16
	v_mul_f32_e32 v16, 0xbfb8aa3b, v14
	v_mul_f32_e32 v20, 0xbfb8aa3b, v15
	v_exp_f32_e32 v16, v16
	v_exp_f32_e32 v20, v20
	v_mul_f32_e32 v13, v13, v27
	v_mul_f32_e32 v13, v13, v17
	v_add_f32_e32 v16, 1.0, v16
	v_add_f32_e32 v17, 1.0, v20
	v_mul_f32_e32 v20, 0xbfb8aa3b, v4
	v_rcp_f32_e32 v16, v16
	v_exp_f32_e32 v20, v20
	v_rcp_f32_e32 v17, v17
	v_add_u32_e32 v0, 0xb0, v0
	v_mul_f32_e32 v14, v14, v16
	v_add_f32_e32 v16, 1.0, v20
	v_mul_f32_e32 v15, v15, v17
	v_rcp_f32_e32 v16, v16
	v_mul_f32_e32 v17, 0xbfb8aa3b, v5
	v_exp_f32_e32 v17, v17
	v_mad_i64_i32 v[2:3], s[18:19], v0, s3, v[2:3]
	v_mul_f32_e32 v4, v4, v16
	v_mul_f32_e32 v8, v4, v8
	v_add_f32_e32 v4, 1.0, v17
	v_mul_f32_e32 v16, 0xbfb8aa3b, v6
	v_rcp_f32_e32 v4, v4
	v_exp_f32_e32 v16, v16
	v_mul_f32_e32 v17, 0xbfb8aa3b, v7
	v_exp_f32_e32 v17, v17
	v_mul_f32_e32 v4, v5, v4
	v_add_f32_e32 v5, 1.0, v16
	v_rcp_f32_e32 v5, v5
	v_add_f32_e32 v16, 1.0, v17
	v_rcp_f32_e32 v16, v16
	v_mul_f32_e32 v9, v4, v9
	v_mul_f32_e32 v4, v6, v5
	v_mul_f32_e32 v10, v4, v10
	v_mul_f32_e32 v4, v7, v16
	v_mul_f32_e32 v7, v4, v11
	v_lshl_add_u64 v[2:3], v[2:3], 0, v[116:117]
	s_mov_b64 s[18:19], s[14:15]
	v_mul_f32_e32 v14, v14, v18
	v_mul_f32_e32 v15, v15, v19
	v_cvt_pk_bf16_f32 v4, v12, v13
	v_cvt_pk_bf16_f32 v5, v14, v15
	v_cvt_pk_bf16_f32 v6, v8, v9
	v_cvt_pk_bf16_f32 v7, v10, v7
	flat_store_dwordx4 v[2:3], v[4:7]
	s_cbranch_vccz .LBB0_522
	s_waitcnt vmcnt(0)
	s_cmpk_gt_u32 s24, 0xff
	s_cbranch_scc1 .LBB0_532
	s_barrier
